# Hyena gate stage rewritten with batched loads (8 consecutive positions per thread); RWKV-7 output flush moved from the recurrence waves to a hand-written staging branch
# speedup vs baseline: 1.0140x; 1.0140x over previous
.LBB0_427:
	v_and_b32_e32 v139, 0x7ff, v138
	v_and_or_b32 v140, v86, s63, v139
	v_cvt_f32_u32_e32 v139, v139
	v_lshl_add_u32 v203, v140, 3, 0
	ds_read2st64_b64 v[150:153], v203 offset1:32
	ds_read2st64_b64 v[154:157], v203 offset0:64 offset1:96
	v_cmp_lt_u32_e32 vcc, s61, v138
	v_mul_f32_e32 v139, 0x39000000, v139
	v_cos_f32_e32 v140, v139
	v_sin_f32_e32 v141, v139
	s_or_b64 s[0:1], vcc, s[0:1]
	v_add_f32_e32 v139, v140, v140
	v_pk_mul_f32 v[204:205], v[140:141], v[140:141]
	v_mul_f32_e32 v206, v141, v139
	s_waitcnt lgkmcnt(1)
	v_pk_mul_f32 v[208:209], v[152:153], v[206:207] op_sel_hi:[1,0]
	v_pk_add_f32 v[204:205], v[204:205], v[204:205] op_sel:[0,1] op_sel_hi:[0,1] neg_lo:[0,1] neg_hi:[0,1]
	s_waitcnt lgkmcnt(0)
	v_pk_mul_f32 v[206:207], v[206:207], v[156:157] op_sel_hi:[0,1]
	v_pk_fma_f32 v[226:227], v[152:153], v[204:205], v[208:209] op_sel:[0,0,1] op_sel_hi:[1,1,0] neg_lo:[0,0,1] neg_hi:[0,0,1]
	v_pk_fma_f32 v[152:153], v[152:153], v[204:205], v[208:209] op_sel:[0,0,1] op_sel_hi:[1,1,0]
	v_pk_fma_f32 v[208:209], v[204:205], v[156:157], v[206:207] op_sel:[0,0,1] op_sel_hi:[1,1,0] neg_lo:[0,0,1] neg_hi:[0,0,1]
	v_pk_fma_f32 v[156:157], v[204:205], v[156:157], v[206:207] op_sel:[0,0,1] op_sel_hi:[1,1,0]
	v_mov_b32_e32 v204, v141
	v_mov_b32_e32 v209, v157
	v_pk_add_f32 v[156:157], v[154:155], v[208:209]
	v_pk_add_f32 v[154:155], v[154:155], v[208:209] neg_lo:[0,1] neg_hi:[0,1]
	v_pk_mul_f32 v[206:207], v[204:205], v[156:157] op_sel_hi:[0,1]
	v_mov_b32_e32 v227, v153
	v_pk_fma_f32 v[228:229], v[140:141], v[156:157], v[206:207] op_sel:[0,0,1] op_sel_hi:[1,1,0] neg_lo:[0,0,1] neg_hi:[0,0,1]
	v_pk_fma_f32 v[156:157], v[140:141], v[156:157], v[206:207] op_sel:[0,0,1] op_sel_hi:[0,1,0]
	v_pk_mul_f32 v[140:141], v[140:141], v[154:155] op_sel_hi:[0,1]
	v_pk_add_f32 v[152:153], v[150:151], v[226:227]
	v_mov_b32_e32 v229, v157
	v_pk_add_f32 v[150:151], v[150:151], v[226:227] neg_lo:[0,1] neg_hi:[0,1]
	v_pk_fma_f32 v[156:157], v[204:205], v[154:155], v[140:141] op_sel:[0,0,1] op_sel_hi:[0,1,0]
	v_pk_fma_f32 v[140:141], v[204:205], v[154:155], v[140:141] op_sel:[0,0,1] op_sel_hi:[0,1,0] neg_lo:[1,0,0] neg_hi:[1,0,0]
	v_pk_add_f32 v[140:141], v[150:151], v[140:141]
	v_add_u32_e32 v139, 0x200, v138
	v_and_b32_e32 v139, 0x7ff, v139
	v_add_u32_e32 v140, 0x800, v86
	v_and_or_b32 v140, v140, s63, v139
	v_cvt_f32_u32_e32 v139, v139
	v_pk_add_f32 v[154:155], v[150:151], v[156:157] neg_lo:[0,1] neg_hi:[0,1]
	v_pk_add_f32 v[152:153], v[152:153], v[228:229]
	v_mov_b32_e32 v155, v141
	v_mul_f32_e32 v139, 0x39000000, v139
	ds_write2st64_b64 v203, v[152:153], v[154:155] offset1:32
	v_lshl_add_u32 v203, v140, 3, 0
	v_cos_f32_e32 v140, v139
	v_sin_f32_e32 v141, v139
	ds_read2st64_b64 v[150:153], v203 offset1:32
	ds_read2st64_b64 v[154:157], v203 offset0:64 offset1:96
	v_add_u32_e32 v86, 0x1000, v86
	v_add_f32_e32 v139, v140, v140
	v_pk_mul_f32 v[204:205], v[140:141], v[140:141]
	v_mul_f32_e32 v206, v141, v139
	s_waitcnt lgkmcnt(1)
	v_pk_mul_f32 v[208:209], v[152:153], v[206:207] op_sel_hi:[1,0]
	v_pk_add_f32 v[204:205], v[204:205], v[204:205] op_sel:[0,1] op_sel_hi:[0,1] neg_lo:[0,1] neg_hi:[0,1]
	s_waitcnt lgkmcnt(0)
	v_pk_mul_f32 v[206:207], v[206:207], v[156:157] op_sel_hi:[0,1]
	v_pk_fma_f32 v[226:227], v[152:153], v[204:205], v[208:209] op_sel:[0,0,1] op_sel_hi:[1,1,0] neg_lo:[0,0,1] neg_hi:[0,0,1]
	v_pk_fma_f32 v[152:153], v[152:153], v[204:205], v[208:209] op_sel:[0,0,1] op_sel_hi:[1,1,0]
	v_pk_fma_f32 v[208:209], v[204:205], v[156:157], v[206:207] op_sel:[0,0,1] op_sel_hi:[1,1,0] neg_lo:[0,0,1] neg_hi:[0,0,1]
	v_pk_fma_f32 v[156:157], v[204:205], v[156:157], v[206:207] op_sel:[0,0,1] op_sel_hi:[1,1,0]
	v_mov_b32_e32 v204, v141
	v_mov_b32_e32 v209, v157
	v_pk_add_f32 v[156:157], v[154:155], v[208:209]
	v_pk_add_f32 v[154:155], v[154:155], v[208:209] neg_lo:[0,1] neg_hi:[0,1]
	v_pk_mul_f32 v[206:207], v[204:205], v[156:157] op_sel_hi:[0,1]
	v_mov_b32_e32 v227, v153
	v_pk_fma_f32 v[228:229], v[140:141], v[156:157], v[206:207] op_sel:[0,0,1] op_sel_hi:[1,1,0] neg_lo:[0,0,1] neg_hi:[0,0,1]
	v_pk_fma_f32 v[156:157], v[140:141], v[156:157], v[206:207] op_sel:[0,0,1] op_sel_hi:[0,1,0]
	v_pk_mul_f32 v[140:141], v[140:141], v[154:155] op_sel_hi:[0,1]
	v_pk_add_f32 v[152:153], v[150:151], v[226:227]
	v_mov_b32_e32 v229, v157
	v_pk_add_f32 v[150:151], v[150:151], v[226:227] neg_lo:[0,1] neg_hi:[0,1]
	v_pk_fma_f32 v[156:157], v[204:205], v[154:155], v[140:141] op_sel:[0,0,1] op_sel_hi:[0,1,0]
	v_pk_fma_f32 v[140:141], v[204:205], v[154:155], v[140:141] op_sel:[0,0,1] op_sel_hi:[0,1,0] neg_lo:[1,0,0] neg_hi:[1,0,0]
	v_pk_add_f32 v[154:155], v[150:151], v[156:157] neg_lo:[0,1] neg_hi:[0,1]
	v_pk_add_f32 v[140:141], v[150:151], v[140:141]
	v_add_u32_e32 v139, 0x400, v138
	v_pk_add_f32 v[152:153], v[152:153], v[228:229]
	v_mov_b32_e32 v155, v141
	v_mov_b32_e32 v138, v139
	ds_write2st64_b64 v203, v[152:153], v[154:155] offset1:32
	s_andn2_b64 exec, exec, s[0:1]
	s_cbranch_execnz .LBB0_427
	s_or_b64 exec, exec, s[0:1]
	v_mov_b64_e32 v[138:139], v[164:165]
	v_mov_b32_e32 v152, v164
	v_mov_b32_e32 v150, v221
	v_mov_b32_e32 v139, v224
	s_waitcnt lgkmcnt(0)
	s_barrier
	s_lshl_b32 s52, s50, 14
	s_add_u32 s52, s47, s52
	s_addc_u32 s53, s64, 0
	s_add_u32 s54, s52, 0x2000
	s_addc_u32 s55, s53, 0
	v_lshlrev_b32_e32 v219, 4, v164
	global_load_dwordx4 v[246:249], v219, s[52:53]
	global_load_dwordx4 v[138:141], v219, s[54:55]
	global_load_ushort v250, v219, s[52:53] offset:-2
	global_load_ushort v251, v219, s[52:53] offset:16
	global_load_ushort v252, v219, s[54:55] offset:-2
	global_load_ushort v253, v219, s[54:55] offset:16
	v_lshlrev_b32_e32 v228, 6, v164
	ds_read_b128 v[230:233], v228 offset:0
	ds_read_b128 v[234:237], v228 offset:16
	ds_read_b128 v[238:241], v228 offset:32
	ds_read_b128 v[242:245], v228 offset:48
	s_lshl_b32 s55, s50, 15
	v_lshl_add_u32 v226, v164, 5, s55
	v_add_u32_e32 v226, 0x10000, v226
	ds_read_b128 v[150:153], v226
	ds_read_b128 v[154:157], v226 offset:16
	v_cmp_ne_u32_e64 s[90:91], 0, v164
	v_cmp_ne_u32_e32 vcc, 0x1ff, v164
	s_waitcnt vmcnt(2)
	v_lshlrev_b32_e32 v203, 16, v246
	v_and_b32_e32 v204, 0xffff0000, v246
	v_lshlrev_b32_e32 v205, 16, v247
	v_and_b32_e32 v206, 0xffff0000, v247
	v_lshlrev_b32_e32 v207, 16, v248
	v_and_b32_e32 v208, 0xffff0000, v248
	v_lshlrev_b32_e32 v209, 16, v249
	v_and_b32_e32 v218, 0xffff0000, v249
	v_lshlrev_b32_e32 v250, 16, v250
	v_lshlrev_b32_e32 v251, 16, v251
	v_cndmask_b32_e64 v250, 0, v250, s[90:91]
	v_cndmask_b32_e32 v251, 0, v251, vcc
	s_waitcnt lgkmcnt(0)
	v_mul_f32_e32 v227, v146, v250
	v_mul_f32_e32 v229, v145, v150
	v_fmac_f32_e32 v227, v147, v203
	v_fmac_f32_e32 v229, 0x39000000, v230
	v_fmac_f32_e32 v227, v148, v204
	v_add_f32_e32 v227, v149, v227
	v_mul_f32_e32 v150, v227, v229
	v_mul_f32_e32 v227, v146, v203
	v_mul_f32_e32 v229, v145, v151
	v_fmac_f32_e32 v227, v147, v204
	v_fmac_f32_e32 v229, 0x39000000, v232
	v_fmac_f32_e32 v227, v148, v205
	v_add_f32_e32 v227, v149, v227
	v_mul_f32_e32 v151, v227, v229
	v_mul_f32_e32 v227, v146, v204
	v_mul_f32_e32 v229, v145, v152
	v_fmac_f32_e32 v227, v147, v205
	v_fmac_f32_e32 v229, 0x39000000, v234
	v_fmac_f32_e32 v227, v148, v206
	v_add_f32_e32 v227, v149, v227
	v_mul_f32_e32 v152, v227, v229
	v_mul_f32_e32 v227, v146, v205
	v_mul_f32_e32 v229, v145, v153
	v_fmac_f32_e32 v227, v147, v206
	v_fmac_f32_e32 v229, 0x39000000, v236
	v_fmac_f32_e32 v227, v148, v207
	v_add_f32_e32 v227, v149, v227
	v_mul_f32_e32 v153, v227, v229
	v_mul_f32_e32 v227, v146, v206
	v_mul_f32_e32 v229, v145, v154
	v_fmac_f32_e32 v227, v147, v207
	v_fmac_f32_e32 v229, 0x39000000, v238
	v_fmac_f32_e32 v227, v148, v208
	v_add_f32_e32 v227, v149, v227
	v_mul_f32_e32 v154, v227, v229
	v_mul_f32_e32 v227, v146, v207
	v_mul_f32_e32 v229, v145, v155
	v_fmac_f32_e32 v227, v147, v208
	v_fmac_f32_e32 v229, 0x39000000, v240
	v_fmac_f32_e32 v227, v148, v209
	v_add_f32_e32 v227, v149, v227
	v_mul_f32_e32 v155, v227, v229
	v_mul_f32_e32 v227, v146, v208
	v_mul_f32_e32 v229, v145, v156
	v_fmac_f32_e32 v227, v147, v209
	v_fmac_f32_e32 v229, 0x39000000, v242
	v_fmac_f32_e32 v227, v148, v218
	v_add_f32_e32 v227, v149, v227
	v_mul_f32_e32 v156, v227, v229
	v_mul_f32_e32 v227, v146, v209
	v_mul_f32_e32 v229, v145, v157
	v_fmac_f32_e32 v227, v147, v218
	v_fmac_f32_e32 v229, 0x39000000, v244
	v_fmac_f32_e32 v227, v148, v251
	v_add_f32_e32 v227, v149, v227
	v_mul_f32_e32 v157, v227, v229
	ds_write_b128 v226, v[150:153] offset:0
	ds_write_b128 v226, v[154:157] offset:16
	ds_read_b128 v[150:153], v226 offset:16384
	ds_read_b128 v[154:157], v226 offset:16400
	s_waitcnt vmcnt(0)
	v_lshlrev_b32_e32 v203, 16, v138
	v_and_b32_e32 v204, 0xffff0000, v138
	v_lshlrev_b32_e32 v205, 16, v139
	v_and_b32_e32 v206, 0xffff0000, v139
	v_lshlrev_b32_e32 v207, 16, v140
	v_and_b32_e32 v208, 0xffff0000, v140
	v_lshlrev_b32_e32 v209, 16, v141
	v_and_b32_e32 v218, 0xffff0000, v141
	v_lshlrev_b32_e32 v252, 16, v252
	v_lshlrev_b32_e32 v253, 16, v253
	v_cndmask_b32_e64 v252, 0, v252, s[90:91]
	v_cndmask_b32_e32 v253, 0, v253, vcc
	s_waitcnt lgkmcnt(0)
	v_mul_f32_e32 v227, v146, v252
	v_mul_f32_e32 v229, v145, v150
	v_fmac_f32_e32 v227, v147, v203
	v_fmac_f32_e32 v229, 0x39000000, v231
	v_fmac_f32_e32 v227, v148, v204
	v_add_f32_e32 v227, v149, v227
	v_mul_f32_e32 v150, v227, v229
	v_mul_f32_e32 v227, v146, v203
	v_mul_f32_e32 v229, v145, v151
	v_fmac_f32_e32 v227, v147, v204
	v_fmac_f32_e32 v229, 0x39000000, v233
	v_fmac_f32_e32 v227, v148, v205
	v_add_f32_e32 v227, v149, v227
	v_mul_f32_e32 v151, v227, v229
	v_mul_f32_e32 v227, v146, v204
	v_mul_f32_e32 v229, v145, v152
	v_fmac_f32_e32 v227, v147, v205
	v_fmac_f32_e32 v229, 0x39000000, v235
	v_fmac_f32_e32 v227, v148, v206
	v_add_f32_e32 v227, v149, v227
	v_mul_f32_e32 v152, v227, v229
	v_mul_f32_e32 v227, v146, v205
	v_mul_f32_e32 v229, v145, v153
	v_fmac_f32_e32 v227, v147, v206
	v_fmac_f32_e32 v229, 0x39000000, v237
	v_fmac_f32_e32 v227, v148, v207
	v_add_f32_e32 v227, v149, v227
	v_mul_f32_e32 v153, v227, v229
	v_mul_f32_e32 v227, v146, v206
	v_mul_f32_e32 v229, v145, v154
	v_fmac_f32_e32 v227, v147, v207
	v_fmac_f32_e32 v229, 0x39000000, v239
	v_fmac_f32_e32 v227, v148, v208
	v_add_f32_e32 v227, v149, v227
	v_mul_f32_e32 v154, v227, v229
	v_mul_f32_e32 v227, v146, v207
	v_mul_f32_e32 v229, v145, v155
	v_fmac_f32_e32 v227, v147, v208
	v_fmac_f32_e32 v229, 0x39000000, v241
	v_fmac_f32_e32 v227, v148, v209
	v_add_f32_e32 v227, v149, v227
	v_mul_f32_e32 v155, v227, v229
	v_mul_f32_e32 v227, v146, v208
	v_mul_f32_e32 v229, v145, v156
	v_fmac_f32_e32 v227, v147, v209
	v_fmac_f32_e32 v229, 0x39000000, v243
	v_fmac_f32_e32 v227, v148, v218
	v_add_f32_e32 v227, v149, v227
	v_mul_f32_e32 v156, v227, v229
	v_mul_f32_e32 v227, v146, v209
	v_mul_f32_e32 v229, v145, v157
	v_fmac_f32_e32 v227, v147, v218
	v_fmac_f32_e32 v229, 0x39000000, v245
	v_fmac_f32_e32 v227, v148, v253
	v_add_f32_e32 v227, v149, v227
	v_mul_f32_e32 v157, v227, v229
	ds_write_b128 v226, v[150:153] offset:16384
	ds_write_b128 v226, v[154:157] offset:16400
	s_waitcnt lgkmcnt(0)
	s_mov_b64 s[90:91], 0
	s_branch .LBB0_360

.Lrc_loop:
	ds_read_b128 v[8:11], v100 offset:0
	ds_read_b128 v[12:15], v100 offset:256
	ds_read_b128 v[16:19], v100 offset:512
	ds_read_b128 v[20:23], v100 offset:768
	ds_read_b128 v[24:27], v100 offset:1024
	ds_read_b64 v[28:29], v101 offset:1280
	ds_read_b128 v[32:35], v100 offset:1536
	ds_read_b128 v[36:39], v100 offset:1792
	ds_read_b128 v[40:43], v100 offset:2048
	ds_read_b128 v[44:47], v100 offset:2304
	ds_read_b128 v[48:51], v100 offset:2560
	ds_read_b64 v[52:53], v101 offset:2816
	ds_read_b128 v[56:59], v100 offset:3072
	ds_read_b128 v[60:63], v100 offset:3328
	ds_read_b128 v[64:67], v100 offset:3584
	ds_read_b128 v[68:71], v100 offset:3840
	ds_read_b128 v[72:75], v100 offset:4096
	ds_read_b64 v[76:77], v101 offset:4352
	s_waitcnt lgkmcnt(12)
	v_pk_mul_f32 v[80:81], v[20:21], v[0:1] op_sel:[0,0] op_sel_hi:[0,1]
	v_pk_mul_f32 v[82:83], v[20:21], v[2:3] op_sel:[1,0] op_sel_hi:[1,1]
	v_pk_fma_f32 v[80:81], v[22:23], v[4:5], v[80:81] op_sel:[0,0,0] op_sel_hi:[0,1,1]
	v_pk_fma_f32 v[82:83], v[22:23], v[6:7], v[82:83] op_sel:[1,0,0] op_sel_hi:[1,1,1]
	s_nop 0
	v_pk_add_f32 v[80:81], v[80:81], v[82:83]
	v_pk_mul_f32 v[0:1], v[12:13], v[0:1] op_sel:[0,0] op_sel_hi:[0,1]
	v_pk_mul_f32 v[2:3], v[12:13], v[2:3] op_sel:[1,0] op_sel_hi:[1,1]
	v_add_f32_dpp v80, v80, v80 quad_perm:[1,0,3,2] row_mask:0xf bank_mask:0xf
	v_add_f32_dpp v81, v81, v81 quad_perm:[1,0,3,2] row_mask:0xf bank_mask:0xf
	v_pk_mul_f32 v[4:5], v[14:15], v[4:5] op_sel:[0,0] op_sel_hi:[0,1]
	v_add_f32_dpp v80, v80, v80 quad_perm:[2,3,0,1] row_mask:0xf bank_mask:0xf
	v_add_f32_dpp v81, v81, v81 quad_perm:[2,3,0,1] row_mask:0xf bank_mask:0xf
	v_pk_mul_f32 v[6:7], v[14:15], v[6:7] op_sel:[1,0] op_sel_hi:[1,1]
	v_add_f32_dpp v80, v80, v80 row_half_mirror row_mask:0xf bank_mask:0xf
	v_add_f32_dpp v81, v81, v81 row_half_mirror row_mask:0xf bank_mask:0xf
	s_nop 0
	v_add_f32_dpp v80, v80, v80 row_mirror row_mask:0xf bank_mask:0xf
	v_add_f32_dpp v81, v81, v81 row_mirror row_mask:0xf bank_mask:0xf
	v_pk_fma_f32 v[0:1], v[80:81], v[24:25], v[0:1] op_sel:[0,0,0] op_sel_hi:[1,0,1] neg_lo:[1,0,0] neg_hi:[1,0,0]
	v_pk_fma_f32 v[2:3], v[80:81], v[24:25], v[2:3] op_sel:[0,1,0] op_sel_hi:[1,1,1] neg_lo:[1,0,0] neg_hi:[1,0,0]
	v_pk_fma_f32 v[4:5], v[80:81], v[26:27], v[4:5] op_sel:[0,0,0] op_sel_hi:[1,0,1] neg_lo:[1,0,0] neg_hi:[1,0,0]
	v_pk_fma_f32 v[6:7], v[80:81], v[26:27], v[6:7] op_sel:[0,1,0] op_sel_hi:[1,1,1] neg_lo:[1,0,0] neg_hi:[1,0,0]
	v_pk_fma_f32 v[0:1], v[28:29], v[16:17], v[0:1] op_sel:[0,0,0] op_sel_hi:[1,0,1]
	v_pk_fma_f32 v[2:3], v[28:29], v[16:17], v[2:3] op_sel:[0,1,0] op_sel_hi:[1,1,1]
	v_pk_fma_f32 v[4:5], v[28:29], v[18:19], v[4:5] op_sel:[0,0,0] op_sel_hi:[1,0,1]
	v_pk_fma_f32 v[6:7], v[28:29], v[18:19], v[6:7] op_sel:[0,1,0] op_sel_hi:[1,1,1]
	v_pk_mul_f32 v[84:85], v[8:9], v[0:1] op_sel:[0,0] op_sel_hi:[0,1]
	v_pk_mul_f32 v[86:87], v[8:9], v[2:3] op_sel:[1,0] op_sel_hi:[1,1]
	v_pk_fma_f32 v[84:85], v[10:11], v[4:5], v[84:85] op_sel:[0,0,0] op_sel_hi:[0,1,1]
	v_pk_fma_f32 v[86:87], v[10:11], v[6:7], v[86:87] op_sel:[1,0,0] op_sel_hi:[1,1,1]
	ds_read_b128 v[8:11], v100 offset:4608
	ds_read_b128 v[12:15], v100 offset:4864
	ds_read_b128 v[16:19], v100 offset:5120
	ds_read_b128 v[20:23], v100 offset:5376
	ds_read_b128 v[24:27], v100 offset:5632
	ds_read_b64 v[28:29], v101 offset:5888
	s_waitcnt lgkmcnt(12)
	v_pk_mul_f32 v[80:81], v[44:45], v[0:1] op_sel:[0,0] op_sel_hi:[0,1]
	v_pk_mul_f32 v[82:83], v[44:45], v[2:3] op_sel:[1,0] op_sel_hi:[1,1]
	v_pk_fma_f32 v[80:81], v[46:47], v[4:5], v[80:81] op_sel:[0,0,0] op_sel_hi:[0,1,1]
	v_pk_fma_f32 v[82:83], v[46:47], v[6:7], v[82:83] op_sel:[1,0,0] op_sel_hi:[1,1,1]
	v_pk_add_f32 v[84:85], v[84:85], v[86:87]
	v_pk_add_f32 v[80:81], v[80:81], v[82:83]
	v_pk_mul_f32 v[0:1], v[36:37], v[0:1] op_sel:[0,0] op_sel_hi:[0,1]
	v_pk_mul_f32 v[2:3], v[36:37], v[2:3] op_sel:[1,0] op_sel_hi:[1,1]
	v_add_f32_dpp v80, v80, v80 quad_perm:[1,0,3,2] row_mask:0xf bank_mask:0xf
	v_add_f32_dpp v81, v81, v81 quad_perm:[1,0,3,2] row_mask:0xf bank_mask:0xf
	v_pk_mul_f32 v[4:5], v[38:39], v[4:5] op_sel:[0,0] op_sel_hi:[0,1]
	v_add_f32_dpp v80, v80, v80 quad_perm:[2,3,0,1] row_mask:0xf bank_mask:0xf
	v_add_f32_dpp v81, v81, v81 quad_perm:[2,3,0,1] row_mask:0xf bank_mask:0xf
	v_pk_mul_f32 v[6:7], v[38:39], v[6:7] op_sel:[1,0] op_sel_hi:[1,1]
	v_add_f32_dpp v80, v80, v80 row_half_mirror row_mask:0xf bank_mask:0xf
	v_add_f32_dpp v81, v81, v81 row_half_mirror row_mask:0xf bank_mask:0xf
	ds_write_b64 v102, v[84:85] offset:0
	v_add_f32_dpp v80, v80, v80 row_mirror row_mask:0xf bank_mask:0xf
	v_add_f32_dpp v81, v81, v81 row_mirror row_mask:0xf bank_mask:0xf
	v_pk_fma_f32 v[0:1], v[80:81], v[48:49], v[0:1] op_sel:[0,0,0] op_sel_hi:[1,0,1] neg_lo:[1,0,0] neg_hi:[1,0,0]
	v_pk_fma_f32 v[2:3], v[80:81], v[48:49], v[2:3] op_sel:[0,1,0] op_sel_hi:[1,1,1] neg_lo:[1,0,0] neg_hi:[1,0,0]
	v_pk_fma_f32 v[4:5], v[80:81], v[50:51], v[4:5] op_sel:[0,0,0] op_sel_hi:[1,0,1] neg_lo:[1,0,0] neg_hi:[1,0,0]
	v_pk_fma_f32 v[6:7], v[80:81], v[50:51], v[6:7] op_sel:[0,1,0] op_sel_hi:[1,1,1] neg_lo:[1,0,0] neg_hi:[1,0,0]
	v_pk_fma_f32 v[0:1], v[52:53], v[40:41], v[0:1] op_sel:[0,0,0] op_sel_hi:[1,0,1]
	v_pk_fma_f32 v[2:3], v[52:53], v[40:41], v[2:3] op_sel:[0,1,0] op_sel_hi:[1,1,1]
	v_pk_fma_f32 v[4:5], v[52:53], v[42:43], v[4:5] op_sel:[0,0,0] op_sel_hi:[1,0,1]
	v_pk_fma_f32 v[6:7], v[52:53], v[42:43], v[6:7] op_sel:[0,1,0] op_sel_hi:[1,1,1]
	v_pk_mul_f32 v[88:89], v[32:33], v[0:1] op_sel:[0,0] op_sel_hi:[0,1]
	v_pk_mul_f32 v[90:91], v[32:33], v[2:3] op_sel:[1,0] op_sel_hi:[1,1]
	v_pk_fma_f32 v[88:89], v[34:35], v[4:5], v[88:89] op_sel:[0,0,0] op_sel_hi:[0,1,1]
	v_pk_fma_f32 v[90:91], v[34:35], v[6:7], v[90:91] op_sel:[1,0,0] op_sel_hi:[1,1,1]
	ds_read_b128 v[32:35], v100 offset:6144
	ds_read_b128 v[36:39], v100 offset:6400
	ds_read_b128 v[40:43], v100 offset:6656
	ds_read_b128 v[44:47], v100 offset:6912
	ds_read_b128 v[48:51], v100 offset:7168
	ds_read_b64 v[52:53], v101 offset:7424
	s_waitcnt lgkmcnt(13)
	v_pk_mul_f32 v[80:81], v[68:69], v[0:1] op_sel:[0,0] op_sel_hi:[0,1]
	v_pk_mul_f32 v[82:83], v[68:69], v[2:3] op_sel:[1,0] op_sel_hi:[1,1]
	v_pk_fma_f32 v[80:81], v[70:71], v[4:5], v[80:81] op_sel:[0,0,0] op_sel_hi:[0,1,1]
	v_pk_fma_f32 v[82:83], v[70:71], v[6:7], v[82:83] op_sel:[1,0,0] op_sel_hi:[1,1,1]
	v_pk_add_f32 v[88:89], v[88:89], v[90:91]
	v_pk_add_f32 v[80:81], v[80:81], v[82:83]
	v_pk_mul_f32 v[0:1], v[60:61], v[0:1] op_sel:[0,0] op_sel_hi:[0,1]
	v_pk_mul_f32 v[2:3], v[60:61], v[2:3] op_sel:[1,0] op_sel_hi:[1,1]
	v_add_f32_dpp v80, v80, v80 quad_perm:[1,0,3,2] row_mask:0xf bank_mask:0xf
	v_add_f32_dpp v81, v81, v81 quad_perm:[1,0,3,2] row_mask:0xf bank_mask:0xf
	v_pk_mul_f32 v[4:5], v[62:63], v[4:5] op_sel:[0,0] op_sel_hi:[0,1]
	v_add_f32_dpp v80, v80, v80 quad_perm:[2,3,0,1] row_mask:0xf bank_mask:0xf
	v_add_f32_dpp v81, v81, v81 quad_perm:[2,3,0,1] row_mask:0xf bank_mask:0xf
	v_pk_mul_f32 v[6:7], v[62:63], v[6:7] op_sel:[1,0] op_sel_hi:[1,1]
	v_add_f32_dpp v80, v80, v80 row_half_mirror row_mask:0xf bank_mask:0xf
	v_add_f32_dpp v81, v81, v81 row_half_mirror row_mask:0xf bank_mask:0xf
	ds_write_b64 v102, v[88:89] offset:2048
	v_add_f32_dpp v80, v80, v80 row_mirror row_mask:0xf bank_mask:0xf
	v_add_f32_dpp v81, v81, v81 row_mirror row_mask:0xf bank_mask:0xf
	v_pk_fma_f32 v[0:1], v[80:81], v[72:73], v[0:1] op_sel:[0,0,0] op_sel_hi:[1,0,1] neg_lo:[1,0,0] neg_hi:[1,0,0]
	v_pk_fma_f32 v[2:3], v[80:81], v[72:73], v[2:3] op_sel:[0,1,0] op_sel_hi:[1,1,1] neg_lo:[1,0,0] neg_hi:[1,0,0]
	v_pk_fma_f32 v[4:5], v[80:81], v[74:75], v[4:5] op_sel:[0,0,0] op_sel_hi:[1,0,1] neg_lo:[1,0,0] neg_hi:[1,0,0]
	v_pk_fma_f32 v[6:7], v[80:81], v[74:75], v[6:7] op_sel:[0,1,0] op_sel_hi:[1,1,1] neg_lo:[1,0,0] neg_hi:[1,0,0]
	v_pk_fma_f32 v[0:1], v[76:77], v[64:65], v[0:1] op_sel:[0,0,0] op_sel_hi:[1,0,1]
	v_pk_fma_f32 v[2:3], v[76:77], v[64:65], v[2:3] op_sel:[0,1,0] op_sel_hi:[1,1,1]
	v_pk_fma_f32 v[4:5], v[76:77], v[66:67], v[4:5] op_sel:[0,0,0] op_sel_hi:[1,0,1]
	v_pk_fma_f32 v[6:7], v[76:77], v[66:67], v[6:7] op_sel:[0,1,0] op_sel_hi:[1,1,1]
	v_pk_mul_f32 v[84:85], v[56:57], v[0:1] op_sel:[0,0] op_sel_hi:[0,1]
	v_pk_mul_f32 v[86:87], v[56:57], v[2:3] op_sel:[1,0] op_sel_hi:[1,1]
	v_pk_fma_f32 v[84:85], v[58:59], v[4:5], v[84:85] op_sel:[0,0,0] op_sel_hi:[0,1,1]
	v_pk_fma_f32 v[86:87], v[58:59], v[6:7], v[86:87] op_sel:[1,0,0] op_sel_hi:[1,1,1]
	ds_read_b128 v[56:59], v100 offset:7680
	ds_read_b128 v[60:63], v100 offset:7936
	ds_read_b128 v[64:67], v100 offset:8192
	ds_read_b128 v[68:71], v100 offset:8448
	ds_read_b128 v[72:75], v100 offset:8704
	ds_read_b64 v[76:77], v101 offset:8960
	s_waitcnt lgkmcnt(14)
	v_pk_mul_f32 v[80:81], v[20:21], v[0:1] op_sel:[0,0] op_sel_hi:[0,1]
	v_pk_mul_f32 v[82:83], v[20:21], v[2:3] op_sel:[1,0] op_sel_hi:[1,1]
	v_pk_fma_f32 v[80:81], v[22:23], v[4:5], v[80:81] op_sel:[0,0,0] op_sel_hi:[0,1,1]
	v_pk_fma_f32 v[82:83], v[22:23], v[6:7], v[82:83] op_sel:[1,0,0] op_sel_hi:[1,1,1]
	v_pk_add_f32 v[84:85], v[84:85], v[86:87]
	v_pk_add_f32 v[80:81], v[80:81], v[82:83]
	v_pk_mul_f32 v[0:1], v[12:13], v[0:1] op_sel:[0,0] op_sel_hi:[0,1]
	v_pk_mul_f32 v[2:3], v[12:13], v[2:3] op_sel:[1,0] op_sel_hi:[1,1]
	v_add_f32_dpp v80, v80, v80 quad_perm:[1,0,3,2] row_mask:0xf bank_mask:0xf
	v_add_f32_dpp v81, v81, v81 quad_perm:[1,0,3,2] row_mask:0xf bank_mask:0xf
	v_pk_mul_f32 v[4:5], v[14:15], v[4:5] op_sel:[0,0] op_sel_hi:[0,1]
	v_add_f32_dpp v80, v80, v80 quad_perm:[2,3,0,1] row_mask:0xf bank_mask:0xf
	v_add_f32_dpp v81, v81, v81 quad_perm:[2,3,0,1] row_mask:0xf bank_mask:0xf
	v_pk_mul_f32 v[6:7], v[14:15], v[6:7] op_sel:[1,0] op_sel_hi:[1,1]
	v_add_f32_dpp v80, v80, v80 row_half_mirror row_mask:0xf bank_mask:0xf
	v_add_f32_dpp v81, v81, v81 row_half_mirror row_mask:0xf bank_mask:0xf
	ds_write_b64 v102, v[84:85] offset:4096
	v_add_f32_dpp v80, v80, v80 row_mirror row_mask:0xf bank_mask:0xf
	v_add_f32_dpp v81, v81, v81 row_mirror row_mask:0xf bank_mask:0xf
	v_pk_fma_f32 v[0:1], v[80:81], v[24:25], v[0:1] op_sel:[0,0,0] op_sel_hi:[1,0,1] neg_lo:[1,0,0] neg_hi:[1,0,0]
	v_pk_fma_f32 v[2:3], v[80:81], v[24:25], v[2:3] op_sel:[0,1,0] op_sel_hi:[1,1,1] neg_lo:[1,0,0] neg_hi:[1,0,0]
	v_pk_fma_f32 v[4:5], v[80:81], v[26:27], v[4:5] op_sel:[0,0,0] op_sel_hi:[1,0,1] neg_lo:[1,0,0] neg_hi:[1,0,0]
	v_pk_fma_f32 v[6:7], v[80:81], v[26:27], v[6:7] op_sel:[0,1,0] op_sel_hi:[1,1,1] neg_lo:[1,0,0] neg_hi:[1,0,0]
	v_pk_fma_f32 v[0:1], v[28:29], v[16:17], v[0:1] op_sel:[0,0,0] op_sel_hi:[1,0,1]
	v_pk_fma_f32 v[2:3], v[28:29], v[16:17], v[2:3] op_sel:[0,1,0] op_sel_hi:[1,1,1]
	v_pk_fma_f32 v[4:5], v[28:29], v[18:19], v[4:5] op_sel:[0,0,0] op_sel_hi:[1,0,1]
	v_pk_fma_f32 v[6:7], v[28:29], v[18:19], v[6:7] op_sel:[0,1,0] op_sel_hi:[1,1,1]
	v_pk_mul_f32 v[88:89], v[8:9], v[0:1] op_sel:[0,0] op_sel_hi:[0,1]
	v_pk_mul_f32 v[90:91], v[8:9], v[2:3] op_sel:[1,0] op_sel_hi:[1,1]
	v_pk_fma_f32 v[88:89], v[10:11], v[4:5], v[88:89] op_sel:[0,0,0] op_sel_hi:[0,1,1]
	v_pk_fma_f32 v[90:91], v[10:11], v[6:7], v[90:91] op_sel:[1,0,0] op_sel_hi:[1,1,1]
	ds_read_b128 v[8:11], v100 offset:9216
	ds_read_b128 v[12:15], v100 offset:9472
	ds_read_b128 v[16:19], v100 offset:9728
	ds_read_b128 v[20:23], v100 offset:9984
	ds_read_b128 v[24:27], v100 offset:10240
	ds_read_b64 v[28:29], v101 offset:10496
	s_waitcnt lgkmcnt(14)
	v_pk_mul_f32 v[80:81], v[44:45], v[0:1] op_sel:[0,0] op_sel_hi:[0,1]
	v_pk_mul_f32 v[82:83], v[44:45], v[2:3] op_sel:[1,0] op_sel_hi:[1,1]
	v_pk_fma_f32 v[80:81], v[46:47], v[4:5], v[80:81] op_sel:[0,0,0] op_sel_hi:[0,1,1]
	v_pk_fma_f32 v[82:83], v[46:47], v[6:7], v[82:83] op_sel:[1,0,0] op_sel_hi:[1,1,1]
	v_pk_add_f32 v[88:89], v[88:89], v[90:91]
	v_pk_add_f32 v[80:81], v[80:81], v[82:83]
	v_pk_mul_f32 v[0:1], v[36:37], v[0:1] op_sel:[0,0] op_sel_hi:[0,1]
	v_pk_mul_f32 v[2:3], v[36:37], v[2:3] op_sel:[1,0] op_sel_hi:[1,1]
	v_add_f32_dpp v80, v80, v80 quad_perm:[1,0,3,2] row_mask:0xf bank_mask:0xf
	v_add_f32_dpp v81, v81, v81 quad_perm:[1,0,3,2] row_mask:0xf bank_mask:0xf
	v_pk_mul_f32 v[4:5], v[38:39], v[4:5] op_sel:[0,0] op_sel_hi:[0,1]
	v_add_f32_dpp v80, v80, v80 quad_perm:[2,3,0,1] row_mask:0xf bank_mask:0xf
	v_add_f32_dpp v81, v81, v81 quad_perm:[2,3,0,1] row_mask:0xf bank_mask:0xf
	v_pk_mul_f32 v[6:7], v[38:39], v[6:7] op_sel:[1,0] op_sel_hi:[1,1]
	v_add_f32_dpp v80, v80, v80 row_half_mirror row_mask:0xf bank_mask:0xf
	v_add_f32_dpp v81, v81, v81 row_half_mirror row_mask:0xf bank_mask:0xf
	ds_write_b64 v102, v[88:89] offset:6144
	v_add_f32_dpp v80, v80, v80 row_mirror row_mask:0xf bank_mask:0xf
	v_add_f32_dpp v81, v81, v81 row_mirror row_mask:0xf bank_mask:0xf
	v_pk_fma_f32 v[0:1], v[80:81], v[48:49], v[0:1] op_sel:[0,0,0] op_sel_hi:[1,0,1] neg_lo:[1,0,0] neg_hi:[1,0,0]
	v_pk_fma_f32 v[2:3], v[80:81], v[48:49], v[2:3] op_sel:[0,1,0] op_sel_hi:[1,1,1] neg_lo:[1,0,0] neg_hi:[1,0,0]
	v_pk_fma_f32 v[4:5], v[80:81], v[50:51], v[4:5] op_sel:[0,0,0] op_sel_hi:[1,0,1] neg_lo:[1,0,0] neg_hi:[1,0,0]
	v_pk_fma_f32 v[6:7], v[80:81], v[50:51], v[6:7] op_sel:[0,1,0] op_sel_hi:[1,1,1] neg_lo:[1,0,0] neg_hi:[1,0,0]
	v_pk_fma_f32 v[0:1], v[52:53], v[40:41], v[0:1] op_sel:[0,0,0] op_sel_hi:[1,0,1]
	v_pk_fma_f32 v[2:3], v[52:53], v[40:41], v[2:3] op_sel:[0,1,0] op_sel_hi:[1,1,1]
	v_pk_fma_f32 v[4:5], v[52:53], v[42:43], v[4:5] op_sel:[0,0,0] op_sel_hi:[1,0,1]
	v_pk_fma_f32 v[6:7], v[52:53], v[42:43], v[6:7] op_sel:[0,1,0] op_sel_hi:[1,1,1]
	v_pk_mul_f32 v[84:85], v[32:33], v[0:1] op_sel:[0,0] op_sel_hi:[0,1]
	v_pk_mul_f32 v[86:87], v[32:33], v[2:3] op_sel:[1,0] op_sel_hi:[1,1]
	v_pk_fma_f32 v[84:85], v[34:35], v[4:5], v[84:85] op_sel:[0,0,0] op_sel_hi:[0,1,1]
	v_pk_fma_f32 v[86:87], v[34:35], v[6:7], v[86:87] op_sel:[1,0,0] op_sel_hi:[1,1,1]
	ds_read_b128 v[32:35], v100 offset:10752
	ds_read_b128 v[36:39], v100 offset:11008
	ds_read_b128 v[40:43], v100 offset:11264
	ds_read_b128 v[44:47], v100 offset:11520
	ds_read_b128 v[48:51], v100 offset:11776
	ds_read_b64 v[52:53], v101 offset:12032
	s_waitcnt lgkmcnt(14)
	v_pk_mul_f32 v[80:81], v[68:69], v[0:1] op_sel:[0,0] op_sel_hi:[0,1]
	v_pk_mul_f32 v[82:83], v[68:69], v[2:3] op_sel:[1,0] op_sel_hi:[1,1]
	v_pk_fma_f32 v[80:81], v[70:71], v[4:5], v[80:81] op_sel:[0,0,0] op_sel_hi:[0,1,1]
	v_pk_fma_f32 v[82:83], v[70:71], v[6:7], v[82:83] op_sel:[1,0,0] op_sel_hi:[1,1,1]
	v_pk_add_f32 v[84:85], v[84:85], v[86:87]
	v_pk_add_f32 v[80:81], v[80:81], v[82:83]
	v_pk_mul_f32 v[0:1], v[60:61], v[0:1] op_sel:[0,0] op_sel_hi:[0,1]
	v_pk_mul_f32 v[2:3], v[60:61], v[2:3] op_sel:[1,0] op_sel_hi:[1,1]
	v_add_f32_dpp v80, v80, v80 quad_perm:[1,0,3,2] row_mask:0xf bank_mask:0xf
	v_add_f32_dpp v81, v81, v81 quad_perm:[1,0,3,2] row_mask:0xf bank_mask:0xf
	v_pk_mul_f32 v[4:5], v[62:63], v[4:5] op_sel:[0,0] op_sel_hi:[0,1]
	v_add_f32_dpp v80, v80, v80 quad_perm:[2,3,0,1] row_mask:0xf bank_mask:0xf
	v_add_f32_dpp v81, v81, v81 quad_perm:[2,3,0,1] row_mask:0xf bank_mask:0xf
	v_pk_mul_f32 v[6:7], v[62:63], v[6:7] op_sel:[1,0] op_sel_hi:[1,1]
	v_add_f32_dpp v80, v80, v80 row_half_mirror row_mask:0xf bank_mask:0xf
	v_add_f32_dpp v81, v81, v81 row_half_mirror row_mask:0xf bank_mask:0xf
	ds_write_b64 v102, v[84:85] offset:8192
	v_add_f32_dpp v80, v80, v80 row_mirror row_mask:0xf bank_mask:0xf
	v_add_f32_dpp v81, v81, v81 row_mirror row_mask:0xf bank_mask:0xf
	v_pk_fma_f32 v[0:1], v[80:81], v[72:73], v[0:1] op_sel:[0,0,0] op_sel_hi:[1,0,1] neg_lo:[1,0,0] neg_hi:[1,0,0]
	v_pk_fma_f32 v[2:3], v[80:81], v[72:73], v[2:3] op_sel:[0,1,0] op_sel_hi:[1,1,1] neg_lo:[1,0,0] neg_hi:[1,0,0]
	v_pk_fma_f32 v[4:5], v[80:81], v[74:75], v[4:5] op_sel:[0,0,0] op_sel_hi:[1,0,1] neg_lo:[1,0,0] neg_hi:[1,0,0]
	v_pk_fma_f32 v[6:7], v[80:81], v[74:75], v[6:7] op_sel:[0,1,0] op_sel_hi:[1,1,1] neg_lo:[1,0,0] neg_hi:[1,0,0]
	v_pk_fma_f32 v[0:1], v[76:77], v[64:65], v[0:1] op_sel:[0,0,0] op_sel_hi:[1,0,1]
	v_pk_fma_f32 v[2:3], v[76:77], v[64:65], v[2:3] op_sel:[0,1,0] op_sel_hi:[1,1,1]
	v_pk_fma_f32 v[4:5], v[76:77], v[66:67], v[4:5] op_sel:[0,0,0] op_sel_hi:[1,0,1]
	v_pk_fma_f32 v[6:7], v[76:77], v[66:67], v[6:7] op_sel:[0,1,0] op_sel_hi:[1,1,1]
	v_pk_mul_f32 v[88:89], v[56:57], v[0:1] op_sel:[0,0] op_sel_hi:[0,1]
	v_pk_mul_f32 v[90:91], v[56:57], v[2:3] op_sel:[1,0] op_sel_hi:[1,1]
	v_pk_fma_f32 v[88:89], v[58:59], v[4:5], v[88:89] op_sel:[0,0,0] op_sel_hi:[0,1,1]
	v_pk_fma_f32 v[90:91], v[58:59], v[6:7], v[90:91] op_sel:[1,0,0] op_sel_hi:[1,1,1]
	ds_read_b128 v[56:59], v100 offset:12288
	ds_read_b128 v[60:63], v100 offset:12544
	ds_read_b128 v[64:67], v100 offset:12800
	ds_read_b128 v[68:71], v100 offset:13056
	ds_read_b128 v[72:75], v100 offset:13312
	ds_read_b64 v[76:77], v101 offset:13568
	s_waitcnt lgkmcnt(14)
	v_pk_mul_f32 v[80:81], v[20:21], v[0:1] op_sel:[0,0] op_sel_hi:[0,1]
	v_pk_mul_f32 v[82:83], v[20:21], v[2:3] op_sel:[1,0] op_sel_hi:[1,1]
	v_pk_fma_f32 v[80:81], v[22:23], v[4:5], v[80:81] op_sel:[0,0,0] op_sel_hi:[0,1,1]
	v_pk_fma_f32 v[82:83], v[22:23], v[6:7], v[82:83] op_sel:[1,0,0] op_sel_hi:[1,1,1]
	v_pk_add_f32 v[88:89], v[88:89], v[90:91]
	v_pk_add_f32 v[80:81], v[80:81], v[82:83]
	v_pk_mul_f32 v[0:1], v[12:13], v[0:1] op_sel:[0,0] op_sel_hi:[0,1]
	v_pk_mul_f32 v[2:3], v[12:13], v[2:3] op_sel:[1,0] op_sel_hi:[1,1]
	v_add_f32_dpp v80, v80, v80 quad_perm:[1,0,3,2] row_mask:0xf bank_mask:0xf
	v_add_f32_dpp v81, v81, v81 quad_perm:[1,0,3,2] row_mask:0xf bank_mask:0xf
	v_pk_mul_f32 v[4:5], v[14:15], v[4:5] op_sel:[0,0] op_sel_hi:[0,1]
	v_add_f32_dpp v80, v80, v80 quad_perm:[2,3,0,1] row_mask:0xf bank_mask:0xf
	v_add_f32_dpp v81, v81, v81 quad_perm:[2,3,0,1] row_mask:0xf bank_mask:0xf
	v_pk_mul_f32 v[6:7], v[14:15], v[6:7] op_sel:[1,0] op_sel_hi:[1,1]
	v_add_f32_dpp v80, v80, v80 row_half_mirror row_mask:0xf bank_mask:0xf
	v_add_f32_dpp v81, v81, v81 row_half_mirror row_mask:0xf bank_mask:0xf
	ds_write_b64 v102, v[88:89] offset:10240
	v_add_f32_dpp v80, v80, v80 row_mirror row_mask:0xf bank_mask:0xf
	v_add_f32_dpp v81, v81, v81 row_mirror row_mask:0xf bank_mask:0xf
	v_pk_fma_f32 v[0:1], v[80:81], v[24:25], v[0:1] op_sel:[0,0,0] op_sel_hi:[1,0,1] neg_lo:[1,0,0] neg_hi:[1,0,0]
	v_pk_fma_f32 v[2:3], v[80:81], v[24:25], v[2:3] op_sel:[0,1,0] op_sel_hi:[1,1,1] neg_lo:[1,0,0] neg_hi:[1,0,0]
	v_pk_fma_f32 v[4:5], v[80:81], v[26:27], v[4:5] op_sel:[0,0,0] op_sel_hi:[1,0,1] neg_lo:[1,0,0] neg_hi:[1,0,0]
	v_pk_fma_f32 v[6:7], v[80:81], v[26:27], v[6:7] op_sel:[0,1,0] op_sel_hi:[1,1,1] neg_lo:[1,0,0] neg_hi:[1,0,0]
	v_pk_fma_f32 v[0:1], v[28:29], v[16:17], v[0:1] op_sel:[0,0,0] op_sel_hi:[1,0,1]
	v_pk_fma_f32 v[2:3], v[28:29], v[16:17], v[2:3] op_sel:[0,1,0] op_sel_hi:[1,1,1]
	v_pk_fma_f32 v[4:5], v[28:29], v[18:19], v[4:5] op_sel:[0,0,0] op_sel_hi:[1,0,1]
	v_pk_fma_f32 v[6:7], v[28:29], v[18:19], v[6:7] op_sel:[0,1,0] op_sel_hi:[1,1,1]
	v_pk_mul_f32 v[84:85], v[8:9], v[0:1] op_sel:[0,0] op_sel_hi:[0,1]
	v_pk_mul_f32 v[86:87], v[8:9], v[2:3] op_sel:[1,0] op_sel_hi:[1,1]
	v_pk_fma_f32 v[84:85], v[10:11], v[4:5], v[84:85] op_sel:[0,0,0] op_sel_hi:[0,1,1]
	v_pk_fma_f32 v[86:87], v[10:11], v[6:7], v[86:87] op_sel:[1,0,0] op_sel_hi:[1,1,1]
	ds_read_b128 v[8:11], v100 offset:13824
	ds_read_b128 v[12:15], v100 offset:14080
	ds_read_b128 v[16:19], v100 offset:14336
	ds_read_b128 v[20:23], v100 offset:14592
	ds_read_b128 v[24:27], v100 offset:14848
	ds_read_b64 v[28:29], v101 offset:15104
	s_waitcnt lgkmcnt(14)
	v_pk_mul_f32 v[80:81], v[44:45], v[0:1] op_sel:[0,0] op_sel_hi:[0,1]
	v_pk_mul_f32 v[82:83], v[44:45], v[2:3] op_sel:[1,0] op_sel_hi:[1,1]
	v_pk_fma_f32 v[80:81], v[46:47], v[4:5], v[80:81] op_sel:[0,0,0] op_sel_hi:[0,1,1]
	v_pk_fma_f32 v[82:83], v[46:47], v[6:7], v[82:83] op_sel:[1,0,0] op_sel_hi:[1,1,1]
	v_pk_add_f32 v[84:85], v[84:85], v[86:87]
	v_pk_add_f32 v[80:81], v[80:81], v[82:83]
	v_pk_mul_f32 v[0:1], v[36:37], v[0:1] op_sel:[0,0] op_sel_hi:[0,1]
	v_pk_mul_f32 v[2:3], v[36:37], v[2:3] op_sel:[1,0] op_sel_hi:[1,1]
	v_add_f32_dpp v80, v80, v80 quad_perm:[1,0,3,2] row_mask:0xf bank_mask:0xf
	v_add_f32_dpp v81, v81, v81 quad_perm:[1,0,3,2] row_mask:0xf bank_mask:0xf
	v_pk_mul_f32 v[4:5], v[38:39], v[4:5] op_sel:[0,0] op_sel_hi:[0,1]
	v_add_f32_dpp v80, v80, v80 quad_perm:[2,3,0,1] row_mask:0xf bank_mask:0xf
	v_add_f32_dpp v81, v81, v81 quad_perm:[2,3,0,1] row_mask:0xf bank_mask:0xf
	v_pk_mul_f32 v[6:7], v[38:39], v[6:7] op_sel:[1,0] op_sel_hi:[1,1]
	v_add_f32_dpp v80, v80, v80 row_half_mirror row_mask:0xf bank_mask:0xf
	v_add_f32_dpp v81, v81, v81 row_half_mirror row_mask:0xf bank_mask:0xf
	ds_write_b64 v102, v[84:85] offset:12288
	v_add_f32_dpp v80, v80, v80 row_mirror row_mask:0xf bank_mask:0xf
	v_add_f32_dpp v81, v81, v81 row_mirror row_mask:0xf bank_mask:0xf
	v_pk_fma_f32 v[0:1], v[80:81], v[48:49], v[0:1] op_sel:[0,0,0] op_sel_hi:[1,0,1] neg_lo:[1,0,0] neg_hi:[1,0,0]
	v_pk_fma_f32 v[2:3], v[80:81], v[48:49], v[2:3] op_sel:[0,1,0] op_sel_hi:[1,1,1] neg_lo:[1,0,0] neg_hi:[1,0,0]
	v_pk_fma_f32 v[4:5], v[80:81], v[50:51], v[4:5] op_sel:[0,0,0] op_sel_hi:[1,0,1] neg_lo:[1,0,0] neg_hi:[1,0,0]
	v_pk_fma_f32 v[6:7], v[80:81], v[50:51], v[6:7] op_sel:[0,1,0] op_sel_hi:[1,1,1] neg_lo:[1,0,0] neg_hi:[1,0,0]
	v_pk_fma_f32 v[0:1], v[52:53], v[40:41], v[0:1] op_sel:[0,0,0] op_sel_hi:[1,0,1]
	v_pk_fma_f32 v[2:3], v[52:53], v[40:41], v[2:3] op_sel:[0,1,0] op_sel_hi:[1,1,1]
	v_pk_fma_f32 v[4:5], v[52:53], v[42:43], v[4:5] op_sel:[0,0,0] op_sel_hi:[1,0,1]
	v_pk_fma_f32 v[6:7], v[52:53], v[42:43], v[6:7] op_sel:[0,1,0] op_sel_hi:[1,1,1]
	v_pk_mul_f32 v[88:89], v[32:33], v[0:1] op_sel:[0,0] op_sel_hi:[0,1]
	v_pk_mul_f32 v[90:91], v[32:33], v[2:3] op_sel:[1,0] op_sel_hi:[1,1]
	v_pk_fma_f32 v[88:89], v[34:35], v[4:5], v[88:89] op_sel:[0,0,0] op_sel_hi:[0,1,1]
	v_pk_fma_f32 v[90:91], v[34:35], v[6:7], v[90:91] op_sel:[1,0,0] op_sel_hi:[1,1,1]
	ds_read_b128 v[32:35], v100 offset:15360
	ds_read_b128 v[36:39], v100 offset:15616
	ds_read_b128 v[40:43], v100 offset:15872
	ds_read_b128 v[44:47], v100 offset:16128
	ds_read_b128 v[48:51], v100 offset:16384
	ds_read_b64 v[52:53], v101 offset:16640
	s_waitcnt lgkmcnt(14)
	v_pk_mul_f32 v[80:81], v[68:69], v[0:1] op_sel:[0,0] op_sel_hi:[0,1]
	v_pk_mul_f32 v[82:83], v[68:69], v[2:3] op_sel:[1,0] op_sel_hi:[1,1]
	v_pk_fma_f32 v[80:81], v[70:71], v[4:5], v[80:81] op_sel:[0,0,0] op_sel_hi:[0,1,1]
	v_pk_fma_f32 v[82:83], v[70:71], v[6:7], v[82:83] op_sel:[1,0,0] op_sel_hi:[1,1,1]
	v_pk_add_f32 v[88:89], v[88:89], v[90:91]
	v_pk_add_f32 v[80:81], v[80:81], v[82:83]
	v_pk_mul_f32 v[0:1], v[60:61], v[0:1] op_sel:[0,0] op_sel_hi:[0,1]
	v_pk_mul_f32 v[2:3], v[60:61], v[2:3] op_sel:[1,0] op_sel_hi:[1,1]
	v_add_f32_dpp v80, v80, v80 quad_perm:[1,0,3,2] row_mask:0xf bank_mask:0xf
	v_add_f32_dpp v81, v81, v81 quad_perm:[1,0,3,2] row_mask:0xf bank_mask:0xf
	v_pk_mul_f32 v[4:5], v[62:63], v[4:5] op_sel:[0,0] op_sel_hi:[0,1]
	v_add_f32_dpp v80, v80, v80 quad_perm:[2,3,0,1] row_mask:0xf bank_mask:0xf
	v_add_f32_dpp v81, v81, v81 quad_perm:[2,3,0,1] row_mask:0xf bank_mask:0xf
	v_pk_mul_f32 v[6:7], v[62:63], v[6:7] op_sel:[1,0] op_sel_hi:[1,1]
	v_add_f32_dpp v80, v80, v80 row_half_mirror row_mask:0xf bank_mask:0xf
	v_add_f32_dpp v81, v81, v81 row_half_mirror row_mask:0xf bank_mask:0xf
	ds_write_b64 v102, v[88:89] offset:14336
	v_add_f32_dpp v80, v80, v80 row_mirror row_mask:0xf bank_mask:0xf
	v_add_f32_dpp v81, v81, v81 row_mirror row_mask:0xf bank_mask:0xf
	v_pk_fma_f32 v[0:1], v[80:81], v[72:73], v[0:1] op_sel:[0,0,0] op_sel_hi:[1,0,1] neg_lo:[1,0,0] neg_hi:[1,0,0]
	v_pk_fma_f32 v[2:3], v[80:81], v[72:73], v[2:3] op_sel:[0,1,0] op_sel_hi:[1,1,1] neg_lo:[1,0,0] neg_hi:[1,0,0]
	v_pk_fma_f32 v[4:5], v[80:81], v[74:75], v[4:5] op_sel:[0,0,0] op_sel_hi:[1,0,1] neg_lo:[1,0,0] neg_hi:[1,0,0]
	v_pk_fma_f32 v[6:7], v[80:81], v[74:75], v[6:7] op_sel:[0,1,0] op_sel_hi:[1,1,1] neg_lo:[1,0,0] neg_hi:[1,0,0]
	v_pk_fma_f32 v[0:1], v[76:77], v[64:65], v[0:1] op_sel:[0,0,0] op_sel_hi:[1,0,1]
	v_pk_fma_f32 v[2:3], v[76:77], v[64:65], v[2:3] op_sel:[0,1,0] op_sel_hi:[1,1,1]
	v_pk_fma_f32 v[4:5], v[76:77], v[66:67], v[4:5] op_sel:[0,0,0] op_sel_hi:[1,0,1]
	v_pk_fma_f32 v[6:7], v[76:77], v[66:67], v[6:7] op_sel:[0,1,0] op_sel_hi:[1,1,1]
	v_pk_mul_f32 v[84:85], v[56:57], v[0:1] op_sel:[0,0] op_sel_hi:[0,1]
	v_pk_mul_f32 v[86:87], v[56:57], v[2:3] op_sel:[1,0] op_sel_hi:[1,1]
	v_pk_fma_f32 v[84:85], v[58:59], v[4:5], v[84:85] op_sel:[0,0,0] op_sel_hi:[0,1,1]
	v_pk_fma_f32 v[86:87], v[58:59], v[6:7], v[86:87] op_sel:[1,0,0] op_sel_hi:[1,1,1]
	ds_read_b128 v[56:59], v100 offset:16896
	ds_read_b128 v[60:63], v100 offset:17152
	ds_read_b128 v[64:67], v100 offset:17408
	ds_read_b128 v[68:71], v100 offset:17664
	ds_read_b128 v[72:75], v100 offset:17920
	ds_read_b64 v[76:77], v101 offset:18176
	s_waitcnt lgkmcnt(14)
	v_pk_mul_f32 v[80:81], v[20:21], v[0:1] op_sel:[0,0] op_sel_hi:[0,1]
	v_pk_mul_f32 v[82:83], v[20:21], v[2:3] op_sel:[1,0] op_sel_hi:[1,1]
	v_pk_fma_f32 v[80:81], v[22:23], v[4:5], v[80:81] op_sel:[0,0,0] op_sel_hi:[0,1,1]
	v_pk_fma_f32 v[82:83], v[22:23], v[6:7], v[82:83] op_sel:[1,0,0] op_sel_hi:[1,1,1]
	v_pk_add_f32 v[84:85], v[84:85], v[86:87]
	v_pk_add_f32 v[80:81], v[80:81], v[82:83]
	v_pk_mul_f32 v[0:1], v[12:13], v[0:1] op_sel:[0,0] op_sel_hi:[0,1]
	v_pk_mul_f32 v[2:3], v[12:13], v[2:3] op_sel:[1,0] op_sel_hi:[1,1]
	v_add_f32_dpp v80, v80, v80 quad_perm:[1,0,3,2] row_mask:0xf bank_mask:0xf
	v_add_f32_dpp v81, v81, v81 quad_perm:[1,0,3,2] row_mask:0xf bank_mask:0xf
	v_pk_mul_f32 v[4:5], v[14:15], v[4:5] op_sel:[0,0] op_sel_hi:[0,1]
	v_add_f32_dpp v80, v80, v80 quad_perm:[2,3,0,1] row_mask:0xf bank_mask:0xf
	v_add_f32_dpp v81, v81, v81 quad_perm:[2,3,0,1] row_mask:0xf bank_mask:0xf
	v_pk_mul_f32 v[6:7], v[14:15], v[6:7] op_sel:[1,0] op_sel_hi:[1,1]
	v_add_f32_dpp v80, v80, v80 row_half_mirror row_mask:0xf bank_mask:0xf
	v_add_f32_dpp v81, v81, v81 row_half_mirror row_mask:0xf bank_mask:0xf
	ds_write_b64 v102, v[84:85] offset:16384
	v_add_f32_dpp v80, v80, v80 row_mirror row_mask:0xf bank_mask:0xf
	v_add_f32_dpp v81, v81, v81 row_mirror row_mask:0xf bank_mask:0xf
	v_pk_fma_f32 v[0:1], v[80:81], v[24:25], v[0:1] op_sel:[0,0,0] op_sel_hi:[1,0,1] neg_lo:[1,0,0] neg_hi:[1,0,0]
	v_pk_fma_f32 v[2:3], v[80:81], v[24:25], v[2:3] op_sel:[0,1,0] op_sel_hi:[1,1,1] neg_lo:[1,0,0] neg_hi:[1,0,0]
	v_pk_fma_f32 v[4:5], v[80:81], v[26:27], v[4:5] op_sel:[0,0,0] op_sel_hi:[1,0,1] neg_lo:[1,0,0] neg_hi:[1,0,0]
	v_pk_fma_f32 v[6:7], v[80:81], v[26:27], v[6:7] op_sel:[0,1,0] op_sel_hi:[1,1,1] neg_lo:[1,0,0] neg_hi:[1,0,0]
	v_pk_fma_f32 v[0:1], v[28:29], v[16:17], v[0:1] op_sel:[0,0,0] op_sel_hi:[1,0,1]
	v_pk_fma_f32 v[2:3], v[28:29], v[16:17], v[2:3] op_sel:[0,1,0] op_sel_hi:[1,1,1]
	v_pk_fma_f32 v[4:5], v[28:29], v[18:19], v[4:5] op_sel:[0,0,0] op_sel_hi:[1,0,1]
	v_pk_fma_f32 v[6:7], v[28:29], v[18:19], v[6:7] op_sel:[0,1,0] op_sel_hi:[1,1,1]
	v_pk_mul_f32 v[88:89], v[8:9], v[0:1] op_sel:[0,0] op_sel_hi:[0,1]
	v_pk_mul_f32 v[90:91], v[8:9], v[2:3] op_sel:[1,0] op_sel_hi:[1,1]
	v_pk_fma_f32 v[88:89], v[10:11], v[4:5], v[88:89] op_sel:[0,0,0] op_sel_hi:[0,1,1]
	v_pk_fma_f32 v[90:91], v[10:11], v[6:7], v[90:91] op_sel:[1,0,0] op_sel_hi:[1,1,1]
	ds_read_b128 v[8:11], v100 offset:18432
	ds_read_b128 v[12:15], v100 offset:18688
	ds_read_b128 v[16:19], v100 offset:18944
	ds_read_b128 v[20:23], v100 offset:19200
	ds_read_b128 v[24:27], v100 offset:19456
	ds_read_b64 v[28:29], v101 offset:19712
	s_waitcnt lgkmcnt(14)
	v_pk_mul_f32 v[80:81], v[44:45], v[0:1] op_sel:[0,0] op_sel_hi:[0,1]
	v_pk_mul_f32 v[82:83], v[44:45], v[2:3] op_sel:[1,0] op_sel_hi:[1,1]
	v_pk_fma_f32 v[80:81], v[46:47], v[4:5], v[80:81] op_sel:[0,0,0] op_sel_hi:[0,1,1]
	v_pk_fma_f32 v[82:83], v[46:47], v[6:7], v[82:83] op_sel:[1,0,0] op_sel_hi:[1,1,1]
	v_pk_add_f32 v[88:89], v[88:89], v[90:91]
	v_pk_add_f32 v[80:81], v[80:81], v[82:83]
	v_pk_mul_f32 v[0:1], v[36:37], v[0:1] op_sel:[0,0] op_sel_hi:[0,1]
	v_pk_mul_f32 v[2:3], v[36:37], v[2:3] op_sel:[1,0] op_sel_hi:[1,1]
	v_add_f32_dpp v80, v80, v80 quad_perm:[1,0,3,2] row_mask:0xf bank_mask:0xf
	v_add_f32_dpp v81, v81, v81 quad_perm:[1,0,3,2] row_mask:0xf bank_mask:0xf
	v_pk_mul_f32 v[4:5], v[38:39], v[4:5] op_sel:[0,0] op_sel_hi:[0,1]
	v_add_f32_dpp v80, v80, v80 quad_perm:[2,3,0,1] row_mask:0xf bank_mask:0xf
	v_add_f32_dpp v81, v81, v81 quad_perm:[2,3,0,1] row_mask:0xf bank_mask:0xf
	v_pk_mul_f32 v[6:7], v[38:39], v[6:7] op_sel:[1,0] op_sel_hi:[1,1]
	v_add_f32_dpp v80, v80, v80 row_half_mirror row_mask:0xf bank_mask:0xf
	v_add_f32_dpp v81, v81, v81 row_half_mirror row_mask:0xf bank_mask:0xf
	ds_write_b64 v102, v[88:89] offset:18432
	v_add_f32_dpp v80, v80, v80 row_mirror row_mask:0xf bank_mask:0xf
	v_add_f32_dpp v81, v81, v81 row_mirror row_mask:0xf bank_mask:0xf
	v_pk_fma_f32 v[0:1], v[80:81], v[48:49], v[0:1] op_sel:[0,0,0] op_sel_hi:[1,0,1] neg_lo:[1,0,0] neg_hi:[1,0,0]
	v_pk_fma_f32 v[2:3], v[80:81], v[48:49], v[2:3] op_sel:[0,1,0] op_sel_hi:[1,1,1] neg_lo:[1,0,0] neg_hi:[1,0,0]
	v_pk_fma_f32 v[4:5], v[80:81], v[50:51], v[4:5] op_sel:[0,0,0] op_sel_hi:[1,0,1] neg_lo:[1,0,0] neg_hi:[1,0,0]
	v_pk_fma_f32 v[6:7], v[80:81], v[50:51], v[6:7] op_sel:[0,1,0] op_sel_hi:[1,1,1] neg_lo:[1,0,0] neg_hi:[1,0,0]
	v_pk_fma_f32 v[0:1], v[52:53], v[40:41], v[0:1] op_sel:[0,0,0] op_sel_hi:[1,0,1]
	v_pk_fma_f32 v[2:3], v[52:53], v[40:41], v[2:3] op_sel:[0,1,0] op_sel_hi:[1,1,1]
	v_pk_fma_f32 v[4:5], v[52:53], v[42:43], v[4:5] op_sel:[0,0,0] op_sel_hi:[1,0,1]
	v_pk_fma_f32 v[6:7], v[52:53], v[42:43], v[6:7] op_sel:[0,1,0] op_sel_hi:[1,1,1]
	v_pk_mul_f32 v[84:85], v[32:33], v[0:1] op_sel:[0,0] op_sel_hi:[0,1]
	v_pk_mul_f32 v[86:87], v[32:33], v[2:3] op_sel:[1,0] op_sel_hi:[1,1]
	v_pk_fma_f32 v[84:85], v[34:35], v[4:5], v[84:85] op_sel:[0,0,0] op_sel_hi:[0,1,1]
	v_pk_fma_f32 v[86:87], v[34:35], v[6:7], v[86:87] op_sel:[1,0,0] op_sel_hi:[1,1,1]
	ds_read_b128 v[32:35], v100 offset:19968
	ds_read_b128 v[36:39], v100 offset:20224
	ds_read_b128 v[40:43], v100 offset:20480
	ds_read_b128 v[44:47], v100 offset:20736
	ds_read_b128 v[48:51], v100 offset:20992
	ds_read_b64 v[52:53], v101 offset:21248
	s_waitcnt lgkmcnt(14)
	v_pk_mul_f32 v[80:81], v[68:69], v[0:1] op_sel:[0,0] op_sel_hi:[0,1]
	v_pk_mul_f32 v[82:83], v[68:69], v[2:3] op_sel:[1,0] op_sel_hi:[1,1]
	v_pk_fma_f32 v[80:81], v[70:71], v[4:5], v[80:81] op_sel:[0,0,0] op_sel_hi:[0,1,1]
	v_pk_fma_f32 v[82:83], v[70:71], v[6:7], v[82:83] op_sel:[1,0,0] op_sel_hi:[1,1,1]
	v_pk_add_f32 v[84:85], v[84:85], v[86:87]
	v_pk_add_f32 v[80:81], v[80:81], v[82:83]
	v_pk_mul_f32 v[0:1], v[60:61], v[0:1] op_sel:[0,0] op_sel_hi:[0,1]
	v_pk_mul_f32 v[2:3], v[60:61], v[2:3] op_sel:[1,0] op_sel_hi:[1,1]
	v_add_f32_dpp v80, v80, v80 quad_perm:[1,0,3,2] row_mask:0xf bank_mask:0xf
	v_add_f32_dpp v81, v81, v81 quad_perm:[1,0,3,2] row_mask:0xf bank_mask:0xf
	v_pk_mul_f32 v[4:5], v[62:63], v[4:5] op_sel:[0,0] op_sel_hi:[0,1]
	v_add_f32_dpp v80, v80, v80 quad_perm:[2,3,0,1] row_mask:0xf bank_mask:0xf
	v_add_f32_dpp v81, v81, v81 quad_perm:[2,3,0,1] row_mask:0xf bank_mask:0xf
	v_pk_mul_f32 v[6:7], v[62:63], v[6:7] op_sel:[1,0] op_sel_hi:[1,1]
	v_add_f32_dpp v80, v80, v80 row_half_mirror row_mask:0xf bank_mask:0xf
	v_add_f32_dpp v81, v81, v81 row_half_mirror row_mask:0xf bank_mask:0xf
	ds_write_b64 v102, v[84:85] offset:20480
	v_add_f32_dpp v80, v80, v80 row_mirror row_mask:0xf bank_mask:0xf
	v_add_f32_dpp v81, v81, v81 row_mirror row_mask:0xf bank_mask:0xf
	v_pk_fma_f32 v[0:1], v[80:81], v[72:73], v[0:1] op_sel:[0,0,0] op_sel_hi:[1,0,1] neg_lo:[1,0,0] neg_hi:[1,0,0]
	v_pk_fma_f32 v[2:3], v[80:81], v[72:73], v[2:3] op_sel:[0,1,0] op_sel_hi:[1,1,1] neg_lo:[1,0,0] neg_hi:[1,0,0]
	v_pk_fma_f32 v[4:5], v[80:81], v[74:75], v[4:5] op_sel:[0,0,0] op_sel_hi:[1,0,1] neg_lo:[1,0,0] neg_hi:[1,0,0]
	v_pk_fma_f32 v[6:7], v[80:81], v[74:75], v[6:7] op_sel:[0,1,0] op_sel_hi:[1,1,1] neg_lo:[1,0,0] neg_hi:[1,0,0]
	v_pk_fma_f32 v[0:1], v[76:77], v[64:65], v[0:1] op_sel:[0,0,0] op_sel_hi:[1,0,1]
	v_pk_fma_f32 v[2:3], v[76:77], v[64:65], v[2:3] op_sel:[0,1,0] op_sel_hi:[1,1,1]
	v_pk_fma_f32 v[4:5], v[76:77], v[66:67], v[4:5] op_sel:[0,0,0] op_sel_hi:[1,0,1]
	v_pk_fma_f32 v[6:7], v[76:77], v[66:67], v[6:7] op_sel:[0,1,0] op_sel_hi:[1,1,1]
	v_pk_mul_f32 v[88:89], v[56:57], v[0:1] op_sel:[0,0] op_sel_hi:[0,1]
	v_pk_mul_f32 v[90:91], v[56:57], v[2:3] op_sel:[1,0] op_sel_hi:[1,1]
	v_pk_fma_f32 v[88:89], v[58:59], v[4:5], v[88:89] op_sel:[0,0,0] op_sel_hi:[0,1,1]
	v_pk_fma_f32 v[90:91], v[58:59], v[6:7], v[90:91] op_sel:[1,0,0] op_sel_hi:[1,1,1]
	ds_read_b128 v[56:59], v100 offset:21504
	ds_read_b128 v[60:63], v100 offset:21760
	ds_read_b128 v[64:67], v100 offset:22016
	ds_read_b128 v[68:71], v100 offset:22272
	ds_read_b128 v[72:75], v100 offset:22528
	ds_read_b64 v[76:77], v101 offset:22784
	s_waitcnt lgkmcnt(14)
	v_pk_mul_f32 v[80:81], v[20:21], v[0:1] op_sel:[0,0] op_sel_hi:[0,1]
	v_pk_mul_f32 v[82:83], v[20:21], v[2:3] op_sel:[1,0] op_sel_hi:[1,1]
	v_pk_fma_f32 v[80:81], v[22:23], v[4:5], v[80:81] op_sel:[0,0,0] op_sel_hi:[0,1,1]
	v_pk_fma_f32 v[82:83], v[22:23], v[6:7], v[82:83] op_sel:[1,0,0] op_sel_hi:[1,1,1]
	v_pk_add_f32 v[88:89], v[88:89], v[90:91]
	v_pk_add_f32 v[80:81], v[80:81], v[82:83]
	v_pk_mul_f32 v[0:1], v[12:13], v[0:1] op_sel:[0,0] op_sel_hi:[0,1]
	v_pk_mul_f32 v[2:3], v[12:13], v[2:3] op_sel:[1,0] op_sel_hi:[1,1]
	v_add_f32_dpp v80, v80, v80 quad_perm:[1,0,3,2] row_mask:0xf bank_mask:0xf
	v_add_f32_dpp v81, v81, v81 quad_perm:[1,0,3,2] row_mask:0xf bank_mask:0xf
	v_pk_mul_f32 v[4:5], v[14:15], v[4:5] op_sel:[0,0] op_sel_hi:[0,1]
	v_add_f32_dpp v80, v80, v80 quad_perm:[2,3,0,1] row_mask:0xf bank_mask:0xf
	v_add_f32_dpp v81, v81, v81 quad_perm:[2,3,0,1] row_mask:0xf bank_mask:0xf
	v_pk_mul_f32 v[6:7], v[14:15], v[6:7] op_sel:[1,0] op_sel_hi:[1,1]
	v_add_f32_dpp v80, v80, v80 row_half_mirror row_mask:0xf bank_mask:0xf
	v_add_f32_dpp v81, v81, v81 row_half_mirror row_mask:0xf bank_mask:0xf
	ds_write_b64 v102, v[88:89] offset:22528
	v_add_f32_dpp v80, v80, v80 row_mirror row_mask:0xf bank_mask:0xf
	v_add_f32_dpp v81, v81, v81 row_mirror row_mask:0xf bank_mask:0xf
	v_pk_fma_f32 v[0:1], v[80:81], v[24:25], v[0:1] op_sel:[0,0,0] op_sel_hi:[1,0,1] neg_lo:[1,0,0] neg_hi:[1,0,0]
	v_pk_fma_f32 v[2:3], v[80:81], v[24:25], v[2:3] op_sel:[0,1,0] op_sel_hi:[1,1,1] neg_lo:[1,0,0] neg_hi:[1,0,0]
	v_pk_fma_f32 v[4:5], v[80:81], v[26:27], v[4:5] op_sel:[0,0,0] op_sel_hi:[1,0,1] neg_lo:[1,0,0] neg_hi:[1,0,0]
	v_pk_fma_f32 v[6:7], v[80:81], v[26:27], v[6:7] op_sel:[0,1,0] op_sel_hi:[1,1,1] neg_lo:[1,0,0] neg_hi:[1,0,0]
	v_pk_fma_f32 v[0:1], v[28:29], v[16:17], v[0:1] op_sel:[0,0,0] op_sel_hi:[1,0,1]
	v_pk_fma_f32 v[2:3], v[28:29], v[16:17], v[2:3] op_sel:[0,1,0] op_sel_hi:[1,1,1]
	v_pk_fma_f32 v[4:5], v[28:29], v[18:19], v[4:5] op_sel:[0,0,0] op_sel_hi:[1,0,1]
	v_pk_fma_f32 v[6:7], v[28:29], v[18:19], v[6:7] op_sel:[0,1,0] op_sel_hi:[1,1,1]
	v_pk_mul_f32 v[84:85], v[8:9], v[0:1] op_sel:[0,0] op_sel_hi:[0,1]
	v_pk_mul_f32 v[86:87], v[8:9], v[2:3] op_sel:[1,0] op_sel_hi:[1,1]
	v_pk_fma_f32 v[84:85], v[10:11], v[4:5], v[84:85] op_sel:[0,0,0] op_sel_hi:[0,1,1]
	v_pk_fma_f32 v[86:87], v[10:11], v[6:7], v[86:87] op_sel:[1,0,0] op_sel_hi:[1,1,1]
	ds_read_b128 v[8:11], v100 offset:23040
	ds_read_b128 v[12:15], v100 offset:23296
	ds_read_b128 v[16:19], v100 offset:23552
	ds_read_b128 v[20:23], v100 offset:23808
	ds_read_b128 v[24:27], v100 offset:24064
	ds_read_b64 v[28:29], v101 offset:24320
	s_waitcnt lgkmcnt(14)
	v_pk_mul_f32 v[80:81], v[44:45], v[0:1] op_sel:[0,0] op_sel_hi:[0,1]
	v_pk_mul_f32 v[82:83], v[44:45], v[2:3] op_sel:[1,0] op_sel_hi:[1,1]
	v_pk_fma_f32 v[80:81], v[46:47], v[4:5], v[80:81] op_sel:[0,0,0] op_sel_hi:[0,1,1]
	v_pk_fma_f32 v[82:83], v[46:47], v[6:7], v[82:83] op_sel:[1,0,0] op_sel_hi:[1,1,1]
	v_pk_add_f32 v[84:85], v[84:85], v[86:87]
	v_pk_add_f32 v[80:81], v[80:81], v[82:83]
	v_pk_mul_f32 v[0:1], v[36:37], v[0:1] op_sel:[0,0] op_sel_hi:[0,1]
	v_pk_mul_f32 v[2:3], v[36:37], v[2:3] op_sel:[1,0] op_sel_hi:[1,1]
	v_add_f32_dpp v80, v80, v80 quad_perm:[1,0,3,2] row_mask:0xf bank_mask:0xf
	v_add_f32_dpp v81, v81, v81 quad_perm:[1,0,3,2] row_mask:0xf bank_mask:0xf
	v_pk_mul_f32 v[4:5], v[38:39], v[4:5] op_sel:[0,0] op_sel_hi:[0,1]
	v_add_f32_dpp v80, v80, v80 quad_perm:[2,3,0,1] row_mask:0xf bank_mask:0xf
	v_add_f32_dpp v81, v81, v81 quad_perm:[2,3,0,1] row_mask:0xf bank_mask:0xf
	v_pk_mul_f32 v[6:7], v[38:39], v[6:7] op_sel:[1,0] op_sel_hi:[1,1]
	v_add_f32_dpp v80, v80, v80 row_half_mirror row_mask:0xf bank_mask:0xf
	v_add_f32_dpp v81, v81, v81 row_half_mirror row_mask:0xf bank_mask:0xf
	ds_write_b64 v102, v[84:85] offset:24576
	v_add_f32_dpp v80, v80, v80 row_mirror row_mask:0xf bank_mask:0xf
	v_add_f32_dpp v81, v81, v81 row_mirror row_mask:0xf bank_mask:0xf
	v_pk_fma_f32 v[0:1], v[80:81], v[48:49], v[0:1] op_sel:[0,0,0] op_sel_hi:[1,0,1] neg_lo:[1,0,0] neg_hi:[1,0,0]
	v_pk_fma_f32 v[2:3], v[80:81], v[48:49], v[2:3] op_sel:[0,1,0] op_sel_hi:[1,1,1] neg_lo:[1,0,0] neg_hi:[1,0,0]
	v_pk_fma_f32 v[4:5], v[80:81], v[50:51], v[4:5] op_sel:[0,0,0] op_sel_hi:[1,0,1] neg_lo:[1,0,0] neg_hi:[1,0,0]
	v_pk_fma_f32 v[6:7], v[80:81], v[50:51], v[6:7] op_sel:[0,1,0] op_sel_hi:[1,1,1] neg_lo:[1,0,0] neg_hi:[1,0,0]
	v_pk_fma_f32 v[0:1], v[52:53], v[40:41], v[0:1] op_sel:[0,0,0] op_sel_hi:[1,0,1]
	v_pk_fma_f32 v[2:3], v[52:53], v[40:41], v[2:3] op_sel:[0,1,0] op_sel_hi:[1,1,1]
	v_pk_fma_f32 v[4:5], v[52:53], v[42:43], v[4:5] op_sel:[0,0,0] op_sel_hi:[1,0,1]
	v_pk_fma_f32 v[6:7], v[52:53], v[42:43], v[6:7] op_sel:[0,1,0] op_sel_hi:[1,1,1]
	v_pk_mul_f32 v[88:89], v[32:33], v[0:1] op_sel:[0,0] op_sel_hi:[0,1]
	v_pk_mul_f32 v[90:91], v[32:33], v[2:3] op_sel:[1,0] op_sel_hi:[1,1]
	v_pk_fma_f32 v[88:89], v[34:35], v[4:5], v[88:89] op_sel:[0,0,0] op_sel_hi:[0,1,1]
	v_pk_fma_f32 v[90:91], v[34:35], v[6:7], v[90:91] op_sel:[1,0,0] op_sel_hi:[1,1,1]
	s_waitcnt lgkmcnt(8)
	v_pk_mul_f32 v[80:81], v[68:69], v[0:1] op_sel:[0,0] op_sel_hi:[0,1]
	v_pk_mul_f32 v[82:83], v[68:69], v[2:3] op_sel:[1,0] op_sel_hi:[1,1]
	v_pk_fma_f32 v[80:81], v[70:71], v[4:5], v[80:81] op_sel:[0,0,0] op_sel_hi:[0,1,1]
	v_pk_fma_f32 v[82:83], v[70:71], v[6:7], v[82:83] op_sel:[1,0,0] op_sel_hi:[1,1,1]
	v_pk_add_f32 v[88:89], v[88:89], v[90:91]
	v_pk_add_f32 v[80:81], v[80:81], v[82:83]
	v_pk_mul_f32 v[0:1], v[60:61], v[0:1] op_sel:[0,0] op_sel_hi:[0,1]
	v_pk_mul_f32 v[2:3], v[60:61], v[2:3] op_sel:[1,0] op_sel_hi:[1,1]
	v_add_f32_dpp v80, v80, v80 quad_perm:[1,0,3,2] row_mask:0xf bank_mask:0xf
	v_add_f32_dpp v81, v81, v81 quad_perm:[1,0,3,2] row_mask:0xf bank_mask:0xf
	v_pk_mul_f32 v[4:5], v[62:63], v[4:5] op_sel:[0,0] op_sel_hi:[0,1]
	v_add_f32_dpp v80, v80, v80 quad_perm:[2,3,0,1] row_mask:0xf bank_mask:0xf
	v_add_f32_dpp v81, v81, v81 quad_perm:[2,3,0,1] row_mask:0xf bank_mask:0xf
	v_pk_mul_f32 v[6:7], v[62:63], v[6:7] op_sel:[1,0] op_sel_hi:[1,1]
	v_add_f32_dpp v80, v80, v80 row_half_mirror row_mask:0xf bank_mask:0xf
	v_add_f32_dpp v81, v81, v81 row_half_mirror row_mask:0xf bank_mask:0xf
	ds_write_b64 v102, v[88:89] offset:26624
	v_add_f32_dpp v80, v80, v80 row_mirror row_mask:0xf bank_mask:0xf
	v_add_f32_dpp v81, v81, v81 row_mirror row_mask:0xf bank_mask:0xf
	v_pk_fma_f32 v[0:1], v[80:81], v[72:73], v[0:1] op_sel:[0,0,0] op_sel_hi:[1,0,1] neg_lo:[1,0,0] neg_hi:[1,0,0]
	v_pk_fma_f32 v[2:3], v[80:81], v[72:73], v[2:3] op_sel:[0,1,0] op_sel_hi:[1,1,1] neg_lo:[1,0,0] neg_hi:[1,0,0]
	v_pk_fma_f32 v[4:5], v[80:81], v[74:75], v[4:5] op_sel:[0,0,0] op_sel_hi:[1,0,1] neg_lo:[1,0,0] neg_hi:[1,0,0]
	v_pk_fma_f32 v[6:7], v[80:81], v[74:75], v[6:7] op_sel:[0,1,0] op_sel_hi:[1,1,1] neg_lo:[1,0,0] neg_hi:[1,0,0]
	v_pk_fma_f32 v[0:1], v[76:77], v[64:65], v[0:1] op_sel:[0,0,0] op_sel_hi:[1,0,1]
	v_pk_fma_f32 v[2:3], v[76:77], v[64:65], v[2:3] op_sel:[0,1,0] op_sel_hi:[1,1,1]
	v_pk_fma_f32 v[4:5], v[76:77], v[66:67], v[4:5] op_sel:[0,0,0] op_sel_hi:[1,0,1]
	v_pk_fma_f32 v[6:7], v[76:77], v[66:67], v[6:7] op_sel:[0,1,0] op_sel_hi:[1,1,1]
	v_pk_mul_f32 v[84:85], v[56:57], v[0:1] op_sel:[0,0] op_sel_hi:[0,1]
	v_pk_mul_f32 v[86:87], v[56:57], v[2:3] op_sel:[1,0] op_sel_hi:[1,1]
	v_pk_fma_f32 v[84:85], v[58:59], v[4:5], v[84:85] op_sel:[0,0,0] op_sel_hi:[0,1,1]
	v_pk_fma_f32 v[86:87], v[58:59], v[6:7], v[86:87] op_sel:[1,0,0] op_sel_hi:[1,1,1]
	s_waitcnt lgkmcnt(2)
	v_pk_mul_f32 v[80:81], v[20:21], v[0:1] op_sel:[0,0] op_sel_hi:[0,1]
	v_pk_mul_f32 v[82:83], v[20:21], v[2:3] op_sel:[1,0] op_sel_hi:[1,1]
	v_pk_fma_f32 v[80:81], v[22:23], v[4:5], v[80:81] op_sel:[0,0,0] op_sel_hi:[0,1,1]
	v_pk_fma_f32 v[82:83], v[22:23], v[6:7], v[82:83] op_sel:[1,0,0] op_sel_hi:[1,1,1]
	v_pk_add_f32 v[84:85], v[84:85], v[86:87]
	v_pk_add_f32 v[80:81], v[80:81], v[82:83]
	v_pk_mul_f32 v[0:1], v[12:13], v[0:1] op_sel:[0,0] op_sel_hi:[0,1]
	v_pk_mul_f32 v[2:3], v[12:13], v[2:3] op_sel:[1,0] op_sel_hi:[1,1]
	v_add_f32_dpp v80, v80, v80 quad_perm:[1,0,3,2] row_mask:0xf bank_mask:0xf
	v_add_f32_dpp v81, v81, v81 quad_perm:[1,0,3,2] row_mask:0xf bank_mask:0xf
	v_pk_mul_f32 v[4:5], v[14:15], v[4:5] op_sel:[0,0] op_sel_hi:[0,1]
	v_add_f32_dpp v80, v80, v80 quad_perm:[2,3,0,1] row_mask:0xf bank_mask:0xf
	v_add_f32_dpp v81, v81, v81 quad_perm:[2,3,0,1] row_mask:0xf bank_mask:0xf
	v_pk_mul_f32 v[6:7], v[14:15], v[6:7] op_sel:[1,0] op_sel_hi:[1,1]
	v_add_f32_dpp v80, v80, v80 row_half_mirror row_mask:0xf bank_mask:0xf
	v_add_f32_dpp v81, v81, v81 row_half_mirror row_mask:0xf bank_mask:0xf
	ds_write_b64 v102, v[84:85] offset:28672
	v_add_f32_dpp v80, v80, v80 row_mirror row_mask:0xf bank_mask:0xf
	v_add_f32_dpp v81, v81, v81 row_mirror row_mask:0xf bank_mask:0xf
	v_pk_fma_f32 v[0:1], v[80:81], v[24:25], v[0:1] op_sel:[0,0,0] op_sel_hi:[1,0,1] neg_lo:[1,0,0] neg_hi:[1,0,0]
	v_pk_fma_f32 v[2:3], v[80:81], v[24:25], v[2:3] op_sel:[0,1,0] op_sel_hi:[1,1,1] neg_lo:[1,0,0] neg_hi:[1,0,0]
	v_pk_fma_f32 v[4:5], v[80:81], v[26:27], v[4:5] op_sel:[0,0,0] op_sel_hi:[1,0,1] neg_lo:[1,0,0] neg_hi:[1,0,0]
	v_pk_fma_f32 v[6:7], v[80:81], v[26:27], v[6:7] op_sel:[0,1,0] op_sel_hi:[1,1,1] neg_lo:[1,0,0] neg_hi:[1,0,0]
	v_pk_fma_f32 v[0:1], v[28:29], v[16:17], v[0:1] op_sel:[0,0,0] op_sel_hi:[1,0,1]
	v_pk_fma_f32 v[2:3], v[28:29], v[16:17], v[2:3] op_sel:[0,1,0] op_sel_hi:[1,1,1]
	v_pk_fma_f32 v[4:5], v[28:29], v[18:19], v[4:5] op_sel:[0,0,0] op_sel_hi:[1,0,1]
	v_pk_fma_f32 v[6:7], v[28:29], v[18:19], v[6:7] op_sel:[0,1,0] op_sel_hi:[1,1,1]
	v_pk_mul_f32 v[88:89], v[8:9], v[0:1] op_sel:[0,0] op_sel_hi:[0,1]
	v_pk_mul_f32 v[90:91], v[8:9], v[2:3] op_sel:[1,0] op_sel_hi:[1,1]
	v_pk_fma_f32 v[88:89], v[10:11], v[4:5], v[88:89] op_sel:[0,0,0] op_sel_hi:[0,1,1]
	v_pk_fma_f32 v[90:91], v[10:11], v[6:7], v[90:91] op_sel:[1,0,0] op_sel_hi:[1,1,1]
	s_nop 0
	v_pk_add_f32 v[88:89], v[88:89], v[90:91]
	s_nop 0
	ds_write_b64 v102, v[88:89] offset:30720
	s_waitcnt lgkmcnt(0)
	s_barrier
	ds_read_b128 v[8:11], v100 offset:24576
	ds_read_b128 v[12:15], v100 offset:24832
	ds_read_b128 v[16:19], v100 offset:25088
	ds_read_b128 v[20:23], v100 offset:25344
	ds_read_b128 v[24:27], v100 offset:25600
	ds_read_b64 v[28:29], v101 offset:25856
	ds_read_b128 v[32:35], v100 offset:26112
	ds_read_b128 v[36:39], v100 offset:26368
	ds_read_b128 v[40:43], v100 offset:26624
	ds_read_b128 v[44:47], v100 offset:26880
	ds_read_b128 v[48:51], v100 offset:27136
	ds_read_b64 v[52:53], v101 offset:27392
	ds_read_b128 v[56:59], v100 offset:27648
	ds_read_b128 v[60:63], v100 offset:27904
	ds_read_b128 v[64:67], v100 offset:28160
	ds_read_b128 v[68:71], v100 offset:28416
	ds_read_b128 v[72:75], v100 offset:28672
	ds_read_b64 v[76:77], v101 offset:28928
	s_waitcnt lgkmcnt(12)
	v_pk_mul_f32 v[80:81], v[20:21], v[0:1] op_sel:[0,0] op_sel_hi:[0,1]
	v_pk_mul_f32 v[82:83], v[20:21], v[2:3] op_sel:[1,0] op_sel_hi:[1,1]
	v_pk_fma_f32 v[80:81], v[22:23], v[4:5], v[80:81] op_sel:[0,0,0] op_sel_hi:[0,1,1]
	v_pk_fma_f32 v[82:83], v[22:23], v[6:7], v[82:83] op_sel:[1,0,0] op_sel_hi:[1,1,1]
	s_nop 0
	v_pk_add_f32 v[80:81], v[80:81], v[82:83]
	v_pk_mul_f32 v[0:1], v[12:13], v[0:1] op_sel:[0,0] op_sel_hi:[0,1]
	v_pk_mul_f32 v[2:3], v[12:13], v[2:3] op_sel:[1,0] op_sel_hi:[1,1]
	v_add_f32_dpp v80, v80, v80 quad_perm:[1,0,3,2] row_mask:0xf bank_mask:0xf
	v_add_f32_dpp v81, v81, v81 quad_perm:[1,0,3,2] row_mask:0xf bank_mask:0xf
	v_pk_mul_f32 v[4:5], v[14:15], v[4:5] op_sel:[0,0] op_sel_hi:[0,1]
	v_add_f32_dpp v80, v80, v80 quad_perm:[2,3,0,1] row_mask:0xf bank_mask:0xf
	v_add_f32_dpp v81, v81, v81 quad_perm:[2,3,0,1] row_mask:0xf bank_mask:0xf
	v_pk_mul_f32 v[6:7], v[14:15], v[6:7] op_sel:[1,0] op_sel_hi:[1,1]
	v_add_f32_dpp v80, v80, v80 row_half_mirror row_mask:0xf bank_mask:0xf
	v_add_f32_dpp v81, v81, v81 row_half_mirror row_mask:0xf bank_mask:0xf
	s_nop 0
	v_add_f32_dpp v80, v80, v80 row_mirror row_mask:0xf bank_mask:0xf
	v_add_f32_dpp v81, v81, v81 row_mirror row_mask:0xf bank_mask:0xf
	v_pk_fma_f32 v[0:1], v[80:81], v[24:25], v[0:1] op_sel:[0,0,0] op_sel_hi:[1,0,1] neg_lo:[1,0,0] neg_hi:[1,0,0]
	v_pk_fma_f32 v[2:3], v[80:81], v[24:25], v[2:3] op_sel:[0,1,0] op_sel_hi:[1,1,1] neg_lo:[1,0,0] neg_hi:[1,0,0]
	v_pk_fma_f32 v[4:5], v[80:81], v[26:27], v[4:5] op_sel:[0,0,0] op_sel_hi:[1,0,1] neg_lo:[1,0,0] neg_hi:[1,0,0]
	v_pk_fma_f32 v[6:7], v[80:81], v[26:27], v[6:7] op_sel:[0,1,0] op_sel_hi:[1,1,1] neg_lo:[1,0,0] neg_hi:[1,0,0]
	v_pk_fma_f32 v[0:1], v[28:29], v[16:17], v[0:1] op_sel:[0,0,0] op_sel_hi:[1,0,1]
	v_pk_fma_f32 v[2:3], v[28:29], v[16:17], v[2:3] op_sel:[0,1,0] op_sel_hi:[1,1,1]
	v_pk_fma_f32 v[4:5], v[28:29], v[18:19], v[4:5] op_sel:[0,0,0] op_sel_hi:[1,0,1]
	v_pk_fma_f32 v[6:7], v[28:29], v[18:19], v[6:7] op_sel:[0,1,0] op_sel_hi:[1,1,1]
	v_pk_mul_f32 v[84:85], v[8:9], v[0:1] op_sel:[0,0] op_sel_hi:[0,1]
	v_pk_mul_f32 v[86:87], v[8:9], v[2:3] op_sel:[1,0] op_sel_hi:[1,1]
	v_pk_fma_f32 v[84:85], v[10:11], v[4:5], v[84:85] op_sel:[0,0,0] op_sel_hi:[0,1,1]
	v_pk_fma_f32 v[86:87], v[10:11], v[6:7], v[86:87] op_sel:[1,0,0] op_sel_hi:[1,1,1]
	ds_read_b128 v[8:11], v100 offset:29184
	ds_read_b128 v[12:15], v100 offset:29440
	ds_read_b128 v[16:19], v100 offset:29696
	ds_read_b128 v[20:23], v100 offset:29952
	ds_read_b128 v[24:27], v100 offset:30208
	ds_read_b64 v[28:29], v101 offset:30464
	s_waitcnt lgkmcnt(12)
	v_pk_mul_f32 v[80:81], v[44:45], v[0:1] op_sel:[0,0] op_sel_hi:[0,1]
	v_pk_mul_f32 v[82:83], v[44:45], v[2:3] op_sel:[1,0] op_sel_hi:[1,1]
	v_pk_fma_f32 v[80:81], v[46:47], v[4:5], v[80:81] op_sel:[0,0,0] op_sel_hi:[0,1,1]
	v_pk_fma_f32 v[82:83], v[46:47], v[6:7], v[82:83] op_sel:[1,0,0] op_sel_hi:[1,1,1]
	v_pk_add_f32 v[84:85], v[84:85], v[86:87]
	v_pk_add_f32 v[80:81], v[80:81], v[82:83]
	v_pk_mul_f32 v[0:1], v[36:37], v[0:1] op_sel:[0,0] op_sel_hi:[0,1]
	v_pk_mul_f32 v[2:3], v[36:37], v[2:3] op_sel:[1,0] op_sel_hi:[1,1]
	v_add_f32_dpp v80, v80, v80 quad_perm:[1,0,3,2] row_mask:0xf bank_mask:0xf
	v_add_f32_dpp v81, v81, v81 quad_perm:[1,0,3,2] row_mask:0xf bank_mask:0xf
	v_pk_mul_f32 v[4:5], v[38:39], v[4:5] op_sel:[0,0] op_sel_hi:[0,1]
	v_add_f32_dpp v80, v80, v80 quad_perm:[2,3,0,1] row_mask:0xf bank_mask:0xf
	v_add_f32_dpp v81, v81, v81 quad_perm:[2,3,0,1] row_mask:0xf bank_mask:0xf
	v_pk_mul_f32 v[6:7], v[38:39], v[6:7] op_sel:[1,0] op_sel_hi:[1,1]
	v_add_f32_dpp v80, v80, v80 row_half_mirror row_mask:0xf bank_mask:0xf
	v_add_f32_dpp v81, v81, v81 row_half_mirror row_mask:0xf bank_mask:0xf
	ds_write_b64 v102, v[84:85] offset:32768
	v_add_f32_dpp v80, v80, v80 row_mirror row_mask:0xf bank_mask:0xf
	v_add_f32_dpp v81, v81, v81 row_mirror row_mask:0xf bank_mask:0xf
	v_pk_fma_f32 v[0:1], v[80:81], v[48:49], v[0:1] op_sel:[0,0,0] op_sel_hi:[1,0,1] neg_lo:[1,0,0] neg_hi:[1,0,0]
	v_pk_fma_f32 v[2:3], v[80:81], v[48:49], v[2:3] op_sel:[0,1,0] op_sel_hi:[1,1,1] neg_lo:[1,0,0] neg_hi:[1,0,0]
	v_pk_fma_f32 v[4:5], v[80:81], v[50:51], v[4:5] op_sel:[0,0,0] op_sel_hi:[1,0,1] neg_lo:[1,0,0] neg_hi:[1,0,0]
	v_pk_fma_f32 v[6:7], v[80:81], v[50:51], v[6:7] op_sel:[0,1,0] op_sel_hi:[1,1,1] neg_lo:[1,0,0] neg_hi:[1,0,0]
	v_pk_fma_f32 v[0:1], v[52:53], v[40:41], v[0:1] op_sel:[0,0,0] op_sel_hi:[1,0,1]
	v_pk_fma_f32 v[2:3], v[52:53], v[40:41], v[2:3] op_sel:[0,1,0] op_sel_hi:[1,1,1]
	v_pk_fma_f32 v[4:5], v[52:53], v[42:43], v[4:5] op_sel:[0,0,0] op_sel_hi:[1,0,1]
	v_pk_fma_f32 v[6:7], v[52:53], v[42:43], v[6:7] op_sel:[0,1,0] op_sel_hi:[1,1,1]
	v_pk_mul_f32 v[88:89], v[32:33], v[0:1] op_sel:[0,0] op_sel_hi:[0,1]
	v_pk_mul_f32 v[90:91], v[32:33], v[2:3] op_sel:[1,0] op_sel_hi:[1,1]
	v_pk_fma_f32 v[88:89], v[34:35], v[4:5], v[88:89] op_sel:[0,0,0] op_sel_hi:[0,1,1]
	v_pk_fma_f32 v[90:91], v[34:35], v[6:7], v[90:91] op_sel:[1,0,0] op_sel_hi:[1,1,1]
	ds_read_b128 v[32:35], v100 offset:30720
	ds_read_b128 v[36:39], v100 offset:30976
	ds_read_b128 v[40:43], v100 offset:31232
	ds_read_b128 v[44:47], v100 offset:31488
	ds_read_b128 v[48:51], v100 offset:31744
	ds_read_b64 v[52:53], v101 offset:32000
	s_waitcnt lgkmcnt(13)
	v_pk_mul_f32 v[80:81], v[68:69], v[0:1] op_sel:[0,0] op_sel_hi:[0,1]
	v_pk_mul_f32 v[82:83], v[68:69], v[2:3] op_sel:[1,0] op_sel_hi:[1,1]
	v_pk_fma_f32 v[80:81], v[70:71], v[4:5], v[80:81] op_sel:[0,0,0] op_sel_hi:[0,1,1]
	v_pk_fma_f32 v[82:83], v[70:71], v[6:7], v[82:83] op_sel:[1,0,0] op_sel_hi:[1,1,1]
	v_pk_add_f32 v[88:89], v[88:89], v[90:91]
	v_pk_add_f32 v[80:81], v[80:81], v[82:83]
	v_pk_mul_f32 v[0:1], v[60:61], v[0:1] op_sel:[0,0] op_sel_hi:[0,1]
	v_pk_mul_f32 v[2:3], v[60:61], v[2:3] op_sel:[1,0] op_sel_hi:[1,1]
	v_add_f32_dpp v80, v80, v80 quad_perm:[1,0,3,2] row_mask:0xf bank_mask:0xf
	v_add_f32_dpp v81, v81, v81 quad_perm:[1,0,3,2] row_mask:0xf bank_mask:0xf
	v_pk_mul_f32 v[4:5], v[62:63], v[4:5] op_sel:[0,0] op_sel_hi:[0,1]
	v_add_f32_dpp v80, v80, v80 quad_perm:[2,3,0,1] row_mask:0xf bank_mask:0xf
	v_add_f32_dpp v81, v81, v81 quad_perm:[2,3,0,1] row_mask:0xf bank_mask:0xf
	v_pk_mul_f32 v[6:7], v[62:63], v[6:7] op_sel:[1,0] op_sel_hi:[1,1]
	v_add_f32_dpp v80, v80, v80 row_half_mirror row_mask:0xf bank_mask:0xf
	v_add_f32_dpp v81, v81, v81 row_half_mirror row_mask:0xf bank_mask:0xf
	ds_write_b64 v102, v[88:89] offset:34816
	v_add_f32_dpp v80, v80, v80 row_mirror row_mask:0xf bank_mask:0xf
	v_add_f32_dpp v81, v81, v81 row_mirror row_mask:0xf bank_mask:0xf
	v_pk_fma_f32 v[0:1], v[80:81], v[72:73], v[0:1] op_sel:[0,0,0] op_sel_hi:[1,0,1] neg_lo:[1,0,0] neg_hi:[1,0,0]
	v_pk_fma_f32 v[2:3], v[80:81], v[72:73], v[2:3] op_sel:[0,1,0] op_sel_hi:[1,1,1] neg_lo:[1,0,0] neg_hi:[1,0,0]
	v_pk_fma_f32 v[4:5], v[80:81], v[74:75], v[4:5] op_sel:[0,0,0] op_sel_hi:[1,0,1] neg_lo:[1,0,0] neg_hi:[1,0,0]
	v_pk_fma_f32 v[6:7], v[80:81], v[74:75], v[6:7] op_sel:[0,1,0] op_sel_hi:[1,1,1] neg_lo:[1,0,0] neg_hi:[1,0,0]
	v_pk_fma_f32 v[0:1], v[76:77], v[64:65], v[0:1] op_sel:[0,0,0] op_sel_hi:[1,0,1]
	v_pk_fma_f32 v[2:3], v[76:77], v[64:65], v[2:3] op_sel:[0,1,0] op_sel_hi:[1,1,1]
	v_pk_fma_f32 v[4:5], v[76:77], v[66:67], v[4:5] op_sel:[0,0,0] op_sel_hi:[1,0,1]
	v_pk_fma_f32 v[6:7], v[76:77], v[66:67], v[6:7] op_sel:[0,1,0] op_sel_hi:[1,1,1]
	v_pk_mul_f32 v[84:85], v[56:57], v[0:1] op_sel:[0,0] op_sel_hi:[0,1]
	v_pk_mul_f32 v[86:87], v[56:57], v[2:3] op_sel:[1,0] op_sel_hi:[1,1]
	v_pk_fma_f32 v[84:85], v[58:59], v[4:5], v[84:85] op_sel:[0,0,0] op_sel_hi:[0,1,1]
	v_pk_fma_f32 v[86:87], v[58:59], v[6:7], v[86:87] op_sel:[1,0,0] op_sel_hi:[1,1,1]
	ds_read_b128 v[56:59], v100 offset:32256
	ds_read_b128 v[60:63], v100 offset:32512
	ds_read_b128 v[64:67], v100 offset:32768
	ds_read_b128 v[68:71], v100 offset:33024
	ds_read_b128 v[72:75], v100 offset:33280
	ds_read_b64 v[76:77], v101 offset:33536
	s_waitcnt lgkmcnt(14)
	v_pk_mul_f32 v[80:81], v[20:21], v[0:1] op_sel:[0,0] op_sel_hi:[0,1]
	v_pk_mul_f32 v[82:83], v[20:21], v[2:3] op_sel:[1,0] op_sel_hi:[1,1]
	v_pk_fma_f32 v[80:81], v[22:23], v[4:5], v[80:81] op_sel:[0,0,0] op_sel_hi:[0,1,1]
	v_pk_fma_f32 v[82:83], v[22:23], v[6:7], v[82:83] op_sel:[1,0,0] op_sel_hi:[1,1,1]
	v_pk_add_f32 v[84:85], v[84:85], v[86:87]
	v_pk_add_f32 v[80:81], v[80:81], v[82:83]
	v_pk_mul_f32 v[0:1], v[12:13], v[0:1] op_sel:[0,0] op_sel_hi:[0,1]
	v_pk_mul_f32 v[2:3], v[12:13], v[2:3] op_sel:[1,0] op_sel_hi:[1,1]
	v_add_f32_dpp v80, v80, v80 quad_perm:[1,0,3,2] row_mask:0xf bank_mask:0xf
	v_add_f32_dpp v81, v81, v81 quad_perm:[1,0,3,2] row_mask:0xf bank_mask:0xf
	v_pk_mul_f32 v[4:5], v[14:15], v[4:5] op_sel:[0,0] op_sel_hi:[0,1]
	v_add_f32_dpp v80, v80, v80 quad_perm:[2,3,0,1] row_mask:0xf bank_mask:0xf
	v_add_f32_dpp v81, v81, v81 quad_perm:[2,3,0,1] row_mask:0xf bank_mask:0xf
	v_pk_mul_f32 v[6:7], v[14:15], v[6:7] op_sel:[1,0] op_sel_hi:[1,1]
	v_add_f32_dpp v80, v80, v80 row_half_mirror row_mask:0xf bank_mask:0xf
	v_add_f32_dpp v81, v81, v81 row_half_mirror row_mask:0xf bank_mask:0xf
	ds_write_b64 v102, v[84:85] offset:36864
	v_add_f32_dpp v80, v80, v80 row_mirror row_mask:0xf bank_mask:0xf
	v_add_f32_dpp v81, v81, v81 row_mirror row_mask:0xf bank_mask:0xf
	v_pk_fma_f32 v[0:1], v[80:81], v[24:25], v[0:1] op_sel:[0,0,0] op_sel_hi:[1,0,1] neg_lo:[1,0,0] neg_hi:[1,0,0]
	v_pk_fma_f32 v[2:3], v[80:81], v[24:25], v[2:3] op_sel:[0,1,0] op_sel_hi:[1,1,1] neg_lo:[1,0,0] neg_hi:[1,0,0]
	v_pk_fma_f32 v[4:5], v[80:81], v[26:27], v[4:5] op_sel:[0,0,0] op_sel_hi:[1,0,1] neg_lo:[1,0,0] neg_hi:[1,0,0]
	v_pk_fma_f32 v[6:7], v[80:81], v[26:27], v[6:7] op_sel:[0,1,0] op_sel_hi:[1,1,1] neg_lo:[1,0,0] neg_hi:[1,0,0]
	v_pk_fma_f32 v[0:1], v[28:29], v[16:17], v[0:1] op_sel:[0,0,0] op_sel_hi:[1,0,1]
	v_pk_fma_f32 v[2:3], v[28:29], v[16:17], v[2:3] op_sel:[0,1,0] op_sel_hi:[1,1,1]
	v_pk_fma_f32 v[4:5], v[28:29], v[18:19], v[4:5] op_sel:[0,0,0] op_sel_hi:[1,0,1]
	v_pk_fma_f32 v[6:7], v[28:29], v[18:19], v[6:7] op_sel:[0,1,0] op_sel_hi:[1,1,1]
	v_pk_mul_f32 v[88:89], v[8:9], v[0:1] op_sel:[0,0] op_sel_hi:[0,1]
	v_pk_mul_f32 v[90:91], v[8:9], v[2:3] op_sel:[1,0] op_sel_hi:[1,1]
	v_pk_fma_f32 v[88:89], v[10:11], v[4:5], v[88:89] op_sel:[0,0,0] op_sel_hi:[0,1,1]
	v_pk_fma_f32 v[90:91], v[10:11], v[6:7], v[90:91] op_sel:[1,0,0] op_sel_hi:[1,1,1]
	ds_read_b128 v[8:11], v100 offset:33792
	ds_read_b128 v[12:15], v100 offset:34048
	ds_read_b128 v[16:19], v100 offset:34304
	ds_read_b128 v[20:23], v100 offset:34560
	ds_read_b128 v[24:27], v100 offset:34816
	ds_read_b64 v[28:29], v101 offset:35072
	s_waitcnt lgkmcnt(14)
	v_pk_mul_f32 v[80:81], v[44:45], v[0:1] op_sel:[0,0] op_sel_hi:[0,1]
	v_pk_mul_f32 v[82:83], v[44:45], v[2:3] op_sel:[1,0] op_sel_hi:[1,1]
	v_pk_fma_f32 v[80:81], v[46:47], v[4:5], v[80:81] op_sel:[0,0,0] op_sel_hi:[0,1,1]
	v_pk_fma_f32 v[82:83], v[46:47], v[6:7], v[82:83] op_sel:[1,0,0] op_sel_hi:[1,1,1]
	v_pk_add_f32 v[88:89], v[88:89], v[90:91]
	v_pk_add_f32 v[80:81], v[80:81], v[82:83]
	v_pk_mul_f32 v[0:1], v[36:37], v[0:1] op_sel:[0,0] op_sel_hi:[0,1]
	v_pk_mul_f32 v[2:3], v[36:37], v[2:3] op_sel:[1,0] op_sel_hi:[1,1]
	v_add_f32_dpp v80, v80, v80 quad_perm:[1,0,3,2] row_mask:0xf bank_mask:0xf
	v_add_f32_dpp v81, v81, v81 quad_perm:[1,0,3,2] row_mask:0xf bank_mask:0xf
	v_pk_mul_f32 v[4:5], v[38:39], v[4:5] op_sel:[0,0] op_sel_hi:[0,1]
	v_add_f32_dpp v80, v80, v80 quad_perm:[2,3,0,1] row_mask:0xf bank_mask:0xf
	v_add_f32_dpp v81, v81, v81 quad_perm:[2,3,0,1] row_mask:0xf bank_mask:0xf
	v_pk_mul_f32 v[6:7], v[38:39], v[6:7] op_sel:[1,0] op_sel_hi:[1,1]
	v_add_f32_dpp v80, v80, v80 row_half_mirror row_mask:0xf bank_mask:0xf
	v_add_f32_dpp v81, v81, v81 row_half_mirror row_mask:0xf bank_mask:0xf
	ds_write_b64 v102, v[88:89] offset:38912
	v_add_f32_dpp v80, v80, v80 row_mirror row_mask:0xf bank_mask:0xf
	v_add_f32_dpp v81, v81, v81 row_mirror row_mask:0xf bank_mask:0xf
	v_pk_fma_f32 v[0:1], v[80:81], v[48:49], v[0:1] op_sel:[0,0,0] op_sel_hi:[1,0,1] neg_lo:[1,0,0] neg_hi:[1,0,0]
	v_pk_fma_f32 v[2:3], v[80:81], v[48:49], v[2:3] op_sel:[0,1,0] op_sel_hi:[1,1,1] neg_lo:[1,0,0] neg_hi:[1,0,0]
	v_pk_fma_f32 v[4:5], v[80:81], v[50:51], v[4:5] op_sel:[0,0,0] op_sel_hi:[1,0,1] neg_lo:[1,0,0] neg_hi:[1,0,0]
	v_pk_fma_f32 v[6:7], v[80:81], v[50:51], v[6:7] op_sel:[0,1,0] op_sel_hi:[1,1,1] neg_lo:[1,0,0] neg_hi:[1,0,0]
	v_pk_fma_f32 v[0:1], v[52:53], v[40:41], v[0:1] op_sel:[0,0,0] op_sel_hi:[1,0,1]
	v_pk_fma_f32 v[2:3], v[52:53], v[40:41], v[2:3] op_sel:[0,1,0] op_sel_hi:[1,1,1]
	v_pk_fma_f32 v[4:5], v[52:53], v[42:43], v[4:5] op_sel:[0,0,0] op_sel_hi:[1,0,1]
	v_pk_fma_f32 v[6:7], v[52:53], v[42:43], v[6:7] op_sel:[0,1,0] op_sel_hi:[1,1,1]
	v_pk_mul_f32 v[84:85], v[32:33], v[0:1] op_sel:[0,0] op_sel_hi:[0,1]
	v_pk_mul_f32 v[86:87], v[32:33], v[2:3] op_sel:[1,0] op_sel_hi:[1,1]
	v_pk_fma_f32 v[84:85], v[34:35], v[4:5], v[84:85] op_sel:[0,0,0] op_sel_hi:[0,1,1]
	v_pk_fma_f32 v[86:87], v[34:35], v[6:7], v[86:87] op_sel:[1,0,0] op_sel_hi:[1,1,1]
	ds_read_b128 v[32:35], v100 offset:35328
	ds_read_b128 v[36:39], v100 offset:35584
	ds_read_b128 v[40:43], v100 offset:35840
	ds_read_b128 v[44:47], v100 offset:36096
	ds_read_b128 v[48:51], v100 offset:36352
	ds_read_b64 v[52:53], v101 offset:36608
	s_waitcnt lgkmcnt(14)
	v_pk_mul_f32 v[80:81], v[68:69], v[0:1] op_sel:[0,0] op_sel_hi:[0,1]
	v_pk_mul_f32 v[82:83], v[68:69], v[2:3] op_sel:[1,0] op_sel_hi:[1,1]
	v_pk_fma_f32 v[80:81], v[70:71], v[4:5], v[80:81] op_sel:[0,0,0] op_sel_hi:[0,1,1]
	v_pk_fma_f32 v[82:83], v[70:71], v[6:7], v[82:83] op_sel:[1,0,0] op_sel_hi:[1,1,1]
	v_pk_add_f32 v[84:85], v[84:85], v[86:87]
	v_pk_add_f32 v[80:81], v[80:81], v[82:83]
	v_pk_mul_f32 v[0:1], v[60:61], v[0:1] op_sel:[0,0] op_sel_hi:[0,1]
	v_pk_mul_f32 v[2:3], v[60:61], v[2:3] op_sel:[1,0] op_sel_hi:[1,1]
	v_add_f32_dpp v80, v80, v80 quad_perm:[1,0,3,2] row_mask:0xf bank_mask:0xf
	v_add_f32_dpp v81, v81, v81 quad_perm:[1,0,3,2] row_mask:0xf bank_mask:0xf
	v_pk_mul_f32 v[4:5], v[62:63], v[4:5] op_sel:[0,0] op_sel_hi:[0,1]
	v_add_f32_dpp v80, v80, v80 quad_perm:[2,3,0,1] row_mask:0xf bank_mask:0xf
	v_add_f32_dpp v81, v81, v81 quad_perm:[2,3,0,1] row_mask:0xf bank_mask:0xf
	v_pk_mul_f32 v[6:7], v[62:63], v[6:7] op_sel:[1,0] op_sel_hi:[1,1]
	v_add_f32_dpp v80, v80, v80 row_half_mirror row_mask:0xf bank_mask:0xf
	v_add_f32_dpp v81, v81, v81 row_half_mirror row_mask:0xf bank_mask:0xf
	ds_write_b64 v102, v[84:85] offset:40960
	v_add_f32_dpp v80, v80, v80 row_mirror row_mask:0xf bank_mask:0xf
	v_add_f32_dpp v81, v81, v81 row_mirror row_mask:0xf bank_mask:0xf
	v_pk_fma_f32 v[0:1], v[80:81], v[72:73], v[0:1] op_sel:[0,0,0] op_sel_hi:[1,0,1] neg_lo:[1,0,0] neg_hi:[1,0,0]
	v_pk_fma_f32 v[2:3], v[80:81], v[72:73], v[2:3] op_sel:[0,1,0] op_sel_hi:[1,1,1] neg_lo:[1,0,0] neg_hi:[1,0,0]
	v_pk_fma_f32 v[4:5], v[80:81], v[74:75], v[4:5] op_sel:[0,0,0] op_sel_hi:[1,0,1] neg_lo:[1,0,0] neg_hi:[1,0,0]
	v_pk_fma_f32 v[6:7], v[80:81], v[74:75], v[6:7] op_sel:[0,1,0] op_sel_hi:[1,1,1] neg_lo:[1,0,0] neg_hi:[1,0,0]
	v_pk_fma_f32 v[0:1], v[76:77], v[64:65], v[0:1] op_sel:[0,0,0] op_sel_hi:[1,0,1]
	v_pk_fma_f32 v[2:3], v[76:77], v[64:65], v[2:3] op_sel:[0,1,0] op_sel_hi:[1,1,1]
	v_pk_fma_f32 v[4:5], v[76:77], v[66:67], v[4:5] op_sel:[0,0,0] op_sel_hi:[1,0,1]
	v_pk_fma_f32 v[6:7], v[76:77], v[66:67], v[6:7] op_sel:[0,1,0] op_sel_hi:[1,1,1]
	v_pk_mul_f32 v[88:89], v[56:57], v[0:1] op_sel:[0,0] op_sel_hi:[0,1]
	v_pk_mul_f32 v[90:91], v[56:57], v[2:3] op_sel:[1,0] op_sel_hi:[1,1]
	v_pk_fma_f32 v[88:89], v[58:59], v[4:5], v[88:89] op_sel:[0,0,0] op_sel_hi:[0,1,1]
	v_pk_fma_f32 v[90:91], v[58:59], v[6:7], v[90:91] op_sel:[1,0,0] op_sel_hi:[1,1,1]
	ds_read_b128 v[56:59], v100 offset:36864
	ds_read_b128 v[60:63], v100 offset:37120
	ds_read_b128 v[64:67], v100 offset:37376
	ds_read_b128 v[68:71], v100 offset:37632
	ds_read_b128 v[72:75], v100 offset:37888
	ds_read_b64 v[76:77], v101 offset:38144
	s_waitcnt lgkmcnt(14)
	v_pk_mul_f32 v[80:81], v[20:21], v[0:1] op_sel:[0,0] op_sel_hi:[0,1]
	v_pk_mul_f32 v[82:83], v[20:21], v[2:3] op_sel:[1,0] op_sel_hi:[1,1]
	v_pk_fma_f32 v[80:81], v[22:23], v[4:5], v[80:81] op_sel:[0,0,0] op_sel_hi:[0,1,1]
	v_pk_fma_f32 v[82:83], v[22:23], v[6:7], v[82:83] op_sel:[1,0,0] op_sel_hi:[1,1,1]
	v_pk_add_f32 v[88:89], v[88:89], v[90:91]
	v_pk_add_f32 v[80:81], v[80:81], v[82:83]
	v_pk_mul_f32 v[0:1], v[12:13], v[0:1] op_sel:[0,0] op_sel_hi:[0,1]
	v_pk_mul_f32 v[2:3], v[12:13], v[2:3] op_sel:[1,0] op_sel_hi:[1,1]
	v_add_f32_dpp v80, v80, v80 quad_perm:[1,0,3,2] row_mask:0xf bank_mask:0xf
	v_add_f32_dpp v81, v81, v81 quad_perm:[1,0,3,2] row_mask:0xf bank_mask:0xf
	v_pk_mul_f32 v[4:5], v[14:15], v[4:5] op_sel:[0,0] op_sel_hi:[0,1]
	v_add_f32_dpp v80, v80, v80 quad_perm:[2,3,0,1] row_mask:0xf bank_mask:0xf
	v_add_f32_dpp v81, v81, v81 quad_perm:[2,3,0,1] row_mask:0xf bank_mask:0xf
	v_pk_mul_f32 v[6:7], v[14:15], v[6:7] op_sel:[1,0] op_sel_hi:[1,1]
	v_add_f32_dpp v80, v80, v80 row_half_mirror row_mask:0xf bank_mask:0xf
	v_add_f32_dpp v81, v81, v81 row_half_mirror row_mask:0xf bank_mask:0xf
	ds_write_b64 v102, v[88:89] offset:43008
	v_add_f32_dpp v80, v80, v80 row_mirror row_mask:0xf bank_mask:0xf
	v_add_f32_dpp v81, v81, v81 row_mirror row_mask:0xf bank_mask:0xf
	v_pk_fma_f32 v[0:1], v[80:81], v[24:25], v[0:1] op_sel:[0,0,0] op_sel_hi:[1,0,1] neg_lo:[1,0,0] neg_hi:[1,0,0]
	v_pk_fma_f32 v[2:3], v[80:81], v[24:25], v[2:3] op_sel:[0,1,0] op_sel_hi:[1,1,1] neg_lo:[1,0,0] neg_hi:[1,0,0]
	v_pk_fma_f32 v[4:5], v[80:81], v[26:27], v[4:5] op_sel:[0,0,0] op_sel_hi:[1,0,1] neg_lo:[1,0,0] neg_hi:[1,0,0]
	v_pk_fma_f32 v[6:7], v[80:81], v[26:27], v[6:7] op_sel:[0,1,0] op_sel_hi:[1,1,1] neg_lo:[1,0,0] neg_hi:[1,0,0]
	v_pk_fma_f32 v[0:1], v[28:29], v[16:17], v[0:1] op_sel:[0,0,0] op_sel_hi:[1,0,1]
	v_pk_fma_f32 v[2:3], v[28:29], v[16:17], v[2:3] op_sel:[0,1,0] op_sel_hi:[1,1,1]
	v_pk_fma_f32 v[4:5], v[28:29], v[18:19], v[4:5] op_sel:[0,0,0] op_sel_hi:[1,0,1]
	v_pk_fma_f32 v[6:7], v[28:29], v[18:19], v[6:7] op_sel:[0,1,0] op_sel_hi:[1,1,1]
	v_pk_mul_f32 v[84:85], v[8:9], v[0:1] op_sel:[0,0] op_sel_hi:[0,1]
	v_pk_mul_f32 v[86:87], v[8:9], v[2:3] op_sel:[1,0] op_sel_hi:[1,1]
	v_pk_fma_f32 v[84:85], v[10:11], v[4:5], v[84:85] op_sel:[0,0,0] op_sel_hi:[0,1,1]
	v_pk_fma_f32 v[86:87], v[10:11], v[6:7], v[86:87] op_sel:[1,0,0] op_sel_hi:[1,1,1]
	ds_read_b128 v[8:11], v100 offset:38400
	ds_read_b128 v[12:15], v100 offset:38656
	ds_read_b128 v[16:19], v100 offset:38912
	ds_read_b128 v[20:23], v100 offset:39168
	ds_read_b128 v[24:27], v100 offset:39424
	ds_read_b64 v[28:29], v101 offset:39680
	s_waitcnt lgkmcnt(14)
	v_pk_mul_f32 v[80:81], v[44:45], v[0:1] op_sel:[0,0] op_sel_hi:[0,1]
	v_pk_mul_f32 v[82:83], v[44:45], v[2:3] op_sel:[1,0] op_sel_hi:[1,1]
	v_pk_fma_f32 v[80:81], v[46:47], v[4:5], v[80:81] op_sel:[0,0,0] op_sel_hi:[0,1,1]
	v_pk_fma_f32 v[82:83], v[46:47], v[6:7], v[82:83] op_sel:[1,0,0] op_sel_hi:[1,1,1]
	v_pk_add_f32 v[84:85], v[84:85], v[86:87]
	v_pk_add_f32 v[80:81], v[80:81], v[82:83]
	v_pk_mul_f32 v[0:1], v[36:37], v[0:1] op_sel:[0,0] op_sel_hi:[0,1]
	v_pk_mul_f32 v[2:3], v[36:37], v[2:3] op_sel:[1,0] op_sel_hi:[1,1]
	v_add_f32_dpp v80, v80, v80 quad_perm:[1,0,3,2] row_mask:0xf bank_mask:0xf
	v_add_f32_dpp v81, v81, v81 quad_perm:[1,0,3,2] row_mask:0xf bank_mask:0xf
	v_pk_mul_f32 v[4:5], v[38:39], v[4:5] op_sel:[0,0] op_sel_hi:[0,1]
	v_add_f32_dpp v80, v80, v80 quad_perm:[2,3,0,1] row_mask:0xf bank_mask:0xf
	v_add_f32_dpp v81, v81, v81 quad_perm:[2,3,0,1] row_mask:0xf bank_mask:0xf
	v_pk_mul_f32 v[6:7], v[38:39], v[6:7] op_sel:[1,0] op_sel_hi:[1,1]
	v_add_f32_dpp v80, v80, v80 row_half_mirror row_mask:0xf bank_mask:0xf
	v_add_f32_dpp v81, v81, v81 row_half_mirror row_mask:0xf bank_mask:0xf
	ds_write_b64 v102, v[84:85] offset:45056
	v_add_f32_dpp v80, v80, v80 row_mirror row_mask:0xf bank_mask:0xf
	v_add_f32_dpp v81, v81, v81 row_mirror row_mask:0xf bank_mask:0xf
	v_pk_fma_f32 v[0:1], v[80:81], v[48:49], v[0:1] op_sel:[0,0,0] op_sel_hi:[1,0,1] neg_lo:[1,0,0] neg_hi:[1,0,0]
	v_pk_fma_f32 v[2:3], v[80:81], v[48:49], v[2:3] op_sel:[0,1,0] op_sel_hi:[1,1,1] neg_lo:[1,0,0] neg_hi:[1,0,0]
	v_pk_fma_f32 v[4:5], v[80:81], v[50:51], v[4:5] op_sel:[0,0,0] op_sel_hi:[1,0,1] neg_lo:[1,0,0] neg_hi:[1,0,0]
	v_pk_fma_f32 v[6:7], v[80:81], v[50:51], v[6:7] op_sel:[0,1,0] op_sel_hi:[1,1,1] neg_lo:[1,0,0] neg_hi:[1,0,0]
	v_pk_fma_f32 v[0:1], v[52:53], v[40:41], v[0:1] op_sel:[0,0,0] op_sel_hi:[1,0,1]
	v_pk_fma_f32 v[2:3], v[52:53], v[40:41], v[2:3] op_sel:[0,1,0] op_sel_hi:[1,1,1]
	v_pk_fma_f32 v[4:5], v[52:53], v[42:43], v[4:5] op_sel:[0,0,0] op_sel_hi:[1,0,1]
	v_pk_fma_f32 v[6:7], v[52:53], v[42:43], v[6:7] op_sel:[0,1,0] op_sel_hi:[1,1,1]
	v_pk_mul_f32 v[88:89], v[32:33], v[0:1] op_sel:[0,0] op_sel_hi:[0,1]
	v_pk_mul_f32 v[90:91], v[32:33], v[2:3] op_sel:[1,0] op_sel_hi:[1,1]
	v_pk_fma_f32 v[88:89], v[34:35], v[4:5], v[88:89] op_sel:[0,0,0] op_sel_hi:[0,1,1]
	v_pk_fma_f32 v[90:91], v[34:35], v[6:7], v[90:91] op_sel:[1,0,0] op_sel_hi:[1,1,1]
	ds_read_b128 v[32:35], v100 offset:39936
	ds_read_b128 v[36:39], v100 offset:40192
	ds_read_b128 v[40:43], v100 offset:40448
	ds_read_b128 v[44:47], v100 offset:40704
	ds_read_b128 v[48:51], v100 offset:40960
	ds_read_b64 v[52:53], v101 offset:41216
	s_waitcnt lgkmcnt(14)
	v_pk_mul_f32 v[80:81], v[68:69], v[0:1] op_sel:[0,0] op_sel_hi:[0,1]
	v_pk_mul_f32 v[82:83], v[68:69], v[2:3] op_sel:[1,0] op_sel_hi:[1,1]
	v_pk_fma_f32 v[80:81], v[70:71], v[4:5], v[80:81] op_sel:[0,0,0] op_sel_hi:[0,1,1]
	v_pk_fma_f32 v[82:83], v[70:71], v[6:7], v[82:83] op_sel:[1,0,0] op_sel_hi:[1,1,1]
	v_pk_add_f32 v[88:89], v[88:89], v[90:91]
	v_pk_add_f32 v[80:81], v[80:81], v[82:83]
	v_pk_mul_f32 v[0:1], v[60:61], v[0:1] op_sel:[0,0] op_sel_hi:[0,1]
	v_pk_mul_f32 v[2:3], v[60:61], v[2:3] op_sel:[1,0] op_sel_hi:[1,1]
	v_add_f32_dpp v80, v80, v80 quad_perm:[1,0,3,2] row_mask:0xf bank_mask:0xf
	v_add_f32_dpp v81, v81, v81 quad_perm:[1,0,3,2] row_mask:0xf bank_mask:0xf
	v_pk_mul_f32 v[4:5], v[62:63], v[4:5] op_sel:[0,0] op_sel_hi:[0,1]
	v_add_f32_dpp v80, v80, v80 quad_perm:[2,3,0,1] row_mask:0xf bank_mask:0xf
	v_add_f32_dpp v81, v81, v81 quad_perm:[2,3,0,1] row_mask:0xf bank_mask:0xf
	v_pk_mul_f32 v[6:7], v[62:63], v[6:7] op_sel:[1,0] op_sel_hi:[1,1]
	v_add_f32_dpp v80, v80, v80 row_half_mirror row_mask:0xf bank_mask:0xf
	v_add_f32_dpp v81, v81, v81 row_half_mirror row_mask:0xf bank_mask:0xf
	ds_write_b64 v102, v[88:89] offset:47104
	v_add_f32_dpp v80, v80, v80 row_mirror row_mask:0xf bank_mask:0xf
	v_add_f32_dpp v81, v81, v81 row_mirror row_mask:0xf bank_mask:0xf
	v_pk_fma_f32 v[0:1], v[80:81], v[72:73], v[0:1] op_sel:[0,0,0] op_sel_hi:[1,0,1] neg_lo:[1,0,0] neg_hi:[1,0,0]
	v_pk_fma_f32 v[2:3], v[80:81], v[72:73], v[2:3] op_sel:[0,1,0] op_sel_hi:[1,1,1] neg_lo:[1,0,0] neg_hi:[1,0,0]
	v_pk_fma_f32 v[4:5], v[80:81], v[74:75], v[4:5] op_sel:[0,0,0] op_sel_hi:[1,0,1] neg_lo:[1,0,0] neg_hi:[1,0,0]
	v_pk_fma_f32 v[6:7], v[80:81], v[74:75], v[6:7] op_sel:[0,1,0] op_sel_hi:[1,1,1] neg_lo:[1,0,0] neg_hi:[1,0,0]
	v_pk_fma_f32 v[0:1], v[76:77], v[64:65], v[0:1] op_sel:[0,0,0] op_sel_hi:[1,0,1]
	v_pk_fma_f32 v[2:3], v[76:77], v[64:65], v[2:3] op_sel:[0,1,0] op_sel_hi:[1,1,1]
	v_pk_fma_f32 v[4:5], v[76:77], v[66:67], v[4:5] op_sel:[0,0,0] op_sel_hi:[1,0,1]
	v_pk_fma_f32 v[6:7], v[76:77], v[66:67], v[6:7] op_sel:[0,1,0] op_sel_hi:[1,1,1]
	v_pk_mul_f32 v[84:85], v[56:57], v[0:1] op_sel:[0,0] op_sel_hi:[0,1]
	v_pk_mul_f32 v[86:87], v[56:57], v[2:3] op_sel:[1,0] op_sel_hi:[1,1]
	v_pk_fma_f32 v[84:85], v[58:59], v[4:5], v[84:85] op_sel:[0,0,0] op_sel_hi:[0,1,1]
	v_pk_fma_f32 v[86:87], v[58:59], v[6:7], v[86:87] op_sel:[1,0,0] op_sel_hi:[1,1,1]
	ds_read_b128 v[56:59], v100 offset:41472
	ds_read_b128 v[60:63], v100 offset:41728
	ds_read_b128 v[64:67], v100 offset:41984
	ds_read_b128 v[68:71], v100 offset:42240
	ds_read_b128 v[72:75], v100 offset:42496
	ds_read_b64 v[76:77], v101 offset:42752
	s_waitcnt lgkmcnt(14)
	v_pk_mul_f32 v[80:81], v[20:21], v[0:1] op_sel:[0,0] op_sel_hi:[0,1]
	v_pk_mul_f32 v[82:83], v[20:21], v[2:3] op_sel:[1,0] op_sel_hi:[1,1]
	v_pk_fma_f32 v[80:81], v[22:23], v[4:5], v[80:81] op_sel:[0,0,0] op_sel_hi:[0,1,1]
	v_pk_fma_f32 v[82:83], v[22:23], v[6:7], v[82:83] op_sel:[1,0,0] op_sel_hi:[1,1,1]
	v_pk_add_f32 v[84:85], v[84:85], v[86:87]
	v_pk_add_f32 v[80:81], v[80:81], v[82:83]
	v_pk_mul_f32 v[0:1], v[12:13], v[0:1] op_sel:[0,0] op_sel_hi:[0,1]
	v_pk_mul_f32 v[2:3], v[12:13], v[2:3] op_sel:[1,0] op_sel_hi:[1,1]
	v_add_f32_dpp v80, v80, v80 quad_perm:[1,0,3,2] row_mask:0xf bank_mask:0xf
	v_add_f32_dpp v81, v81, v81 quad_perm:[1,0,3,2] row_mask:0xf bank_mask:0xf
	v_pk_mul_f32 v[4:5], v[14:15], v[4:5] op_sel:[0,0] op_sel_hi:[0,1]
	v_add_f32_dpp v80, v80, v80 quad_perm:[2,3,0,1] row_mask:0xf bank_mask:0xf
	v_add_f32_dpp v81, v81, v81 quad_perm:[2,3,0,1] row_mask:0xf bank_mask:0xf
	v_pk_mul_f32 v[6:7], v[14:15], v[6:7] op_sel:[1,0] op_sel_hi:[1,1]
	v_add_f32_dpp v80, v80, v80 row_half_mirror row_mask:0xf bank_mask:0xf
	v_add_f32_dpp v81, v81, v81 row_half_mirror row_mask:0xf bank_mask:0xf
	ds_write_b64 v102, v[84:85] offset:49152
	v_add_f32_dpp v80, v80, v80 row_mirror row_mask:0xf bank_mask:0xf
	v_add_f32_dpp v81, v81, v81 row_mirror row_mask:0xf bank_mask:0xf
	v_pk_fma_f32 v[0:1], v[80:81], v[24:25], v[0:1] op_sel:[0,0,0] op_sel_hi:[1,0,1] neg_lo:[1,0,0] neg_hi:[1,0,0]
	v_pk_fma_f32 v[2:3], v[80:81], v[24:25], v[2:3] op_sel:[0,1,0] op_sel_hi:[1,1,1] neg_lo:[1,0,0] neg_hi:[1,0,0]
	v_pk_fma_f32 v[4:5], v[80:81], v[26:27], v[4:5] op_sel:[0,0,0] op_sel_hi:[1,0,1] neg_lo:[1,0,0] neg_hi:[1,0,0]
	v_pk_fma_f32 v[6:7], v[80:81], v[26:27], v[6:7] op_sel:[0,1,0] op_sel_hi:[1,1,1] neg_lo:[1,0,0] neg_hi:[1,0,0]
	v_pk_fma_f32 v[0:1], v[28:29], v[16:17], v[0:1] op_sel:[0,0,0] op_sel_hi:[1,0,1]
	v_pk_fma_f32 v[2:3], v[28:29], v[16:17], v[2:3] op_sel:[0,1,0] op_sel_hi:[1,1,1]
	v_pk_fma_f32 v[4:5], v[28:29], v[18:19], v[4:5] op_sel:[0,0,0] op_sel_hi:[1,0,1]
	v_pk_fma_f32 v[6:7], v[28:29], v[18:19], v[6:7] op_sel:[0,1,0] op_sel_hi:[1,1,1]
	v_pk_mul_f32 v[88:89], v[8:9], v[0:1] op_sel:[0,0] op_sel_hi:[0,1]
	v_pk_mul_f32 v[90:91], v[8:9], v[2:3] op_sel:[1,0] op_sel_hi:[1,1]
	v_pk_fma_f32 v[88:89], v[10:11], v[4:5], v[88:89] op_sel:[0,0,0] op_sel_hi:[0,1,1]
	v_pk_fma_f32 v[90:91], v[10:11], v[6:7], v[90:91] op_sel:[1,0,0] op_sel_hi:[1,1,1]
	ds_read_b128 v[8:11], v100 offset:43008
	ds_read_b128 v[12:15], v100 offset:43264
	ds_read_b128 v[16:19], v100 offset:43520
	ds_read_b128 v[20:23], v100 offset:43776
	ds_read_b128 v[24:27], v100 offset:44032
	ds_read_b64 v[28:29], v101 offset:44288
	s_waitcnt lgkmcnt(14)
	v_pk_mul_f32 v[80:81], v[44:45], v[0:1] op_sel:[0,0] op_sel_hi:[0,1]
	v_pk_mul_f32 v[82:83], v[44:45], v[2:3] op_sel:[1,0] op_sel_hi:[1,1]
	v_pk_fma_f32 v[80:81], v[46:47], v[4:5], v[80:81] op_sel:[0,0,0] op_sel_hi:[0,1,1]
	v_pk_fma_f32 v[82:83], v[46:47], v[6:7], v[82:83] op_sel:[1,0,0] op_sel_hi:[1,1,1]
	v_pk_add_f32 v[88:89], v[88:89], v[90:91]
	v_pk_add_f32 v[80:81], v[80:81], v[82:83]
	v_pk_mul_f32 v[0:1], v[36:37], v[0:1] op_sel:[0,0] op_sel_hi:[0,1]
	v_pk_mul_f32 v[2:3], v[36:37], v[2:3] op_sel:[1,0] op_sel_hi:[1,1]
	v_add_f32_dpp v80, v80, v80 quad_perm:[1,0,3,2] row_mask:0xf bank_mask:0xf
	v_add_f32_dpp v81, v81, v81 quad_perm:[1,0,3,2] row_mask:0xf bank_mask:0xf
	v_pk_mul_f32 v[4:5], v[38:39], v[4:5] op_sel:[0,0] op_sel_hi:[0,1]
	v_add_f32_dpp v80, v80, v80 quad_perm:[2,3,0,1] row_mask:0xf bank_mask:0xf
	v_add_f32_dpp v81, v81, v81 quad_perm:[2,3,0,1] row_mask:0xf bank_mask:0xf
	v_pk_mul_f32 v[6:7], v[38:39], v[6:7] op_sel:[1,0] op_sel_hi:[1,1]
	v_add_f32_dpp v80, v80, v80 row_half_mirror row_mask:0xf bank_mask:0xf
	v_add_f32_dpp v81, v81, v81 row_half_mirror row_mask:0xf bank_mask:0xf
	ds_write_b64 v102, v[88:89] offset:51200
	v_add_f32_dpp v80, v80, v80 row_mirror row_mask:0xf bank_mask:0xf
	v_add_f32_dpp v81, v81, v81 row_mirror row_mask:0xf bank_mask:0xf
	v_pk_fma_f32 v[0:1], v[80:81], v[48:49], v[0:1] op_sel:[0,0,0] op_sel_hi:[1,0,1] neg_lo:[1,0,0] neg_hi:[1,0,0]
	v_pk_fma_f32 v[2:3], v[80:81], v[48:49], v[2:3] op_sel:[0,1,0] op_sel_hi:[1,1,1] neg_lo:[1,0,0] neg_hi:[1,0,0]
	v_pk_fma_f32 v[4:5], v[80:81], v[50:51], v[4:5] op_sel:[0,0,0] op_sel_hi:[1,0,1] neg_lo:[1,0,0] neg_hi:[1,0,0]
	v_pk_fma_f32 v[6:7], v[80:81], v[50:51], v[6:7] op_sel:[0,1,0] op_sel_hi:[1,1,1] neg_lo:[1,0,0] neg_hi:[1,0,0]
	v_pk_fma_f32 v[0:1], v[52:53], v[40:41], v[0:1] op_sel:[0,0,0] op_sel_hi:[1,0,1]
	v_pk_fma_f32 v[2:3], v[52:53], v[40:41], v[2:3] op_sel:[0,1,0] op_sel_hi:[1,1,1]
	v_pk_fma_f32 v[4:5], v[52:53], v[42:43], v[4:5] op_sel:[0,0,0] op_sel_hi:[1,0,1]
	v_pk_fma_f32 v[6:7], v[52:53], v[42:43], v[6:7] op_sel:[0,1,0] op_sel_hi:[1,1,1]
	v_pk_mul_f32 v[84:85], v[32:33], v[0:1] op_sel:[0,0] op_sel_hi:[0,1]
	v_pk_mul_f32 v[86:87], v[32:33], v[2:3] op_sel:[1,0] op_sel_hi:[1,1]
	v_pk_fma_f32 v[84:85], v[34:35], v[4:5], v[84:85] op_sel:[0,0,0] op_sel_hi:[0,1,1]
	v_pk_fma_f32 v[86:87], v[34:35], v[6:7], v[86:87] op_sel:[1,0,0] op_sel_hi:[1,1,1]
	ds_read_b128 v[32:35], v100 offset:44544
	ds_read_b128 v[36:39], v100 offset:44800
	ds_read_b128 v[40:43], v100 offset:45056
	ds_read_b128 v[44:47], v100 offset:45312
	ds_read_b128 v[48:51], v100 offset:45568
	ds_read_b64 v[52:53], v101 offset:45824
	s_waitcnt lgkmcnt(14)
	v_pk_mul_f32 v[80:81], v[68:69], v[0:1] op_sel:[0,0] op_sel_hi:[0,1]
	v_pk_mul_f32 v[82:83], v[68:69], v[2:3] op_sel:[1,0] op_sel_hi:[1,1]
	v_pk_fma_f32 v[80:81], v[70:71], v[4:5], v[80:81] op_sel:[0,0,0] op_sel_hi:[0,1,1]
	v_pk_fma_f32 v[82:83], v[70:71], v[6:7], v[82:83] op_sel:[1,0,0] op_sel_hi:[1,1,1]
	v_pk_add_f32 v[84:85], v[84:85], v[86:87]
	v_pk_add_f32 v[80:81], v[80:81], v[82:83]
	v_pk_mul_f32 v[0:1], v[60:61], v[0:1] op_sel:[0,0] op_sel_hi:[0,1]
	v_pk_mul_f32 v[2:3], v[60:61], v[2:3] op_sel:[1,0] op_sel_hi:[1,1]
	v_add_f32_dpp v80, v80, v80 quad_perm:[1,0,3,2] row_mask:0xf bank_mask:0xf
	v_add_f32_dpp v81, v81, v81 quad_perm:[1,0,3,2] row_mask:0xf bank_mask:0xf
	v_pk_mul_f32 v[4:5], v[62:63], v[4:5] op_sel:[0,0] op_sel_hi:[0,1]
	v_add_f32_dpp v80, v80, v80 quad_perm:[2,3,0,1] row_mask:0xf bank_mask:0xf
	v_add_f32_dpp v81, v81, v81 quad_perm:[2,3,0,1] row_mask:0xf bank_mask:0xf
	v_pk_mul_f32 v[6:7], v[62:63], v[6:7] op_sel:[1,0] op_sel_hi:[1,1]
	v_add_f32_dpp v80, v80, v80 row_half_mirror row_mask:0xf bank_mask:0xf
	v_add_f32_dpp v81, v81, v81 row_half_mirror row_mask:0xf bank_mask:0xf
	ds_write_b64 v102, v[84:85] offset:53248
	v_add_f32_dpp v80, v80, v80 row_mirror row_mask:0xf bank_mask:0xf
	v_add_f32_dpp v81, v81, v81 row_mirror row_mask:0xf bank_mask:0xf
	v_pk_fma_f32 v[0:1], v[80:81], v[72:73], v[0:1] op_sel:[0,0,0] op_sel_hi:[1,0,1] neg_lo:[1,0,0] neg_hi:[1,0,0]
	v_pk_fma_f32 v[2:3], v[80:81], v[72:73], v[2:3] op_sel:[0,1,0] op_sel_hi:[1,1,1] neg_lo:[1,0,0] neg_hi:[1,0,0]
	v_pk_fma_f32 v[4:5], v[80:81], v[74:75], v[4:5] op_sel:[0,0,0] op_sel_hi:[1,0,1] neg_lo:[1,0,0] neg_hi:[1,0,0]
	v_pk_fma_f32 v[6:7], v[80:81], v[74:75], v[6:7] op_sel:[0,1,0] op_sel_hi:[1,1,1] neg_lo:[1,0,0] neg_hi:[1,0,0]
	v_pk_fma_f32 v[0:1], v[76:77], v[64:65], v[0:1] op_sel:[0,0,0] op_sel_hi:[1,0,1]
	v_pk_fma_f32 v[2:3], v[76:77], v[64:65], v[2:3] op_sel:[0,1,0] op_sel_hi:[1,1,1]
	v_pk_fma_f32 v[4:5], v[76:77], v[66:67], v[4:5] op_sel:[0,0,0] op_sel_hi:[1,0,1]
	v_pk_fma_f32 v[6:7], v[76:77], v[66:67], v[6:7] op_sel:[0,1,0] op_sel_hi:[1,1,1]
	v_pk_mul_f32 v[88:89], v[56:57], v[0:1] op_sel:[0,0] op_sel_hi:[0,1]
	v_pk_mul_f32 v[90:91], v[56:57], v[2:3] op_sel:[1,0] op_sel_hi:[1,1]
	v_pk_fma_f32 v[88:89], v[58:59], v[4:5], v[88:89] op_sel:[0,0,0] op_sel_hi:[0,1,1]
	v_pk_fma_f32 v[90:91], v[58:59], v[6:7], v[90:91] op_sel:[1,0,0] op_sel_hi:[1,1,1]
	ds_read_b128 v[56:59], v100 offset:46080
	ds_read_b128 v[60:63], v100 offset:46336
	ds_read_b128 v[64:67], v100 offset:46592
	ds_read_b128 v[68:71], v100 offset:46848
	ds_read_b128 v[72:75], v100 offset:47104
	ds_read_b64 v[76:77], v101 offset:47360
	s_waitcnt lgkmcnt(14)
	v_pk_mul_f32 v[80:81], v[20:21], v[0:1] op_sel:[0,0] op_sel_hi:[0,1]
	v_pk_mul_f32 v[82:83], v[20:21], v[2:3] op_sel:[1,0] op_sel_hi:[1,1]
	v_pk_fma_f32 v[80:81], v[22:23], v[4:5], v[80:81] op_sel:[0,0,0] op_sel_hi:[0,1,1]
	v_pk_fma_f32 v[82:83], v[22:23], v[6:7], v[82:83] op_sel:[1,0,0] op_sel_hi:[1,1,1]
	v_pk_add_f32 v[88:89], v[88:89], v[90:91]
	v_pk_add_f32 v[80:81], v[80:81], v[82:83]
	v_pk_mul_f32 v[0:1], v[12:13], v[0:1] op_sel:[0,0] op_sel_hi:[0,1]
	v_pk_mul_f32 v[2:3], v[12:13], v[2:3] op_sel:[1,0] op_sel_hi:[1,1]
	v_add_f32_dpp v80, v80, v80 quad_perm:[1,0,3,2] row_mask:0xf bank_mask:0xf
	v_add_f32_dpp v81, v81, v81 quad_perm:[1,0,3,2] row_mask:0xf bank_mask:0xf
	v_pk_mul_f32 v[4:5], v[14:15], v[4:5] op_sel:[0,0] op_sel_hi:[0,1]
	v_add_f32_dpp v80, v80, v80 quad_perm:[2,3,0,1] row_mask:0xf bank_mask:0xf
	v_add_f32_dpp v81, v81, v81 quad_perm:[2,3,0,1] row_mask:0xf bank_mask:0xf
	v_pk_mul_f32 v[6:7], v[14:15], v[6:7] op_sel:[1,0] op_sel_hi:[1,1]
	v_add_f32_dpp v80, v80, v80 row_half_mirror row_mask:0xf bank_mask:0xf
	v_add_f32_dpp v81, v81, v81 row_half_mirror row_mask:0xf bank_mask:0xf
	ds_write_b64 v102, v[88:89] offset:55296
	v_add_f32_dpp v80, v80, v80 row_mirror row_mask:0xf bank_mask:0xf
	v_add_f32_dpp v81, v81, v81 row_mirror row_mask:0xf bank_mask:0xf
	v_pk_fma_f32 v[0:1], v[80:81], v[24:25], v[0:1] op_sel:[0,0,0] op_sel_hi:[1,0,1] neg_lo:[1,0,0] neg_hi:[1,0,0]
	v_pk_fma_f32 v[2:3], v[80:81], v[24:25], v[2:3] op_sel:[0,1,0] op_sel_hi:[1,1,1] neg_lo:[1,0,0] neg_hi:[1,0,0]
	v_pk_fma_f32 v[4:5], v[80:81], v[26:27], v[4:5] op_sel:[0,0,0] op_sel_hi:[1,0,1] neg_lo:[1,0,0] neg_hi:[1,0,0]
	v_pk_fma_f32 v[6:7], v[80:81], v[26:27], v[6:7] op_sel:[0,1,0] op_sel_hi:[1,1,1] neg_lo:[1,0,0] neg_hi:[1,0,0]
	v_pk_fma_f32 v[0:1], v[28:29], v[16:17], v[0:1] op_sel:[0,0,0] op_sel_hi:[1,0,1]
	v_pk_fma_f32 v[2:3], v[28:29], v[16:17], v[2:3] op_sel:[0,1,0] op_sel_hi:[1,1,1]
	v_pk_fma_f32 v[4:5], v[28:29], v[18:19], v[4:5] op_sel:[0,0,0] op_sel_hi:[1,0,1]
	v_pk_fma_f32 v[6:7], v[28:29], v[18:19], v[6:7] op_sel:[0,1,0] op_sel_hi:[1,1,1]
	v_pk_mul_f32 v[84:85], v[8:9], v[0:1] op_sel:[0,0] op_sel_hi:[0,1]
	v_pk_mul_f32 v[86:87], v[8:9], v[2:3] op_sel:[1,0] op_sel_hi:[1,1]
	v_pk_fma_f32 v[84:85], v[10:11], v[4:5], v[84:85] op_sel:[0,0,0] op_sel_hi:[0,1,1]
	v_pk_fma_f32 v[86:87], v[10:11], v[6:7], v[86:87] op_sel:[1,0,0] op_sel_hi:[1,1,1]
	ds_read_b128 v[8:11], v100 offset:47616
	ds_read_b128 v[12:15], v100 offset:47872
	ds_read_b128 v[16:19], v100 offset:48128
	ds_read_b128 v[20:23], v100 offset:48384
	ds_read_b128 v[24:27], v100 offset:48640
	ds_read_b64 v[28:29], v101 offset:48896
	s_waitcnt lgkmcnt(14)
	v_pk_mul_f32 v[80:81], v[44:45], v[0:1] op_sel:[0,0] op_sel_hi:[0,1]
	v_pk_mul_f32 v[82:83], v[44:45], v[2:3] op_sel:[1,0] op_sel_hi:[1,1]
	v_pk_fma_f32 v[80:81], v[46:47], v[4:5], v[80:81] op_sel:[0,0,0] op_sel_hi:[0,1,1]
	v_pk_fma_f32 v[82:83], v[46:47], v[6:7], v[82:83] op_sel:[1,0,0] op_sel_hi:[1,1,1]
	v_pk_add_f32 v[84:85], v[84:85], v[86:87]
	v_pk_add_f32 v[80:81], v[80:81], v[82:83]
	v_pk_mul_f32 v[0:1], v[36:37], v[0:1] op_sel:[0,0] op_sel_hi:[0,1]
	v_pk_mul_f32 v[2:3], v[36:37], v[2:3] op_sel:[1,0] op_sel_hi:[1,1]
	v_add_f32_dpp v80, v80, v80 quad_perm:[1,0,3,2] row_mask:0xf bank_mask:0xf
	v_add_f32_dpp v81, v81, v81 quad_perm:[1,0,3,2] row_mask:0xf bank_mask:0xf
	v_pk_mul_f32 v[4:5], v[38:39], v[4:5] op_sel:[0,0] op_sel_hi:[0,1]
	v_add_f32_dpp v80, v80, v80 quad_perm:[2,3,0,1] row_mask:0xf bank_mask:0xf
	v_add_f32_dpp v81, v81, v81 quad_perm:[2,3,0,1] row_mask:0xf bank_mask:0xf
	v_pk_mul_f32 v[6:7], v[38:39], v[6:7] op_sel:[1,0] op_sel_hi:[1,1]
	v_add_f32_dpp v80, v80, v80 row_half_mirror row_mask:0xf bank_mask:0xf
	v_add_f32_dpp v81, v81, v81 row_half_mirror row_mask:0xf bank_mask:0xf
	ds_write_b64 v102, v[84:85] offset:57344
	v_add_f32_dpp v80, v80, v80 row_mirror row_mask:0xf bank_mask:0xf
	v_add_f32_dpp v81, v81, v81 row_mirror row_mask:0xf bank_mask:0xf
	v_pk_fma_f32 v[0:1], v[80:81], v[48:49], v[0:1] op_sel:[0,0,0] op_sel_hi:[1,0,1] neg_lo:[1,0,0] neg_hi:[1,0,0]
	v_pk_fma_f32 v[2:3], v[80:81], v[48:49], v[2:3] op_sel:[0,1,0] op_sel_hi:[1,1,1] neg_lo:[1,0,0] neg_hi:[1,0,0]
	v_pk_fma_f32 v[4:5], v[80:81], v[50:51], v[4:5] op_sel:[0,0,0] op_sel_hi:[1,0,1] neg_lo:[1,0,0] neg_hi:[1,0,0]
	v_pk_fma_f32 v[6:7], v[80:81], v[50:51], v[6:7] op_sel:[0,1,0] op_sel_hi:[1,1,1] neg_lo:[1,0,0] neg_hi:[1,0,0]
	v_pk_fma_f32 v[0:1], v[52:53], v[40:41], v[0:1] op_sel:[0,0,0] op_sel_hi:[1,0,1]
	v_pk_fma_f32 v[2:3], v[52:53], v[40:41], v[2:3] op_sel:[0,1,0] op_sel_hi:[1,1,1]
	v_pk_fma_f32 v[4:5], v[52:53], v[42:43], v[4:5] op_sel:[0,0,0] op_sel_hi:[1,0,1]
	v_pk_fma_f32 v[6:7], v[52:53], v[42:43], v[6:7] op_sel:[0,1,0] op_sel_hi:[1,1,1]
	v_pk_mul_f32 v[88:89], v[32:33], v[0:1] op_sel:[0,0] op_sel_hi:[0,1]
	v_pk_mul_f32 v[90:91], v[32:33], v[2:3] op_sel:[1,0] op_sel_hi:[1,1]
	v_pk_fma_f32 v[88:89], v[34:35], v[4:5], v[88:89] op_sel:[0,0,0] op_sel_hi:[0,1,1]
	v_pk_fma_f32 v[90:91], v[34:35], v[6:7], v[90:91] op_sel:[1,0,0] op_sel_hi:[1,1,1]
	s_waitcnt lgkmcnt(8)
	v_pk_mul_f32 v[80:81], v[68:69], v[0:1] op_sel:[0,0] op_sel_hi:[0,1]
	v_pk_mul_f32 v[82:83], v[68:69], v[2:3] op_sel:[1,0] op_sel_hi:[1,1]
	v_pk_fma_f32 v[80:81], v[70:71], v[4:5], v[80:81] op_sel:[0,0,0] op_sel_hi:[0,1,1]
	v_pk_fma_f32 v[82:83], v[70:71], v[6:7], v[82:83] op_sel:[1,0,0] op_sel_hi:[1,1,1]
	v_pk_add_f32 v[88:89], v[88:89], v[90:91]
	v_pk_add_f32 v[80:81], v[80:81], v[82:83]
	v_pk_mul_f32 v[0:1], v[60:61], v[0:1] op_sel:[0,0] op_sel_hi:[0,1]
	v_pk_mul_f32 v[2:3], v[60:61], v[2:3] op_sel:[1,0] op_sel_hi:[1,1]
	v_add_f32_dpp v80, v80, v80 quad_perm:[1,0,3,2] row_mask:0xf bank_mask:0xf
	v_add_f32_dpp v81, v81, v81 quad_perm:[1,0,3,2] row_mask:0xf bank_mask:0xf
	v_pk_mul_f32 v[4:5], v[62:63], v[4:5] op_sel:[0,0] op_sel_hi:[0,1]
	v_add_f32_dpp v80, v80, v80 quad_perm:[2,3,0,1] row_mask:0xf bank_mask:0xf
	v_add_f32_dpp v81, v81, v81 quad_perm:[2,3,0,1] row_mask:0xf bank_mask:0xf
	v_pk_mul_f32 v[6:7], v[62:63], v[6:7] op_sel:[1,0] op_sel_hi:[1,1]
	v_add_f32_dpp v80, v80, v80 row_half_mirror row_mask:0xf bank_mask:0xf
	v_add_f32_dpp v81, v81, v81 row_half_mirror row_mask:0xf bank_mask:0xf
	ds_write_b64 v102, v[88:89] offset:59392
	v_add_f32_dpp v80, v80, v80 row_mirror row_mask:0xf bank_mask:0xf
	v_add_f32_dpp v81, v81, v81 row_mirror row_mask:0xf bank_mask:0xf
	v_pk_fma_f32 v[0:1], v[80:81], v[72:73], v[0:1] op_sel:[0,0,0] op_sel_hi:[1,0,1] neg_lo:[1,0,0] neg_hi:[1,0,0]
	v_pk_fma_f32 v[2:3], v[80:81], v[72:73], v[2:3] op_sel:[0,1,0] op_sel_hi:[1,1,1] neg_lo:[1,0,0] neg_hi:[1,0,0]
	v_pk_fma_f32 v[4:5], v[80:81], v[74:75], v[4:5] op_sel:[0,0,0] op_sel_hi:[1,0,1] neg_lo:[1,0,0] neg_hi:[1,0,0]
	v_pk_fma_f32 v[6:7], v[80:81], v[74:75], v[6:7] op_sel:[0,1,0] op_sel_hi:[1,1,1] neg_lo:[1,0,0] neg_hi:[1,0,0]
	v_pk_fma_f32 v[0:1], v[76:77], v[64:65], v[0:1] op_sel:[0,0,0] op_sel_hi:[1,0,1]
	v_pk_fma_f32 v[2:3], v[76:77], v[64:65], v[2:3] op_sel:[0,1,0] op_sel_hi:[1,1,1]
	v_pk_fma_f32 v[4:5], v[76:77], v[66:67], v[4:5] op_sel:[0,0,0] op_sel_hi:[1,0,1]
	v_pk_fma_f32 v[6:7], v[76:77], v[66:67], v[6:7] op_sel:[0,1,0] op_sel_hi:[1,1,1]
	v_pk_mul_f32 v[84:85], v[56:57], v[0:1] op_sel:[0,0] op_sel_hi:[0,1]
	v_pk_mul_f32 v[86:87], v[56:57], v[2:3] op_sel:[1,0] op_sel_hi:[1,1]
	v_pk_fma_f32 v[84:85], v[58:59], v[4:5], v[84:85] op_sel:[0,0,0] op_sel_hi:[0,1,1]
	v_pk_fma_f32 v[86:87], v[58:59], v[6:7], v[86:87] op_sel:[1,0,0] op_sel_hi:[1,1,1]
	s_waitcnt lgkmcnt(2)
	v_pk_mul_f32 v[80:81], v[20:21], v[0:1] op_sel:[0,0] op_sel_hi:[0,1]
	v_pk_mul_f32 v[82:83], v[20:21], v[2:3] op_sel:[1,0] op_sel_hi:[1,1]
	v_pk_fma_f32 v[80:81], v[22:23], v[4:5], v[80:81] op_sel:[0,0,0] op_sel_hi:[0,1,1]
	v_pk_fma_f32 v[82:83], v[22:23], v[6:7], v[82:83] op_sel:[1,0,0] op_sel_hi:[1,1,1]
	v_pk_add_f32 v[84:85], v[84:85], v[86:87]
	v_pk_add_f32 v[80:81], v[80:81], v[82:83]
	v_pk_mul_f32 v[0:1], v[12:13], v[0:1] op_sel:[0,0] op_sel_hi:[0,1]
	v_pk_mul_f32 v[2:3], v[12:13], v[2:3] op_sel:[1,0] op_sel_hi:[1,1]
	v_add_f32_dpp v80, v80, v80 quad_perm:[1,0,3,2] row_mask:0xf bank_mask:0xf
	v_add_f32_dpp v81, v81, v81 quad_perm:[1,0,3,2] row_mask:0xf bank_mask:0xf
	v_pk_mul_f32 v[4:5], v[14:15], v[4:5] op_sel:[0,0] op_sel_hi:[0,1]
	v_add_f32_dpp v80, v80, v80 quad_perm:[2,3,0,1] row_mask:0xf bank_mask:0xf
	v_add_f32_dpp v81, v81, v81 quad_perm:[2,3,0,1] row_mask:0xf bank_mask:0xf
	v_pk_mul_f32 v[6:7], v[14:15], v[6:7] op_sel:[1,0] op_sel_hi:[1,1]
	v_add_f32_dpp v80, v80, v80 row_half_mirror row_mask:0xf bank_mask:0xf
	v_add_f32_dpp v81, v81, v81 row_half_mirror row_mask:0xf bank_mask:0xf
	ds_write_b64 v102, v[84:85] offset:61440
	v_add_f32_dpp v80, v80, v80 row_mirror row_mask:0xf bank_mask:0xf
	v_add_f32_dpp v81, v81, v81 row_mirror row_mask:0xf bank_mask:0xf
	v_pk_fma_f32 v[0:1], v[80:81], v[24:25], v[0:1] op_sel:[0,0,0] op_sel_hi:[1,0,1] neg_lo:[1,0,0] neg_hi:[1,0,0]
	v_pk_fma_f32 v[2:3], v[80:81], v[24:25], v[2:3] op_sel:[0,1,0] op_sel_hi:[1,1,1] neg_lo:[1,0,0] neg_hi:[1,0,0]
	v_pk_fma_f32 v[4:5], v[80:81], v[26:27], v[4:5] op_sel:[0,0,0] op_sel_hi:[1,0,1] neg_lo:[1,0,0] neg_hi:[1,0,0]
	v_pk_fma_f32 v[6:7], v[80:81], v[26:27], v[6:7] op_sel:[0,1,0] op_sel_hi:[1,1,1] neg_lo:[1,0,0] neg_hi:[1,0,0]
	v_pk_fma_f32 v[0:1], v[28:29], v[16:17], v[0:1] op_sel:[0,0,0] op_sel_hi:[1,0,1]
	v_pk_fma_f32 v[2:3], v[28:29], v[16:17], v[2:3] op_sel:[0,1,0] op_sel_hi:[1,1,1]
	v_pk_fma_f32 v[4:5], v[28:29], v[18:19], v[4:5] op_sel:[0,0,0] op_sel_hi:[1,0,1]
	v_pk_fma_f32 v[6:7], v[28:29], v[18:19], v[6:7] op_sel:[0,1,0] op_sel_hi:[1,1,1]
	v_pk_mul_f32 v[88:89], v[8:9], v[0:1] op_sel:[0,0] op_sel_hi:[0,1]
	v_pk_mul_f32 v[90:91], v[8:9], v[2:3] op_sel:[1,0] op_sel_hi:[1,1]
	v_pk_fma_f32 v[88:89], v[10:11], v[4:5], v[88:89] op_sel:[0,0,0] op_sel_hi:[0,1,1]
	v_pk_fma_f32 v[90:91], v[10:11], v[6:7], v[90:91] op_sel:[1,0,0] op_sel_hi:[1,1,1]
	s_nop 0
	v_pk_add_f32 v[88:89], v[88:89], v[90:91]
	s_nop 0
	ds_write_b64 v102, v[88:89] offset:63488
	s_waitcnt lgkmcnt(0)
	s_barrier
	s_add_i32 s16, s16, 2
	s_cmp_lt_u32 s16, 0x100
	s_cbranch_scc1 .Lrc_loop
	s_waitcnt vmcnt(0) lgkmcnt(0)
	s_setprio 0
.LBB0_1033:
	s_andn2_saveexec_b64 s[20:21], s[0:1]
	s_cbranch_execz .LBB0_1026
	s_lshr_b32 s10, s34, 6
	s_bfe_u32 s11, s34, 0x20004
	s_bfe_u32 s14, s34, 0x30001
	s_add_u32 s16, s28, 0x3400000
	s_addc_u32 s17, s29, 0
	s_add_u32 s18, s28, 0x1a80000
	s_addc_u32 s19, s29, 0
	s_add_u32 s22, s26, 0x2000000
	s_addc_u32 s23, s27, 0
	s_mov_b32 s52, 0x22000
	s_mov_b32 s53, 0
	s_mov_b32 s54, 0x4000
	s_mov_b32 s55, 0
	s_mov_b32 s56, 16
	s_mov_b32 s57, 1
	s_lshl_b32 s58, s11, 12
	s_mov_b32 s59, 0
	s_cmp_eq_u32 s10, 0
	s_cbranch_scc1 .Lrs_fwd
	s_add_u32 s22, s26, 0x3000000
	s_addc_u32 s23, s27, 0
	s_mov_b32 s52, 0xfffde000
	s_mov_b32 s53, -1
	s_mov_b32 s54, 0xffffc000
	s_mov_b32 s55, -1
	s_mov_b32 s56, -16
	s_mov_b32 s57, -1
	s_movk_i32 s59, 0xfff
.Lrs_fwd:
	s_movk_i32 s15, 0x2200
	s_lshl_b32 s12, s14, 6
	s_lshl_b32 s13, s10, 9
	v_readlane_b32 s46, v255, 23
	v_readlane_b32 s47, v255, 24
	v_readlane_b32 s48, v255, 25
	v_readlane_b32 s49, v255, 26
	v_readlane_b32 s60, v255, 29
	v_readlane_b32 s61, v255, 30
	v_readlane_b32 s10, v255, 35
	v_readlane_b32 s11, v255, 36
	v_readlane_b32 s24, v255, 37
	v_readlane_b32 s25, v255, 38
	v_and_b32_e32 v112, 15, v164
	v_bfe_u32 v113, v164, 4, 4
	v_lshl_add_u32 v114, v112, 2, s12
	v_mul_lo_u32 v95, v113, s57
	v_add_u32_e32 v95, s59, v95
	v_add_u32_e32 v115, s58, v95
	v_mul_lo_u32 v108, v115, s15
	v_add_u32_e32 v109, 0xa00, v114
	v_lshl_add_u32 v108, v109, 1, v108
	v_mov_b32_e32 v109, 0
	v_lshl_add_u64 v[84:85], v[108:109], 0, s[16:17]
	s_mov_b32 s50, 0xffffde00
	s_mov_b32 s51, -1
	v_lshl_add_u64 v[86:87], v[84:85], 0, s[50:51]
	s_mov_b32 s50, 0x2200
	s_mov_b32 s51, 0
	v_lshl_add_u64 v[88:89], v[84:85], 0, s[50:51]
	v_lshlrev_b32_e32 v108, 10, v115
	v_lshl_add_u32 v108, v114, 1, v108
	v_lshl_add_u64 v[90:91], v[108:109], 0, s[22:23]
	v_lshl_add_u64 v[92:93], v[108:109], 0, s[18:19]
	v_mul_u32_u24_e32 v94, 0x600, v113
	v_lshl_add_u32 v94, v112, 4, v94
	v_lshlrev_b32_e32 v110, 2, v114
	v_add_u32_e32 v109, 0x1000, v110
	global_load_dwordx4 v[44:47], v110, s[46:47]
	global_load_dwordx4 v[48:51], v110, s[46:47] offset:2048
	global_load_dwordx4 v[52:55], v109, s[46:47]
	v_add_u32_e32 v111, 0x1c00, v110
	v_add_u32_e32 v109, 0x1000, v111
	global_load_dwordx4 v[56:59], v111, s[46:47]
	global_load_dwordx4 v[60:63], v111, s[46:47] offset:2048
	global_load_dwordx4 v[64:67], v109, s[46:47]
	global_load_dwordx4 v[68:71], v110, s[60:61]
	s_lshl_b32 s13, s13, 2
	v_add_u32_e32 v111, s13, v110
	global_load_dwordx4 v[72:75], v111, s[48:49]
	global_load_dwordx4 v[76:79], v110, s[10:11]
	global_load_dwordx4 v[80:83], v110, s[24:25]
	s_lshr_b32 s24, s34, 6
	s_and_b32 s22, s34, 1
	s_lshl_b32 s22, s22, 5
	s_lshl_b32 s23, s14, 6
	s_add_u32 s22, s22, s23
	s_add_u32 s22, s22, 0x200
	v_lshl_add_u32 v133, v112, 1, s22
	v_lshlrev_b32_e32 v132, 11, v115
	v_lshl_add_u32 v132, v133, 1, v132
	v_mov_b32_e32 v133, 0
	s_add_u32 s22, s28, 0xdc00000
	s_addc_u32 s23, s29, 0
	s_cmp_eq_u32 s24, 0
	s_cselect_b32 s22, s22, s26
	s_cselect_b32 s23, s23, s27
	v_lshl_add_u64 v[132:133], v[132:133], 0, s[22:23]
	s_mov_b32 s50, 0x8000
	s_mov_b32 s51, 0
	s_cmp_eq_u32 s24, 0
	s_cbranch_scc1 .Lrs_ofwd
	s_mov_b32 s50, 0xffff8000
	s_mov_b32 s51, -1
.Lrs_ofwd:
	v_and_b32_e32 v134, 0xff, v164
	v_bfe_u32 v135, v164, 1, 3
	v_lshlrev_b32_e32 v134, 7, v134
	v_add_u32_e32 v134, 49152, v134
	v_lshl_or_b32 v134, v135, 4, v134
	global_load_dwordx2 v[0:1], v[84:85], off offset:0
	global_load_dwordx2 v[2:3], v[84:85], off offset:1024
	global_load_dwordx2 v[4:5], v[84:85], off offset:2048
	global_load_dwordx2 v[6:7], v[86:87], off offset:0
	global_load_dwordx2 v[8:9], v[86:87], off offset:1024
	global_load_dwordx2 v[10:11], v[86:87], off offset:2048
	global_load_dwordx2 v[12:13], v[88:89], off offset:0
	global_load_dwordx2 v[14:15], v[88:89], off offset:1024
	global_load_dwordx2 v[16:17], v[88:89], off offset:2048
	global_load_dwordx2 v[18:19], v[90:91], off
	global_load_dwordx2 v[20:21], v[92:93], off
	v_lshl_add_u64 v[84:85], v[84:85], 0, s[52:53]
	v_lshl_add_u64 v[86:87], v[86:87], 0, s[52:53]
	v_lshl_add_u64 v[88:89], v[88:89], 0, s[52:53]
	v_lshl_add_u64 v[90:91], v[90:91], 0, s[54:55]
	v_lshl_add_u64 v[92:93], v[92:93], 0, s[54:55]
	global_load_dwordx2 v[22:23], v[84:85], off offset:0
	global_load_dwordx2 v[24:25], v[84:85], off offset:1024
	global_load_dwordx2 v[26:27], v[84:85], off offset:2048
	global_load_dwordx2 v[28:29], v[86:87], off offset:0
	global_load_dwordx2 v[30:31], v[86:87], off offset:1024
	global_load_dwordx2 v[32:33], v[86:87], off offset:2048
	global_load_dwordx2 v[34:35], v[88:89], off offset:0
	global_load_dwordx2 v[36:37], v[88:89], off offset:1024
	global_load_dwordx2 v[38:39], v[88:89], off offset:2048
	global_load_dwordx2 v[40:41], v[90:91], off
	global_load_dwordx2 v[42:43], v[92:93], off
	v_lshl_add_u64 v[84:85], v[84:85], 0, s[52:53]
	v_lshl_add_u64 v[86:87], v[86:87], 0, s[52:53]
	v_lshl_add_u64 v[88:89], v[88:89], 0, s[52:53]
	v_lshl_add_u64 v[90:91], v[90:91], 0, s[54:55]
	v_lshl_add_u64 v[92:93], v[92:93], 0, s[54:55]
	s_waitcnt vmcnt(11)
	s_movk_i32 s60, 0xfff
	v_cmp_ne_u32_e64 s[12:13], 0, v95
	v_cmp_ne_u32_e64 s[18:19], s60, v95
	v_add_u32_e32 v95, s56, v95
	v_cndmask_b32_e64 v6, 0, v6, s[12:13]
	v_cndmask_b32_e64 v7, 0, v7, s[12:13]
	v_cndmask_b32_e64 v8, 0, v8, s[12:13]
	v_cndmask_b32_e64 v9, 0, v9, s[12:13]
	v_cndmask_b32_e64 v10, 0, v10, s[12:13]
	v_cndmask_b32_e64 v11, 0, v11, s[12:13]
	v_cndmask_b32_e64 v12, 0, v12, s[18:19]
	v_cndmask_b32_e64 v13, 0, v13, s[18:19]
	v_cndmask_b32_e64 v14, 0, v14, s[18:19]
	v_cndmask_b32_e64 v15, 0, v15, s[18:19]
	v_cndmask_b32_e64 v16, 0, v16, s[18:19]
	v_cndmask_b32_e64 v17, 0, v17, s[18:19]
	v_lshlrev_b32_e32 v96, 16, v0
	v_and_b32_e32 v97, 0xffff0000, v0
	v_lshlrev_b32_e32 v108, 16, v6
	v_and_b32_e32 v109, 0xffff0000, v6
	v_lshlrev_b32_e32 v112, 16, v12
	v_and_b32_e32 v113, 0xffff0000, v12
	v_lshlrev_b32_e32 v98, 16, v1
	v_and_b32_e32 v99, 0xffff0000, v1
	v_lshlrev_b32_e32 v110, 16, v7
	v_and_b32_e32 v111, 0xffff0000, v7
	v_lshlrev_b32_e32 v114, 16, v13
	v_and_b32_e32 v115, 0xffff0000, v13
	v_sub_f32_e32 v108, v108, v96
	v_sub_f32_e32 v112, v112, v96
	v_sub_f32_e32 v109, v109, v97
	v_sub_f32_e32 v113, v113, v97
	v_sub_f32_e32 v110, v110, v98
	v_sub_f32_e32 v114, v114, v98
	v_sub_f32_e32 v111, v111, v99
	v_sub_f32_e32 v115, v115, v99
	v_fmac_f32_e32 v96, v44, v108
	v_fmac_f32_e32 v97, v45, v109
	v_fmac_f32_e32 v98, v46, v110
	v_fmac_f32_e32 v99, v47, v111
	v_fmac_f32_e32 v96, v56, v112
	v_fmac_f32_e32 v97, v57, v113
	v_fmac_f32_e32 v98, v58, v114
	v_fmac_f32_e32 v99, v59, v115
	v_lshlrev_b32_e32 v100, 16, v2
	v_and_b32_e32 v101, 0xffff0000, v2
	v_lshlrev_b32_e32 v108, 16, v8
	v_and_b32_e32 v109, 0xffff0000, v8
	v_lshlrev_b32_e32 v112, 16, v14
	v_and_b32_e32 v113, 0xffff0000, v14
	v_lshlrev_b32_e32 v102, 16, v3
	v_and_b32_e32 v103, 0xffff0000, v3
	v_lshlrev_b32_e32 v110, 16, v9
	v_and_b32_e32 v111, 0xffff0000, v9
	v_lshlrev_b32_e32 v114, 16, v15
	v_and_b32_e32 v115, 0xffff0000, v15
	v_sub_f32_e32 v108, v108, v100
	v_sub_f32_e32 v112, v112, v100
	v_sub_f32_e32 v109, v109, v101
	v_sub_f32_e32 v113, v113, v101
	v_sub_f32_e32 v110, v110, v102
	v_sub_f32_e32 v114, v114, v102
	v_sub_f32_e32 v111, v111, v103
	v_sub_f32_e32 v115, v115, v103
	v_fmac_f32_e32 v100, v48, v108
	v_fmac_f32_e32 v101, v49, v109
	v_fmac_f32_e32 v102, v50, v110
	v_fmac_f32_e32 v103, v51, v111
	v_fmac_f32_e32 v100, v60, v112
	v_fmac_f32_e32 v101, v61, v113
	v_fmac_f32_e32 v102, v62, v114
	v_fmac_f32_e32 v103, v63, v115
	v_lshlrev_b32_e32 v104, 16, v4
	v_and_b32_e32 v105, 0xffff0000, v4
	v_lshlrev_b32_e32 v108, 16, v10
	v_and_b32_e32 v109, 0xffff0000, v10
	v_lshlrev_b32_e32 v112, 16, v16
	v_and_b32_e32 v113, 0xffff0000, v16
	v_lshlrev_b32_e32 v106, 16, v5
	v_and_b32_e32 v107, 0xffff0000, v5
	v_lshlrev_b32_e32 v110, 16, v11
	v_and_b32_e32 v111, 0xffff0000, v11
	v_lshlrev_b32_e32 v114, 16, v17
	v_and_b32_e32 v115, 0xffff0000, v17
	v_sub_f32_e32 v108, v108, v104
	v_sub_f32_e32 v112, v112, v104
	v_sub_f32_e32 v109, v109, v105
	v_sub_f32_e32 v113, v113, v105
	v_sub_f32_e32 v110, v110, v106
	v_sub_f32_e32 v114, v114, v106
	v_sub_f32_e32 v111, v111, v107
	v_sub_f32_e32 v115, v115, v107
	v_fmac_f32_e32 v104, v52, v108
	v_fmac_f32_e32 v105, v53, v109
	v_fmac_f32_e32 v106, v54, v110
	v_fmac_f32_e32 v107, v55, v111
	v_fmac_f32_e32 v104, v64, v112
	v_fmac_f32_e32 v105, v65, v113
	v_fmac_f32_e32 v106, v66, v114
	v_fmac_f32_e32 v107, v67, v115
	v_lshlrev_b32_e32 v108, 16, v18
	v_and_b32_e32 v109, 0xffff0000, v18
	v_lshlrev_b32_e32 v112, 16, v20
	v_and_b32_e32 v113, 0xffff0000, v20
	v_lshlrev_b32_e32 v110, 16, v19
	v_and_b32_e32 v111, 0xffff0000, v19
	v_lshlrev_b32_e32 v114, 16, v21
	v_and_b32_e32 v115, 0xffff0000, v21
	v_add_f32_e32 v116, v68, v112
	v_add_f32_e32 v120, v72, v108
	v_add_f32_e32 v117, v69, v113
	v_add_f32_e32 v121, v73, v109
	v_add_f32_e32 v118, v70, v114
	v_add_f32_e32 v122, v74, v110
	v_add_f32_e32 v119, v71, v115
	v_add_f32_e32 v123, v75, v111
	v_mul_f32_e32 v116, 0xbfb8aa3b, v116
	v_mul_f32_e32 v117, 0xbfb8aa3b, v117
	v_mul_f32_e32 v118, 0xbfb8aa3b, v118
	v_mul_f32_e32 v119, 0xbfb8aa3b, v119
	v_mul_f32_e32 v120, 0xbfb8aa3b, v120
	v_mul_f32_e32 v121, 0xbfb8aa3b, v121
	v_mul_f32_e32 v122, 0xbfb8aa3b, v122
	v_mul_f32_e32 v123, 0xbfb8aa3b, v123
	v_exp_f32_e32 v116, v116
	v_exp_f32_e32 v117, v117
	v_exp_f32_e32 v118, v118
	v_exp_f32_e32 v119, v119
	v_exp_f32_e32 v120, v120
	v_exp_f32_e32 v121, v121
	v_exp_f32_e32 v122, v122
	v_exp_f32_e32 v123, v123
	v_add_f32_e32 v116, 1.0, v116
	v_add_f32_e32 v117, 1.0, v117
	v_add_f32_e32 v118, 1.0, v118
	v_add_f32_e32 v119, 1.0, v119
	v_add_f32_e32 v120, 1.0, v120
	v_add_f32_e32 v121, 1.0, v121
	v_add_f32_e32 v122, 1.0, v122
	v_add_f32_e32 v123, 1.0, v123
	v_rcp_f32_e32 v116, v116
	v_rcp_f32_e32 v117, v117
	v_rcp_f32_e32 v118, v118
	v_rcp_f32_e32 v119, v119
	v_rcp_f32_e32 v120, v120
	v_rcp_f32_e32 v121, v121
	v_rcp_f32_e32 v122, v122
	v_rcp_f32_e32 v123, v123
	v_mul_f32_e32 v120, 0xbf60028b, v120
	v_mul_f32_e32 v121, 0xbf60028b, v121
	v_mul_f32_e32 v122, 0xbf60028b, v122
	v_mul_f32_e32 v123, 0xbf60028b, v123
	v_exp_f32_e32 v120, v120
	v_exp_f32_e32 v121, v121
	v_exp_f32_e32 v122, v122
	v_exp_f32_e32 v123, v123
	v_mul_f32_e32 v124, v100, v76
	v_mul_f32_e32 v125, v101, v77
	v_mul_f32_e32 v126, v102, v78
	v_mul_f32_e32 v127, v103, v79
	v_mul_f32_e32 v108, v124, v124
	v_fmac_f32_e32 v108, v125, v125
	v_fmac_f32_e32 v108, v126, v126
	v_fmac_f32_e32 v108, v127, v127
	v_add_f32_e32 v112, -1.0, v116
	v_add_f32_e32 v113, -1.0, v117
	v_add_f32_e32 v114, -1.0, v118
	v_add_f32_e32 v115, -1.0, v119
	v_add_f32_dpp v108, v108, v108 row_ror:8 row_mask:0xf bank_mask:0xf
	v_fma_f32 v112, v112, v80, 1.0
	v_mul_f32_e32 v112, v100, v112
	v_add_f32_dpp v108, v108, v108 row_ror:4 row_mask:0xf bank_mask:0xf
	v_fma_f32 v113, v113, v81, 1.0
	v_mul_f32_e32 v113, v101, v113
	v_add_f32_dpp v108, v108, v108 row_ror:2 row_mask:0xf bank_mask:0xf
	v_fma_f32 v114, v114, v82, 1.0
	v_mul_f32_e32 v114, v102, v114
	v_add_f32_dpp v108, v108, v108 row_ror:1 row_mask:0xf bank_mask:0xf
	v_fma_f32 v115, v115, v83, 1.0
	v_mul_f32_e32 v115, v103, v115
	v_add_f32_e32 v108, 0x358637bd, v108
	v_rsq_f32_e32 v108, v108
	ds_write_b128 v94, v[96:99] offset:0
	ds_write_b128 v94, v[120:123] offset:256
	ds_write_b128 v94, v[112:115] offset:512
	v_mul_f32_e32 v124, v124, v108
	v_mul_f32_e32 v125, v125, v108
	v_mul_f32_e32 v126, v126, v108
	v_mul_f32_e32 v127, v127, v108
	ds_write_b128 v94, v[104:107] offset:1280
	ds_write_b128 v94, v[124:127] offset:768
	v_mul_f32_e32 v116, v124, v116
	v_mul_f32_e32 v117, v125, v117
	v_mul_f32_e32 v118, v126, v118
	v_mul_f32_e32 v119, v127, v119
	ds_write_b128 v94, v[116:119] offset:1024
	global_load_dwordx2 v[0:1], v[84:85], off offset:0
	global_load_dwordx2 v[2:3], v[84:85], off offset:1024
	global_load_dwordx2 v[4:5], v[84:85], off offset:2048
	global_load_dwordx2 v[6:7], v[86:87], off offset:0
	global_load_dwordx2 v[8:9], v[86:87], off offset:1024
	global_load_dwordx2 v[10:11], v[86:87], off offset:2048
	global_load_dwordx2 v[12:13], v[88:89], off offset:0
	global_load_dwordx2 v[14:15], v[88:89], off offset:1024
	global_load_dwordx2 v[16:17], v[88:89], off offset:2048
	global_load_dwordx2 v[18:19], v[90:91], off
	global_load_dwordx2 v[20:21], v[92:93], off
	v_lshl_add_u64 v[84:85], v[84:85], 0, s[52:53]
	v_lshl_add_u64 v[86:87], v[86:87], 0, s[52:53]
	v_lshl_add_u64 v[88:89], v[88:89], 0, s[52:53]
	v_lshl_add_u64 v[90:91], v[90:91], 0, s[54:55]
	v_lshl_add_u64 v[92:93], v[92:93], 0, s[54:55]
	s_waitcnt lgkmcnt(0)
	s_barrier
	s_mov_b32 s44, 0
.Lrs_loop:
	ds_read_b128 v[96:99], v134 offset:32768
	v_xor_b32_e32 v135, 16, v134
	ds_read_b128 v[100:103], v135 offset:32768
	v_xor_b32_e32 v135, 32, v134
	ds_read_b128 v[104:107], v135 offset:32768
	v_xor_b32_e32 v135, 48, v134
	ds_read_b128 v[108:111], v135 offset:32768
	v_xor_b32_e32 v135, 64, v134
	ds_read_b128 v[112:115], v135 offset:32768
	v_xor_b32_e32 v135, 80, v134
	ds_read_b128 v[116:119], v135 offset:32768
	v_xor_b32_e32 v135, 96, v134
	ds_read_b128 v[120:123], v135 offset:32768
	v_xor_b32_e32 v135, 112, v134
	ds_read_b128 v[124:127], v135 offset:32768
	s_waitcnt lgkmcnt(0)
	v_pk_add_f32 v[96:97], v[96:97], v[98:99]
	v_pk_add_f32 v[100:101], v[100:101], v[102:103]
	v_pk_add_f32 v[104:105], v[104:105], v[106:107]
	v_pk_add_f32 v[108:109], v[108:109], v[110:111]
	v_pk_add_f32 v[112:113], v[112:113], v[114:115]
	v_pk_add_f32 v[116:117], v[116:117], v[118:119]
	v_pk_add_f32 v[120:121], v[120:121], v[122:123]
	v_pk_add_f32 v[124:125], v[124:125], v[126:127]
	v_pk_add_f32 v[96:97], v[96:97], v[100:101]
	v_pk_add_f32 v[104:105], v[104:105], v[108:109]
	v_pk_add_f32 v[112:113], v[112:113], v[116:117]
	v_pk_add_f32 v[120:121], v[120:121], v[124:125]
	v_pk_add_f32 v[96:97], v[96:97], v[104:105]
	v_pk_add_f32 v[112:113], v[112:113], v[120:121]
	s_nop 0
	v_pk_add_f32 v[96:97], v[96:97], v[112:113]
	s_nop 0
	v_cvt_pk_bf16_f32 v98, v96, v97
	s_cmp_eq_u32 s44, 0
	s_cselect_b64 s[22:23], 0, -1
	s_cselect_b64 s[24:25], 0, s[50:51]
	s_mov_b64 exec, s[22:23]
	global_store_dword v[132:133], v98, off
	s_mov_b64 exec, -1
	v_lshl_add_u64 v[132:133], v[132:133], 0, s[24:25]
	s_waitcnt vmcnt(12)
	s_movk_i32 s60, 0xfff
	v_cmp_ne_u32_e64 s[12:13], 0, v95
	v_cmp_ne_u32_e64 s[18:19], s60, v95
	v_add_u32_e32 v95, s56, v95
	v_cndmask_b32_e64 v28, 0, v28, s[12:13]
	v_cndmask_b32_e64 v29, 0, v29, s[12:13]
	v_cndmask_b32_e64 v30, 0, v30, s[12:13]
	v_cndmask_b32_e64 v31, 0, v31, s[12:13]
	v_cndmask_b32_e64 v32, 0, v32, s[12:13]
	v_cndmask_b32_e64 v33, 0, v33, s[12:13]
	v_cndmask_b32_e64 v34, 0, v34, s[18:19]
	v_cndmask_b32_e64 v35, 0, v35, s[18:19]
	v_cndmask_b32_e64 v36, 0, v36, s[18:19]
	v_cndmask_b32_e64 v37, 0, v37, s[18:19]
	v_cndmask_b32_e64 v38, 0, v38, s[18:19]
	v_cndmask_b32_e64 v39, 0, v39, s[18:19]
	v_lshlrev_b32_e32 v96, 16, v22
	v_and_b32_e32 v97, 0xffff0000, v22
	v_lshlrev_b32_e32 v108, 16, v28
	v_and_b32_e32 v109, 0xffff0000, v28
	v_lshlrev_b32_e32 v112, 16, v34
	v_and_b32_e32 v113, 0xffff0000, v34
	v_lshlrev_b32_e32 v98, 16, v23
	v_and_b32_e32 v99, 0xffff0000, v23
	v_lshlrev_b32_e32 v110, 16, v29
	v_and_b32_e32 v111, 0xffff0000, v29
	v_lshlrev_b32_e32 v114, 16, v35
	v_and_b32_e32 v115, 0xffff0000, v35
	v_sub_f32_e32 v108, v108, v96
	v_sub_f32_e32 v112, v112, v96
	v_sub_f32_e32 v109, v109, v97
	v_sub_f32_e32 v113, v113, v97
	v_sub_f32_e32 v110, v110, v98
	v_sub_f32_e32 v114, v114, v98
	v_sub_f32_e32 v111, v111, v99
	v_sub_f32_e32 v115, v115, v99
	v_fmac_f32_e32 v96, v44, v108
	v_fmac_f32_e32 v97, v45, v109
	v_fmac_f32_e32 v98, v46, v110
	v_fmac_f32_e32 v99, v47, v111
	v_fmac_f32_e32 v96, v56, v112
	v_fmac_f32_e32 v97, v57, v113
	v_fmac_f32_e32 v98, v58, v114
	v_fmac_f32_e32 v99, v59, v115
	v_lshlrev_b32_e32 v100, 16, v24
	v_and_b32_e32 v101, 0xffff0000, v24
	v_lshlrev_b32_e32 v108, 16, v30
	v_and_b32_e32 v109, 0xffff0000, v30
	v_lshlrev_b32_e32 v112, 16, v36
	v_and_b32_e32 v113, 0xffff0000, v36
	v_lshlrev_b32_e32 v102, 16, v25
	v_and_b32_e32 v103, 0xffff0000, v25
	v_lshlrev_b32_e32 v110, 16, v31
	v_and_b32_e32 v111, 0xffff0000, v31
	v_lshlrev_b32_e32 v114, 16, v37
	v_and_b32_e32 v115, 0xffff0000, v37
	v_sub_f32_e32 v108, v108, v100
	v_sub_f32_e32 v112, v112, v100
	v_sub_f32_e32 v109, v109, v101
	v_sub_f32_e32 v113, v113, v101
	v_sub_f32_e32 v110, v110, v102
	v_sub_f32_e32 v114, v114, v102
	v_sub_f32_e32 v111, v111, v103
	v_sub_f32_e32 v115, v115, v103
	v_fmac_f32_e32 v100, v48, v108
	v_fmac_f32_e32 v101, v49, v109
	v_fmac_f32_e32 v102, v50, v110
	v_fmac_f32_e32 v103, v51, v111
	v_fmac_f32_e32 v100, v60, v112
	v_fmac_f32_e32 v101, v61, v113
	v_fmac_f32_e32 v102, v62, v114
	v_fmac_f32_e32 v103, v63, v115
	v_lshlrev_b32_e32 v104, 16, v26
	v_and_b32_e32 v105, 0xffff0000, v26
	v_lshlrev_b32_e32 v108, 16, v32
	v_and_b32_e32 v109, 0xffff0000, v32
	v_lshlrev_b32_e32 v112, 16, v38
	v_and_b32_e32 v113, 0xffff0000, v38
	v_lshlrev_b32_e32 v106, 16, v27
	v_and_b32_e32 v107, 0xffff0000, v27
	v_lshlrev_b32_e32 v110, 16, v33
	v_and_b32_e32 v111, 0xffff0000, v33
	v_lshlrev_b32_e32 v114, 16, v39
	v_and_b32_e32 v115, 0xffff0000, v39
	v_sub_f32_e32 v108, v108, v104
	v_sub_f32_e32 v112, v112, v104
	v_sub_f32_e32 v109, v109, v105
	v_sub_f32_e32 v113, v113, v105
	v_sub_f32_e32 v110, v110, v106
	v_sub_f32_e32 v114, v114, v106
	v_sub_f32_e32 v111, v111, v107
	v_sub_f32_e32 v115, v115, v107
	v_fmac_f32_e32 v104, v52, v108
	v_fmac_f32_e32 v105, v53, v109
	v_fmac_f32_e32 v106, v54, v110
	v_fmac_f32_e32 v107, v55, v111
	v_fmac_f32_e32 v104, v64, v112
	v_fmac_f32_e32 v105, v65, v113
	v_fmac_f32_e32 v106, v66, v114
	v_fmac_f32_e32 v107, v67, v115
	v_lshlrev_b32_e32 v108, 16, v40
	v_and_b32_e32 v109, 0xffff0000, v40
	v_lshlrev_b32_e32 v112, 16, v42
	v_and_b32_e32 v113, 0xffff0000, v42
	v_lshlrev_b32_e32 v110, 16, v41
	v_and_b32_e32 v111, 0xffff0000, v41
	v_lshlrev_b32_e32 v114, 16, v43
	v_and_b32_e32 v115, 0xffff0000, v43
	v_add_f32_e32 v116, v68, v112
	v_add_f32_e32 v120, v72, v108
	v_add_f32_e32 v117, v69, v113
	v_add_f32_e32 v121, v73, v109
	v_add_f32_e32 v118, v70, v114
	v_add_f32_e32 v122, v74, v110
	v_add_f32_e32 v119, v71, v115
	v_add_f32_e32 v123, v75, v111
	v_mul_f32_e32 v116, 0xbfb8aa3b, v116
	v_mul_f32_e32 v117, 0xbfb8aa3b, v117
	v_mul_f32_e32 v118, 0xbfb8aa3b, v118
	v_mul_f32_e32 v119, 0xbfb8aa3b, v119
	v_mul_f32_e32 v120, 0xbfb8aa3b, v120
	v_mul_f32_e32 v121, 0xbfb8aa3b, v121
	v_mul_f32_e32 v122, 0xbfb8aa3b, v122
	v_mul_f32_e32 v123, 0xbfb8aa3b, v123
	v_exp_f32_e32 v116, v116
	v_exp_f32_e32 v117, v117
	v_exp_f32_e32 v118, v118
	v_exp_f32_e32 v119, v119
	v_exp_f32_e32 v120, v120
	v_exp_f32_e32 v121, v121
	v_exp_f32_e32 v122, v122
	v_exp_f32_e32 v123, v123
	v_add_f32_e32 v116, 1.0, v116
	v_add_f32_e32 v117, 1.0, v117
	v_add_f32_e32 v118, 1.0, v118
	v_add_f32_e32 v119, 1.0, v119
	v_add_f32_e32 v120, 1.0, v120
	v_add_f32_e32 v121, 1.0, v121
	v_add_f32_e32 v122, 1.0, v122
	v_add_f32_e32 v123, 1.0, v123
	v_rcp_f32_e32 v116, v116
	v_rcp_f32_e32 v117, v117
	v_rcp_f32_e32 v118, v118
	v_rcp_f32_e32 v119, v119
	v_rcp_f32_e32 v120, v120
	v_rcp_f32_e32 v121, v121
	v_rcp_f32_e32 v122, v122
	v_rcp_f32_e32 v123, v123
	v_mul_f32_e32 v120, 0xbf60028b, v120
	v_mul_f32_e32 v121, 0xbf60028b, v121
	v_mul_f32_e32 v122, 0xbf60028b, v122
	v_mul_f32_e32 v123, 0xbf60028b, v123
	v_exp_f32_e32 v120, v120
	v_exp_f32_e32 v121, v121
	v_exp_f32_e32 v122, v122
	v_exp_f32_e32 v123, v123
	v_mul_f32_e32 v124, v100, v76
	v_mul_f32_e32 v125, v101, v77
	v_mul_f32_e32 v126, v102, v78
	v_mul_f32_e32 v127, v103, v79
	v_mul_f32_e32 v108, v124, v124
	v_fmac_f32_e32 v108, v125, v125
	v_fmac_f32_e32 v108, v126, v126
	v_fmac_f32_e32 v108, v127, v127
	v_add_f32_e32 v112, -1.0, v116
	v_add_f32_e32 v113, -1.0, v117
	v_add_f32_e32 v114, -1.0, v118
	v_add_f32_e32 v115, -1.0, v119
	v_add_f32_dpp v108, v108, v108 row_ror:8 row_mask:0xf bank_mask:0xf
	v_fma_f32 v112, v112, v80, 1.0
	v_mul_f32_e32 v112, v100, v112
	v_add_f32_dpp v108, v108, v108 row_ror:4 row_mask:0xf bank_mask:0xf
	v_fma_f32 v113, v113, v81, 1.0
	v_mul_f32_e32 v113, v101, v113
	v_add_f32_dpp v108, v108, v108 row_ror:2 row_mask:0xf bank_mask:0xf
	v_fma_f32 v114, v114, v82, 1.0
	v_mul_f32_e32 v114, v102, v114
	v_add_f32_dpp v108, v108, v108 row_ror:1 row_mask:0xf bank_mask:0xf
	v_fma_f32 v115, v115, v83, 1.0
	v_mul_f32_e32 v115, v103, v115
	v_add_f32_e32 v108, 0x358637bd, v108
	v_rsq_f32_e32 v108, v108
	ds_write_b128 v94, v[96:99] offset:24576
	ds_write_b128 v94, v[120:123] offset:24832
	ds_write_b128 v94, v[112:115] offset:25088
	v_mul_f32_e32 v124, v124, v108
	v_mul_f32_e32 v125, v125, v108
	v_mul_f32_e32 v126, v126, v108
	v_mul_f32_e32 v127, v127, v108
	ds_write_b128 v94, v[104:107] offset:25856
	ds_write_b128 v94, v[124:127] offset:25344
	v_mul_f32_e32 v116, v124, v116
	v_mul_f32_e32 v117, v125, v117
	v_mul_f32_e32 v118, v126, v118
	v_mul_f32_e32 v119, v127, v119
	ds_write_b128 v94, v[116:119] offset:25600
	global_load_dwordx2 v[22:23], v[84:85], off offset:0
	global_load_dwordx2 v[24:25], v[84:85], off offset:1024
	global_load_dwordx2 v[26:27], v[84:85], off offset:2048
	global_load_dwordx2 v[28:29], v[86:87], off offset:0
	global_load_dwordx2 v[30:31], v[86:87], off offset:1024
	global_load_dwordx2 v[32:33], v[86:87], off offset:2048
	global_load_dwordx2 v[34:35], v[88:89], off offset:0
	global_load_dwordx2 v[36:37], v[88:89], off offset:1024
	global_load_dwordx2 v[38:39], v[88:89], off offset:2048
	global_load_dwordx2 v[40:41], v[90:91], off
	global_load_dwordx2 v[42:43], v[92:93], off
	v_lshl_add_u64 v[84:85], v[84:85], 0, s[52:53]
	v_lshl_add_u64 v[86:87], v[86:87], 0, s[52:53]
	v_lshl_add_u64 v[88:89], v[88:89], 0, s[52:53]
	v_lshl_add_u64 v[90:91], v[90:91], 0, s[54:55]
	v_lshl_add_u64 v[92:93], v[92:93], 0, s[54:55]
	s_waitcnt lgkmcnt(0)
	s_barrier
	ds_read_b128 v[96:99], v134 offset:0
	v_xor_b32_e32 v135, 16, v134
	ds_read_b128 v[100:103], v135 offset:0
	v_xor_b32_e32 v135, 32, v134
	ds_read_b128 v[104:107], v135 offset:0
	v_xor_b32_e32 v135, 48, v134
	ds_read_b128 v[108:111], v135 offset:0
	v_xor_b32_e32 v135, 64, v134
	ds_read_b128 v[112:115], v135 offset:0
	v_xor_b32_e32 v135, 80, v134
	ds_read_b128 v[116:119], v135 offset:0
	v_xor_b32_e32 v135, 96, v134
	ds_read_b128 v[120:123], v135 offset:0
	v_xor_b32_e32 v135, 112, v134
	ds_read_b128 v[124:127], v135 offset:0
	s_waitcnt lgkmcnt(0)
	v_pk_add_f32 v[96:97], v[96:97], v[98:99]
	v_pk_add_f32 v[100:101], v[100:101], v[102:103]
	v_pk_add_f32 v[104:105], v[104:105], v[106:107]
	v_pk_add_f32 v[108:109], v[108:109], v[110:111]
	v_pk_add_f32 v[112:113], v[112:113], v[114:115]
	v_pk_add_f32 v[116:117], v[116:117], v[118:119]
	v_pk_add_f32 v[120:121], v[120:121], v[122:123]
	v_pk_add_f32 v[124:125], v[124:125], v[126:127]
	v_pk_add_f32 v[96:97], v[96:97], v[100:101]
	v_pk_add_f32 v[104:105], v[104:105], v[108:109]
	v_pk_add_f32 v[112:113], v[112:113], v[116:117]
	v_pk_add_f32 v[120:121], v[120:121], v[124:125]
	v_pk_add_f32 v[96:97], v[96:97], v[104:105]
	v_pk_add_f32 v[112:113], v[112:113], v[120:121]
	s_nop 0
	v_pk_add_f32 v[96:97], v[96:97], v[112:113]
	s_nop 0
	v_cvt_pk_bf16_f32 v98, v96, v97
	global_store_dword v[132:133], v98, off
	v_lshl_add_u64 v[132:133], v[132:133], 0, s[50:51]
	s_waitcnt vmcnt(12)
	s_movk_i32 s60, 0xfff
	v_cmp_ne_u32_e64 s[12:13], 0, v95
	v_cmp_ne_u32_e64 s[18:19], s60, v95
	v_add_u32_e32 v95, s56, v95
	v_cndmask_b32_e64 v6, 0, v6, s[12:13]
	v_cndmask_b32_e64 v7, 0, v7, s[12:13]
	v_cndmask_b32_e64 v8, 0, v8, s[12:13]
	v_cndmask_b32_e64 v9, 0, v9, s[12:13]
	v_cndmask_b32_e64 v10, 0, v10, s[12:13]
	v_cndmask_b32_e64 v11, 0, v11, s[12:13]
	v_cndmask_b32_e64 v12, 0, v12, s[18:19]
	v_cndmask_b32_e64 v13, 0, v13, s[18:19]
	v_cndmask_b32_e64 v14, 0, v14, s[18:19]
	v_cndmask_b32_e64 v15, 0, v15, s[18:19]
	v_cndmask_b32_e64 v16, 0, v16, s[18:19]
	v_cndmask_b32_e64 v17, 0, v17, s[18:19]
	v_lshlrev_b32_e32 v96, 16, v0
	v_and_b32_e32 v97, 0xffff0000, v0
	v_lshlrev_b32_e32 v108, 16, v6
	v_and_b32_e32 v109, 0xffff0000, v6
	v_lshlrev_b32_e32 v112, 16, v12
	v_and_b32_e32 v113, 0xffff0000, v12
	v_lshlrev_b32_e32 v98, 16, v1
	v_and_b32_e32 v99, 0xffff0000, v1
	v_lshlrev_b32_e32 v110, 16, v7
	v_and_b32_e32 v111, 0xffff0000, v7
	v_lshlrev_b32_e32 v114, 16, v13
	v_and_b32_e32 v115, 0xffff0000, v13
	v_sub_f32_e32 v108, v108, v96
	v_sub_f32_e32 v112, v112, v96
	v_sub_f32_e32 v109, v109, v97
	v_sub_f32_e32 v113, v113, v97
	v_sub_f32_e32 v110, v110, v98
	v_sub_f32_e32 v114, v114, v98
	v_sub_f32_e32 v111, v111, v99
	v_sub_f32_e32 v115, v115, v99
	v_fmac_f32_e32 v96, v44, v108
	v_fmac_f32_e32 v97, v45, v109
	v_fmac_f32_e32 v98, v46, v110
	v_fmac_f32_e32 v99, v47, v111
	v_fmac_f32_e32 v96, v56, v112
	v_fmac_f32_e32 v97, v57, v113
	v_fmac_f32_e32 v98, v58, v114
	v_fmac_f32_e32 v99, v59, v115
	v_lshlrev_b32_e32 v100, 16, v2
	v_and_b32_e32 v101, 0xffff0000, v2
	v_lshlrev_b32_e32 v108, 16, v8
	v_and_b32_e32 v109, 0xffff0000, v8
	v_lshlrev_b32_e32 v112, 16, v14
	v_and_b32_e32 v113, 0xffff0000, v14
	v_lshlrev_b32_e32 v102, 16, v3
	v_and_b32_e32 v103, 0xffff0000, v3
	v_lshlrev_b32_e32 v110, 16, v9
	v_and_b32_e32 v111, 0xffff0000, v9
	v_lshlrev_b32_e32 v114, 16, v15
	v_and_b32_e32 v115, 0xffff0000, v15
	v_sub_f32_e32 v108, v108, v100
	v_sub_f32_e32 v112, v112, v100
	v_sub_f32_e32 v109, v109, v101
	v_sub_f32_e32 v113, v113, v101
	v_sub_f32_e32 v110, v110, v102
	v_sub_f32_e32 v114, v114, v102
	v_sub_f32_e32 v111, v111, v103
	v_sub_f32_e32 v115, v115, v103
	v_fmac_f32_e32 v100, v48, v108
	v_fmac_f32_e32 v101, v49, v109
	v_fmac_f32_e32 v102, v50, v110
	v_fmac_f32_e32 v103, v51, v111
	v_fmac_f32_e32 v100, v60, v112
	v_fmac_f32_e32 v101, v61, v113
	v_fmac_f32_e32 v102, v62, v114
	v_fmac_f32_e32 v103, v63, v115
	v_lshlrev_b32_e32 v104, 16, v4
	v_and_b32_e32 v105, 0xffff0000, v4
	v_lshlrev_b32_e32 v108, 16, v10
	v_and_b32_e32 v109, 0xffff0000, v10
	v_lshlrev_b32_e32 v112, 16, v16
	v_and_b32_e32 v113, 0xffff0000, v16
	v_lshlrev_b32_e32 v106, 16, v5
	v_and_b32_e32 v107, 0xffff0000, v5
	v_lshlrev_b32_e32 v110, 16, v11
	v_and_b32_e32 v111, 0xffff0000, v11
	v_lshlrev_b32_e32 v114, 16, v17
	v_and_b32_e32 v115, 0xffff0000, v17
	v_sub_f32_e32 v108, v108, v104
	v_sub_f32_e32 v112, v112, v104
	v_sub_f32_e32 v109, v109, v105
	v_sub_f32_e32 v113, v113, v105
	v_sub_f32_e32 v110, v110, v106
	v_sub_f32_e32 v114, v114, v106
	v_sub_f32_e32 v111, v111, v107
	v_sub_f32_e32 v115, v115, v107
	v_fmac_f32_e32 v104, v52, v108
	v_fmac_f32_e32 v105, v53, v109
	v_fmac_f32_e32 v106, v54, v110
	v_fmac_f32_e32 v107, v55, v111
	v_fmac_f32_e32 v104, v64, v112
	v_fmac_f32_e32 v105, v65, v113
	v_fmac_f32_e32 v106, v66, v114
	v_fmac_f32_e32 v107, v67, v115
	v_lshlrev_b32_e32 v108, 16, v18
	v_and_b32_e32 v109, 0xffff0000, v18
	v_lshlrev_b32_e32 v112, 16, v20
	v_and_b32_e32 v113, 0xffff0000, v20
	v_lshlrev_b32_e32 v110, 16, v19
	v_and_b32_e32 v111, 0xffff0000, v19
	v_lshlrev_b32_e32 v114, 16, v21
	v_and_b32_e32 v115, 0xffff0000, v21
	v_add_f32_e32 v116, v68, v112
	v_add_f32_e32 v120, v72, v108
	v_add_f32_e32 v117, v69, v113
	v_add_f32_e32 v121, v73, v109
	v_add_f32_e32 v118, v70, v114
	v_add_f32_e32 v122, v74, v110
	v_add_f32_e32 v119, v71, v115
	v_add_f32_e32 v123, v75, v111
	v_mul_f32_e32 v116, 0xbfb8aa3b, v116
	v_mul_f32_e32 v117, 0xbfb8aa3b, v117
	v_mul_f32_e32 v118, 0xbfb8aa3b, v118
	v_mul_f32_e32 v119, 0xbfb8aa3b, v119
	v_mul_f32_e32 v120, 0xbfb8aa3b, v120
	v_mul_f32_e32 v121, 0xbfb8aa3b, v121
	v_mul_f32_e32 v122, 0xbfb8aa3b, v122
	v_mul_f32_e32 v123, 0xbfb8aa3b, v123
	v_exp_f32_e32 v116, v116
	v_exp_f32_e32 v117, v117
	v_exp_f32_e32 v118, v118
	v_exp_f32_e32 v119, v119
	v_exp_f32_e32 v120, v120
	v_exp_f32_e32 v121, v121
	v_exp_f32_e32 v122, v122
	v_exp_f32_e32 v123, v123
	v_add_f32_e32 v116, 1.0, v116
	v_add_f32_e32 v117, 1.0, v117
	v_add_f32_e32 v118, 1.0, v118
	v_add_f32_e32 v119, 1.0, v119
	v_add_f32_e32 v120, 1.0, v120
	v_add_f32_e32 v121, 1.0, v121
	v_add_f32_e32 v122, 1.0, v122
	v_add_f32_e32 v123, 1.0, v123
	v_rcp_f32_e32 v116, v116
	v_rcp_f32_e32 v117, v117
	v_rcp_f32_e32 v118, v118
	v_rcp_f32_e32 v119, v119
	v_rcp_f32_e32 v120, v120
	v_rcp_f32_e32 v121, v121
	v_rcp_f32_e32 v122, v122
	v_rcp_f32_e32 v123, v123
	v_mul_f32_e32 v120, 0xbf60028b, v120
	v_mul_f32_e32 v121, 0xbf60028b, v121
	v_mul_f32_e32 v122, 0xbf60028b, v122
	v_mul_f32_e32 v123, 0xbf60028b, v123
	v_exp_f32_e32 v120, v120
	v_exp_f32_e32 v121, v121
	v_exp_f32_e32 v122, v122
	v_exp_f32_e32 v123, v123
	v_mul_f32_e32 v124, v100, v76
	v_mul_f32_e32 v125, v101, v77
	v_mul_f32_e32 v126, v102, v78
	v_mul_f32_e32 v127, v103, v79
	v_mul_f32_e32 v108, v124, v124
	v_fmac_f32_e32 v108, v125, v125
	v_fmac_f32_e32 v108, v126, v126
	v_fmac_f32_e32 v108, v127, v127
	v_add_f32_e32 v112, -1.0, v116
	v_add_f32_e32 v113, -1.0, v117
	v_add_f32_e32 v114, -1.0, v118
	v_add_f32_e32 v115, -1.0, v119
	v_add_f32_dpp v108, v108, v108 row_ror:8 row_mask:0xf bank_mask:0xf
	v_fma_f32 v112, v112, v80, 1.0
	v_mul_f32_e32 v112, v100, v112
	v_add_f32_dpp v108, v108, v108 row_ror:4 row_mask:0xf bank_mask:0xf
	v_fma_f32 v113, v113, v81, 1.0
	v_mul_f32_e32 v113, v101, v113
	v_add_f32_dpp v108, v108, v108 row_ror:2 row_mask:0xf bank_mask:0xf
	v_fma_f32 v114, v114, v82, 1.0
	v_mul_f32_e32 v114, v102, v114
	v_add_f32_dpp v108, v108, v108 row_ror:1 row_mask:0xf bank_mask:0xf
	v_fma_f32 v115, v115, v83, 1.0
	v_mul_f32_e32 v115, v103, v115
	v_add_f32_e32 v108, 0x358637bd, v108
	v_rsq_f32_e32 v108, v108
	ds_write_b128 v94, v[96:99] offset:0
	ds_write_b128 v94, v[120:123] offset:256
	ds_write_b128 v94, v[112:115] offset:512
	v_mul_f32_e32 v124, v124, v108
	v_mul_f32_e32 v125, v125, v108
	v_mul_f32_e32 v126, v126, v108
	v_mul_f32_e32 v127, v127, v108
	ds_write_b128 v94, v[104:107] offset:1280
	ds_write_b128 v94, v[124:127] offset:768
	v_mul_f32_e32 v116, v124, v116
	v_mul_f32_e32 v117, v125, v117
	v_mul_f32_e32 v118, v126, v118
	v_mul_f32_e32 v119, v127, v119
	ds_write_b128 v94, v[116:119] offset:1024
	global_load_dwordx2 v[0:1], v[84:85], off offset:0
	global_load_dwordx2 v[2:3], v[84:85], off offset:1024
	global_load_dwordx2 v[4:5], v[84:85], off offset:2048
	global_load_dwordx2 v[6:7], v[86:87], off offset:0
	global_load_dwordx2 v[8:9], v[86:87], off offset:1024
	global_load_dwordx2 v[10:11], v[86:87], off offset:2048
	global_load_dwordx2 v[12:13], v[88:89], off offset:0
	global_load_dwordx2 v[14:15], v[88:89], off offset:1024
	global_load_dwordx2 v[16:17], v[88:89], off offset:2048
	global_load_dwordx2 v[18:19], v[90:91], off
	global_load_dwordx2 v[20:21], v[92:93], off
	v_lshl_add_u64 v[84:85], v[84:85], 0, s[52:53]
	v_lshl_add_u64 v[86:87], v[86:87], 0, s[52:53]
	v_lshl_add_u64 v[88:89], v[88:89], 0, s[52:53]
	v_lshl_add_u64 v[90:91], v[90:91], 0, s[54:55]
	v_lshl_add_u64 v[92:93], v[92:93], 0, s[54:55]
	s_waitcnt lgkmcnt(0)
	s_barrier
	s_add_i32 s44, s44, 1
	s_cmp_lt_u32 s44, 127
	s_cbranch_scc1 .Lrs_loop
	ds_read_b128 v[96:99], v134 offset:32768
	v_xor_b32_e32 v135, 16, v134
	ds_read_b128 v[100:103], v135 offset:32768
	v_xor_b32_e32 v135, 32, v134
	ds_read_b128 v[104:107], v135 offset:32768
	v_xor_b32_e32 v135, 48, v134
	ds_read_b128 v[108:111], v135 offset:32768
	v_xor_b32_e32 v135, 64, v134
	ds_read_b128 v[112:115], v135 offset:32768
	v_xor_b32_e32 v135, 80, v134
	ds_read_b128 v[116:119], v135 offset:32768
	v_xor_b32_e32 v135, 96, v134
	ds_read_b128 v[120:123], v135 offset:32768
	v_xor_b32_e32 v135, 112, v134
	ds_read_b128 v[124:127], v135 offset:32768
	s_waitcnt lgkmcnt(0)
	v_pk_add_f32 v[96:97], v[96:97], v[98:99]
	v_pk_add_f32 v[100:101], v[100:101], v[102:103]
	v_pk_add_f32 v[104:105], v[104:105], v[106:107]
	v_pk_add_f32 v[108:109], v[108:109], v[110:111]
	v_pk_add_f32 v[112:113], v[112:113], v[114:115]
	v_pk_add_f32 v[116:117], v[116:117], v[118:119]
	v_pk_add_f32 v[120:121], v[120:121], v[122:123]
	v_pk_add_f32 v[124:125], v[124:125], v[126:127]
	v_pk_add_f32 v[96:97], v[96:97], v[100:101]
	v_pk_add_f32 v[104:105], v[104:105], v[108:109]
	v_pk_add_f32 v[112:113], v[112:113], v[116:117]
	v_pk_add_f32 v[120:121], v[120:121], v[124:125]
	v_pk_add_f32 v[96:97], v[96:97], v[104:105]
	v_pk_add_f32 v[112:113], v[112:113], v[120:121]
	s_nop 0
	v_pk_add_f32 v[96:97], v[96:97], v[112:113]
	s_nop 0
	v_cvt_pk_bf16_f32 v98, v96, v97
	s_cmp_eq_u32 s44, 0
	s_cselect_b64 s[22:23], 0, -1
	s_cselect_b64 s[24:25], 0, s[50:51]
	s_mov_b64 exec, s[22:23]
	global_store_dword v[132:133], v98, off
	s_mov_b64 exec, -1
	v_lshl_add_u64 v[132:133], v[132:133], 0, s[24:25]
	s_waitcnt vmcnt(12)
	s_movk_i32 s60, 0xfff
	v_cmp_ne_u32_e64 s[12:13], 0, v95
	v_cmp_ne_u32_e64 s[18:19], s60, v95
	v_add_u32_e32 v95, s56, v95
	v_cndmask_b32_e64 v28, 0, v28, s[12:13]
	v_cndmask_b32_e64 v29, 0, v29, s[12:13]
	v_cndmask_b32_e64 v30, 0, v30, s[12:13]
	v_cndmask_b32_e64 v31, 0, v31, s[12:13]
	v_cndmask_b32_e64 v32, 0, v32, s[12:13]
	v_cndmask_b32_e64 v33, 0, v33, s[12:13]
	v_cndmask_b32_e64 v34, 0, v34, s[18:19]
	v_cndmask_b32_e64 v35, 0, v35, s[18:19]
	v_cndmask_b32_e64 v36, 0, v36, s[18:19]
	v_cndmask_b32_e64 v37, 0, v37, s[18:19]
	v_cndmask_b32_e64 v38, 0, v38, s[18:19]
	v_cndmask_b32_e64 v39, 0, v39, s[18:19]
	v_lshlrev_b32_e32 v96, 16, v22
	v_and_b32_e32 v97, 0xffff0000, v22
	v_lshlrev_b32_e32 v108, 16, v28
	v_and_b32_e32 v109, 0xffff0000, v28
	v_lshlrev_b32_e32 v112, 16, v34
	v_and_b32_e32 v113, 0xffff0000, v34
	v_lshlrev_b32_e32 v98, 16, v23
	v_and_b32_e32 v99, 0xffff0000, v23
	v_lshlrev_b32_e32 v110, 16, v29
	v_and_b32_e32 v111, 0xffff0000, v29
	v_lshlrev_b32_e32 v114, 16, v35
	v_and_b32_e32 v115, 0xffff0000, v35
	v_sub_f32_e32 v108, v108, v96
	v_sub_f32_e32 v112, v112, v96
	v_sub_f32_e32 v109, v109, v97
	v_sub_f32_e32 v113, v113, v97
	v_sub_f32_e32 v110, v110, v98
	v_sub_f32_e32 v114, v114, v98
	v_sub_f32_e32 v111, v111, v99
	v_sub_f32_e32 v115, v115, v99
	v_fmac_f32_e32 v96, v44, v108
	v_fmac_f32_e32 v97, v45, v109
	v_fmac_f32_e32 v98, v46, v110
	v_fmac_f32_e32 v99, v47, v111
	v_fmac_f32_e32 v96, v56, v112
	v_fmac_f32_e32 v97, v57, v113
	v_fmac_f32_e32 v98, v58, v114
	v_fmac_f32_e32 v99, v59, v115
	v_lshlrev_b32_e32 v100, 16, v24
	v_and_b32_e32 v101, 0xffff0000, v24
	v_lshlrev_b32_e32 v108, 16, v30
	v_and_b32_e32 v109, 0xffff0000, v30
	v_lshlrev_b32_e32 v112, 16, v36
	v_and_b32_e32 v113, 0xffff0000, v36
	v_lshlrev_b32_e32 v102, 16, v25
	v_and_b32_e32 v103, 0xffff0000, v25
	v_lshlrev_b32_e32 v110, 16, v31
	v_and_b32_e32 v111, 0xffff0000, v31
	v_lshlrev_b32_e32 v114, 16, v37
	v_and_b32_e32 v115, 0xffff0000, v37
	v_sub_f32_e32 v108, v108, v100
	v_sub_f32_e32 v112, v112, v100
	v_sub_f32_e32 v109, v109, v101
	v_sub_f32_e32 v113, v113, v101
	v_sub_f32_e32 v110, v110, v102
	v_sub_f32_e32 v114, v114, v102
	v_sub_f32_e32 v111, v111, v103
	v_sub_f32_e32 v115, v115, v103
	v_fmac_f32_e32 v100, v48, v108
	v_fmac_f32_e32 v101, v49, v109
	v_fmac_f32_e32 v102, v50, v110
	v_fmac_f32_e32 v103, v51, v111
	v_fmac_f32_e32 v100, v60, v112
	v_fmac_f32_e32 v101, v61, v113
	v_fmac_f32_e32 v102, v62, v114
	v_fmac_f32_e32 v103, v63, v115
	v_lshlrev_b32_e32 v104, 16, v26
	v_and_b32_e32 v105, 0xffff0000, v26
	v_lshlrev_b32_e32 v108, 16, v32
	v_and_b32_e32 v109, 0xffff0000, v32
	v_lshlrev_b32_e32 v112, 16, v38
	v_and_b32_e32 v113, 0xffff0000, v38
	v_lshlrev_b32_e32 v106, 16, v27
	v_and_b32_e32 v107, 0xffff0000, v27
	v_lshlrev_b32_e32 v110, 16, v33
	v_and_b32_e32 v111, 0xffff0000, v33
	v_lshlrev_b32_e32 v114, 16, v39
	v_and_b32_e32 v115, 0xffff0000, v39
	v_sub_f32_e32 v108, v108, v104
	v_sub_f32_e32 v112, v112, v104
	v_sub_f32_e32 v109, v109, v105
	v_sub_f32_e32 v113, v113, v105
	v_sub_f32_e32 v110, v110, v106
	v_sub_f32_e32 v114, v114, v106
	v_sub_f32_e32 v111, v111, v107
	v_sub_f32_e32 v115, v115, v107
	v_fmac_f32_e32 v104, v52, v108
	v_fmac_f32_e32 v105, v53, v109
	v_fmac_f32_e32 v106, v54, v110
	v_fmac_f32_e32 v107, v55, v111
	v_fmac_f32_e32 v104, v64, v112
	v_fmac_f32_e32 v105, v65, v113
	v_fmac_f32_e32 v106, v66, v114
	v_fmac_f32_e32 v107, v67, v115
	v_lshlrev_b32_e32 v108, 16, v40
	v_and_b32_e32 v109, 0xffff0000, v40
	v_lshlrev_b32_e32 v112, 16, v42
	v_and_b32_e32 v113, 0xffff0000, v42
	v_lshlrev_b32_e32 v110, 16, v41
	v_and_b32_e32 v111, 0xffff0000, v41
	v_lshlrev_b32_e32 v114, 16, v43
	v_and_b32_e32 v115, 0xffff0000, v43
	v_add_f32_e32 v116, v68, v112
	v_add_f32_e32 v120, v72, v108
	v_add_f32_e32 v117, v69, v113
	v_add_f32_e32 v121, v73, v109
	v_add_f32_e32 v118, v70, v114
	v_add_f32_e32 v122, v74, v110
	v_add_f32_e32 v119, v71, v115
	v_add_f32_e32 v123, v75, v111
	v_mul_f32_e32 v116, 0xbfb8aa3b, v116
	v_mul_f32_e32 v117, 0xbfb8aa3b, v117
	v_mul_f32_e32 v118, 0xbfb8aa3b, v118
	v_mul_f32_e32 v119, 0xbfb8aa3b, v119
	v_mul_f32_e32 v120, 0xbfb8aa3b, v120
	v_mul_f32_e32 v121, 0xbfb8aa3b, v121
	v_mul_f32_e32 v122, 0xbfb8aa3b, v122
	v_mul_f32_e32 v123, 0xbfb8aa3b, v123
	v_exp_f32_e32 v116, v116
	v_exp_f32_e32 v117, v117
	v_exp_f32_e32 v118, v118
	v_exp_f32_e32 v119, v119
	v_exp_f32_e32 v120, v120
	v_exp_f32_e32 v121, v121
	v_exp_f32_e32 v122, v122
	v_exp_f32_e32 v123, v123
	v_add_f32_e32 v116, 1.0, v116
	v_add_f32_e32 v117, 1.0, v117
	v_add_f32_e32 v118, 1.0, v118
	v_add_f32_e32 v119, 1.0, v119
	v_add_f32_e32 v120, 1.0, v120
	v_add_f32_e32 v121, 1.0, v121
	v_add_f32_e32 v122, 1.0, v122
	v_add_f32_e32 v123, 1.0, v123
	v_rcp_f32_e32 v116, v116
	v_rcp_f32_e32 v117, v117
	v_rcp_f32_e32 v118, v118
	v_rcp_f32_e32 v119, v119
	v_rcp_f32_e32 v120, v120
	v_rcp_f32_e32 v121, v121
	v_rcp_f32_e32 v122, v122
	v_rcp_f32_e32 v123, v123
	v_mul_f32_e32 v120, 0xbf60028b, v120
	v_mul_f32_e32 v121, 0xbf60028b, v121
	v_mul_f32_e32 v122, 0xbf60028b, v122
	v_mul_f32_e32 v123, 0xbf60028b, v123
	v_exp_f32_e32 v120, v120
	v_exp_f32_e32 v121, v121
	v_exp_f32_e32 v122, v122
	v_exp_f32_e32 v123, v123
	v_mul_f32_e32 v124, v100, v76
	v_mul_f32_e32 v125, v101, v77
	v_mul_f32_e32 v126, v102, v78
	v_mul_f32_e32 v127, v103, v79
	v_mul_f32_e32 v108, v124, v124
	v_fmac_f32_e32 v108, v125, v125
	v_fmac_f32_e32 v108, v126, v126
	v_fmac_f32_e32 v108, v127, v127
	v_add_f32_e32 v112, -1.0, v116
	v_add_f32_e32 v113, -1.0, v117
	v_add_f32_e32 v114, -1.0, v118
	v_add_f32_e32 v115, -1.0, v119
	v_add_f32_dpp v108, v108, v108 row_ror:8 row_mask:0xf bank_mask:0xf
	v_fma_f32 v112, v112, v80, 1.0
	v_mul_f32_e32 v112, v100, v112
	v_add_f32_dpp v108, v108, v108 row_ror:4 row_mask:0xf bank_mask:0xf
	v_fma_f32 v113, v113, v81, 1.0
	v_mul_f32_e32 v113, v101, v113
	v_add_f32_dpp v108, v108, v108 row_ror:2 row_mask:0xf bank_mask:0xf
	v_fma_f32 v114, v114, v82, 1.0
	v_mul_f32_e32 v114, v102, v114
	v_add_f32_dpp v108, v108, v108 row_ror:1 row_mask:0xf bank_mask:0xf
	v_fma_f32 v115, v115, v83, 1.0
	v_mul_f32_e32 v115, v103, v115
	v_add_f32_e32 v108, 0x358637bd, v108
	v_rsq_f32_e32 v108, v108
	ds_write_b128 v94, v[96:99] offset:24576
	ds_write_b128 v94, v[120:123] offset:24832
	ds_write_b128 v94, v[112:115] offset:25088
	v_mul_f32_e32 v124, v124, v108
	v_mul_f32_e32 v125, v125, v108
	v_mul_f32_e32 v126, v126, v108
	v_mul_f32_e32 v127, v127, v108
	ds_write_b128 v94, v[104:107] offset:25856
	ds_write_b128 v94, v[124:127] offset:25344
	v_mul_f32_e32 v116, v124, v116
	v_mul_f32_e32 v117, v125, v117
	v_mul_f32_e32 v118, v126, v118
	v_mul_f32_e32 v119, v127, v119
	ds_write_b128 v94, v[116:119] offset:25600
	global_load_dwordx2 v[22:23], v[84:85], off offset:0
	global_load_dwordx2 v[24:25], v[84:85], off offset:1024
	global_load_dwordx2 v[26:27], v[84:85], off offset:2048
	global_load_dwordx2 v[28:29], v[86:87], off offset:0
	global_load_dwordx2 v[30:31], v[86:87], off offset:1024
	global_load_dwordx2 v[32:33], v[86:87], off offset:2048
	global_load_dwordx2 v[34:35], v[88:89], off offset:0
	global_load_dwordx2 v[36:37], v[88:89], off offset:1024
	global_load_dwordx2 v[38:39], v[88:89], off offset:2048
	global_load_dwordx2 v[40:41], v[90:91], off
	global_load_dwordx2 v[42:43], v[92:93], off
	v_lshl_add_u64 v[84:85], v[84:85], 0, s[52:53]
	v_lshl_add_u64 v[86:87], v[86:87], 0, s[52:53]
	v_lshl_add_u64 v[88:89], v[88:89], 0, s[52:53]
	v_lshl_add_u64 v[90:91], v[90:91], 0, s[54:55]
	v_lshl_add_u64 v[92:93], v[92:93], 0, s[54:55]
	s_waitcnt lgkmcnt(0)
	s_barrier
	ds_read_b128 v[96:99], v134 offset:0
	v_xor_b32_e32 v135, 16, v134
	ds_read_b128 v[100:103], v135 offset:0
	v_xor_b32_e32 v135, 32, v134
	ds_read_b128 v[104:107], v135 offset:0
	v_xor_b32_e32 v135, 48, v134
	ds_read_b128 v[108:111], v135 offset:0
	v_xor_b32_e32 v135, 64, v134
	ds_read_b128 v[112:115], v135 offset:0
	v_xor_b32_e32 v135, 80, v134
	ds_read_b128 v[116:119], v135 offset:0
	v_xor_b32_e32 v135, 96, v134
	ds_read_b128 v[120:123], v135 offset:0
	v_xor_b32_e32 v135, 112, v134
	ds_read_b128 v[124:127], v135 offset:0
	s_waitcnt lgkmcnt(0)
	v_pk_add_f32 v[96:97], v[96:97], v[98:99]
	v_pk_add_f32 v[100:101], v[100:101], v[102:103]
	v_pk_add_f32 v[104:105], v[104:105], v[106:107]
	v_pk_add_f32 v[108:109], v[108:109], v[110:111]
	v_pk_add_f32 v[112:113], v[112:113], v[114:115]
	v_pk_add_f32 v[116:117], v[116:117], v[118:119]
	v_pk_add_f32 v[120:121], v[120:121], v[122:123]
	v_pk_add_f32 v[124:125], v[124:125], v[126:127]
	v_pk_add_f32 v[96:97], v[96:97], v[100:101]
	v_pk_add_f32 v[104:105], v[104:105], v[108:109]
	v_pk_add_f32 v[112:113], v[112:113], v[116:117]
	v_pk_add_f32 v[120:121], v[120:121], v[124:125]
	v_pk_add_f32 v[96:97], v[96:97], v[104:105]
	v_pk_add_f32 v[112:113], v[112:113], v[120:121]
	s_nop 0
	v_pk_add_f32 v[96:97], v[96:97], v[112:113]
	s_nop 0
	v_cvt_pk_bf16_f32 v98, v96, v97
	global_store_dword v[132:133], v98, off
	v_lshl_add_u64 v[132:133], v[132:133], 0, s[50:51]
	s_waitcnt vmcnt(0)
	s_barrier
	ds_read_b128 v[96:99], v134 offset:32768
	v_xor_b32_e32 v135, 16, v134
	ds_read_b128 v[100:103], v135 offset:32768
	v_xor_b32_e32 v135, 32, v134
	ds_read_b128 v[104:107], v135 offset:32768
	v_xor_b32_e32 v135, 48, v134
	ds_read_b128 v[108:111], v135 offset:32768
	v_xor_b32_e32 v135, 64, v134
	ds_read_b128 v[112:115], v135 offset:32768
	v_xor_b32_e32 v135, 80, v134
	ds_read_b128 v[116:119], v135 offset:32768
	v_xor_b32_e32 v135, 96, v134
	ds_read_b128 v[120:123], v135 offset:32768
	v_xor_b32_e32 v135, 112, v134
	ds_read_b128 v[124:127], v135 offset:32768
	s_waitcnt lgkmcnt(0)
	v_pk_add_f32 v[96:97], v[96:97], v[98:99]
	v_pk_add_f32 v[100:101], v[100:101], v[102:103]
	v_pk_add_f32 v[104:105], v[104:105], v[106:107]
	v_pk_add_f32 v[108:109], v[108:109], v[110:111]
	v_pk_add_f32 v[112:113], v[112:113], v[114:115]
	v_pk_add_f32 v[116:117], v[116:117], v[118:119]
	v_pk_add_f32 v[120:121], v[120:121], v[122:123]
	v_pk_add_f32 v[124:125], v[124:125], v[126:127]
	v_pk_add_f32 v[96:97], v[96:97], v[100:101]
	v_pk_add_f32 v[104:105], v[104:105], v[108:109]
	v_pk_add_f32 v[112:113], v[112:113], v[116:117]
	v_pk_add_f32 v[120:121], v[120:121], v[124:125]
	v_pk_add_f32 v[96:97], v[96:97], v[104:105]
	v_pk_add_f32 v[112:113], v[112:113], v[120:121]
	s_nop 0
	v_pk_add_f32 v[96:97], v[96:97], v[112:113]
	s_nop 0
	v_cvt_pk_bf16_f32 v98, v96, v97
	global_store_dword v[132:133], v98, off
	v_lshl_add_u64 v[132:133], v[132:133], 0, s[50:51]
	s_waitcnt vmcnt(0)
	s_branch .LBB0_1026
